# LayerNorm phase row loads marked nt (once-read streams)
# baseline (speedup 1.0000x reference)
.LBB0_132:
	s_or_b64 exec, exec, s[2:3]
	global_load_dwordx4 v[156:159], v[132:133], off nt
	global_load_dwordx4 v[160:163], v[134:135], off nt
	v_pk_mul_f32 v[168:169], v[106:107], v[120:121] op_sel_hi:[1,0]
	v_lshl_add_u64 v[106:107], s[54:55], 0, v[136:137]
	v_pk_mul_f32 v[164:165], v[18:19], v[56:57] op_sel_hi:[1,0]
	v_add_co_u32_e32 v18, vcc, s59, v106
	v_pk_mul_f32 v[170:171], v[20:21], v[56:57] op_sel_hi:[1,0]
	s_nop 0
	v_addc_co_u32_e32 v19, vcc, 0, v107, vcc
	v_add_co_u32_e32 v20, vcc, s68, v106
	v_pk_mul_f32 v[166:167], v[22:23], v[84:85] op_sel_hi:[1,0]
	s_nop 0
	v_addc_co_u32_e32 v21, vcc, 0, v107, vcc
	v_add_co_u32_e32 v22, vcc, s69, v106
	v_pk_mul_f32 v[110:111], v[110:111], v[124:125] op_sel_hi:[1,0]
	v_pk_mul_f32 v[114:115], v[114:115], v[128:129] op_sel_hi:[1,0]
	v_pk_mul_f32 v[118:119], v[118:119], v[150:151] op_sel_hi:[1,0]
	v_pk_mul_f32 v[122:123], v[122:123], v[152:153] op_sel_hi:[1,0]
	v_pk_mul_f32 v[126:127], v[126:127], v[154:155] op_sel_hi:[1,0]
	v_pk_mul_f32 v[142:143], v[142:143], v[84:85] op_sel_hi:[1,0]
	v_pk_mul_f32 v[108:109], v[108:109], v[120:121] op_sel_hi:[1,0]
	v_pk_mul_f32 v[112:113], v[112:113], v[124:125] op_sel_hi:[1,0]
	v_pk_mul_f32 v[116:117], v[116:117], v[128:129] op_sel_hi:[1,0]
	v_pk_mul_f32 v[144:145], v[144:145], v[150:151] op_sel_hi:[1,0]
	v_pk_mul_f32 v[146:147], v[146:147], v[152:153] op_sel_hi:[1,0]
	v_pk_mul_f32 v[148:149], v[148:149], v[154:155] op_sel_hi:[1,0]
	v_addc_co_u32_e32 v23, vcc, 0, v107, vcc
	v_add_co_u32_e32 v106, vcc, s70, v106
	v_pk_mul_f32 v[10:11], v[10:11], v[56:57] op_sel_hi:[1,0]
	s_nop 0
	v_addc_co_u32_e32 v107, vcc, 0, v107, vcc
	v_pk_mul_f32 v[12:13], v[12:13], v[56:57] op_sel_hi:[1,0]
	v_pk_mul_f32 v[14:15], v[14:15], v[84:85] op_sel_hi:[1,0]
	v_pk_mul_f32 v[70:71], v[70:71], v[120:121] op_sel_hi:[1,0]
	v_pk_mul_f32 v[86:87], v[86:87], v[124:125] op_sel_hi:[1,0]
	v_pk_mul_f32 v[90:91], v[90:91], v[128:129] op_sel_hi:[1,0]
	v_pk_mul_f32 v[94:95], v[94:95], v[150:151] op_sel_hi:[1,0]
	v_pk_mul_f32 v[98:99], v[98:99], v[152:153] op_sel_hi:[1,0]
	v_pk_mul_f32 v[102:103], v[102:103], v[154:155] op_sel_hi:[1,0]
	v_pk_mul_f32 v[72:73], v[72:73], v[120:121] op_sel_hi:[1,0]
	v_pk_mul_f32 v[88:89], v[88:89], v[124:125] op_sel_hi:[1,0]
	v_pk_mul_f32 v[92:93], v[92:93], v[128:129] op_sel_hi:[1,0]
	v_pk_mul_f32 v[96:97], v[96:97], v[150:151] op_sel_hi:[1,0]
	v_pk_mul_f32 v[100:101], v[100:101], v[152:153] op_sel_hi:[1,0]
	v_pk_mul_f32 v[104:105], v[104:105], v[154:155] op_sel_hi:[1,0]
	v_pk_mul_f32 v[8:9], v[8:9], v[56:57] op_sel_hi:[1,0]
	v_pk_mul_f32 v[6:7], v[6:7], v[56:57] op_sel_hi:[1,0]
	v_pk_mul_f32 v[46:47], v[46:47], v[84:85] op_sel_hi:[1,0]
	v_pk_mul_f32 v[58:59], v[58:59], v[120:121] op_sel_hi:[1,0]
	v_pk_mul_f32 v[62:63], v[62:63], v[124:125] op_sel_hi:[1,0]
	v_pk_mul_f32 v[66:67], v[66:67], v[128:129] op_sel_hi:[1,0]
	v_pk_mul_f32 v[74:75], v[74:75], v[150:151] op_sel_hi:[1,0]
	v_pk_mul_f32 v[78:79], v[78:79], v[152:153] op_sel_hi:[1,0]
	v_pk_mul_f32 v[52:53], v[52:53], v[154:155] op_sel_hi:[1,0]
	s_add_i32 s56, s56, s58
	v_pk_mul_f32 v[4:5], v[4:5], v[56:57] op_sel_hi:[1,0]
	v_pk_mul_f32 v[2:3], v[2:3], v[56:57] op_sel_hi:[1,0]
	s_add_u32 s60, s60, s62
	v_pk_mul_f32 v[24:25], v[24:25], v[120:121] op_sel_hi:[1,0]
	v_pk_mul_f32 v[28:29], v[28:29], v[124:125] op_sel_hi:[1,0]
	v_pk_mul_f32 v[32:33], v[32:33], v[128:129] op_sel_hi:[1,0]
	v_pk_mul_f32 v[36:37], v[36:37], v[150:151] op_sel_hi:[1,0]
	v_pk_mul_f32 v[40:41], v[40:41], v[152:153] op_sel_hi:[1,0]
	v_pk_mul_f32 v[44:45], v[44:45], v[154:155] op_sel_hi:[1,0]
	s_addc_u32 s61, s61, s63
	v_lshl_add_u64 v[136:137], v[136:137], 0, s[64:65]
	s_cmp_lt_i32 s56, 0x8000
	v_lshl_add_u64 v[138:139], v[138:139], 0, s[66:67]
	s_waitcnt vmcnt(0) lgkmcnt(0)
	v_pk_fma_f32 v[170:171], v[170:171], v[158:159], v[162:163]
	v_pk_fma_f32 v[164:165], v[164:165], v[156:157], v[160:161]
	v_pk_fma_f32 v[142:143], v[142:143], v[158:159], v[162:163]
	v_pk_fma_f32 v[166:167], v[166:167], v[156:157], v[160:161]
	v_pk_fma_f32 v[108:109], v[108:109], v[158:159], v[162:163]
	v_pk_fma_f32 v[168:169], v[168:169], v[156:157], v[160:161]
	v_pk_fma_f32 v[112:113], v[112:113], v[158:159], v[162:163]
	v_pk_fma_f32 v[110:111], v[110:111], v[156:157], v[160:161]
	v_pk_fma_f32 v[116:117], v[116:117], v[158:159], v[162:163]
	v_pk_fma_f32 v[114:115], v[114:115], v[156:157], v[160:161]
	v_pk_fma_f32 v[144:145], v[144:145], v[158:159], v[162:163]
	v_pk_fma_f32 v[118:119], v[118:119], v[156:157], v[160:161]
	v_pk_fma_f32 v[146:147], v[146:147], v[158:159], v[162:163]
	v_pk_fma_f32 v[122:123], v[122:123], v[156:157], v[160:161]
	v_pk_fma_f32 v[148:149], v[148:149], v[158:159], v[162:163]
	v_pk_fma_f32 v[126:127], v[126:127], v[156:157], v[160:161]
	v_cvt_pk_bf16_f32 v156, v164, v165
	v_cvt_pk_bf16_f32 v157, v170, v171
	v_cvt_pk_bf16_f32 v158, v166, v167
	v_cvt_pk_bf16_f32 v159, v142, v143
	v_cvt_pk_bf16_f32 v142, v168, v169
	v_cvt_pk_bf16_f32 v143, v108, v109
	v_cvt_pk_bf16_f32 v108, v110, v111
	v_cvt_pk_bf16_f32 v109, v112, v113
	v_cvt_pk_bf16_f32 v110, v114, v115
	v_cvt_pk_bf16_f32 v111, v116, v117
	v_cvt_pk_bf16_f32 v112, v118, v119
	v_cvt_pk_bf16_f32 v113, v144, v145
	v_cvt_pk_bf16_f32 v114, v122, v123
	v_cvt_pk_bf16_f32 v115, v146, v147
	v_cvt_pk_bf16_f32 v116, v126, v127
	v_cvt_pk_bf16_f32 v117, v148, v149
	global_store_dwordx2 v[18:19], v[156:157], off
	global_store_dwordx2 v[18:19], v[158:159], off offset:2048
	global_store_dwordx2 v[20:21], v[142:143], off
	global_store_dwordx2 v[20:21], v[108:109], off offset:2048
	global_store_dwordx2 v[22:23], v[110:111], off
	global_store_dwordx2 v[22:23], v[112:113], off offset:2048
	global_store_dwordx2 v[106:107], v[114:115], off
	global_store_dwordx2 v[106:107], v[116:117], off offset:2048
	global_load_dwordx4 v[108:111], v[132:133], off offset:1024 nt
	s_nop 0
	global_load_dwordx4 v[112:115], v[134:135], off offset:1024 nt
	v_pk_mul_f32 v[116:117], v[140:141], v[84:85] op_sel_hi:[1,0]
	s_waitcnt vmcnt(0) lgkmcnt(0)
	v_pk_fma_f32 v[12:13], v[12:13], v[110:111], v[114:115]
	v_pk_fma_f32 v[10:11], v[10:11], v[108:109], v[112:113]
	v_pk_fma_f32 v[116:117], v[116:117], v[110:111], v[114:115]
	v_pk_fma_f32 v[14:15], v[14:15], v[108:109], v[112:113]
	v_pk_fma_f32 v[72:73], v[72:73], v[110:111], v[114:115]
	v_pk_fma_f32 v[70:71], v[70:71], v[108:109], v[112:113]
	v_pk_fma_f32 v[88:89], v[88:89], v[110:111], v[114:115]
	v_pk_fma_f32 v[86:87], v[86:87], v[108:109], v[112:113]
	v_pk_fma_f32 v[92:93], v[92:93], v[110:111], v[114:115]
	v_pk_fma_f32 v[90:91], v[90:91], v[108:109], v[112:113]
	v_pk_fma_f32 v[96:97], v[96:97], v[110:111], v[114:115]
	v_pk_fma_f32 v[94:95], v[94:95], v[108:109], v[112:113]
	v_pk_fma_f32 v[100:101], v[100:101], v[110:111], v[114:115]
	v_pk_fma_f32 v[98:99], v[98:99], v[108:109], v[112:113]
	v_pk_fma_f32 v[104:105], v[104:105], v[110:111], v[114:115]
	v_pk_fma_f32 v[102:103], v[102:103], v[108:109], v[112:113]
	v_cvt_pk_bf16_f32 v10, v10, v11
	v_cvt_pk_bf16_f32 v11, v12, v13
	v_cvt_pk_bf16_f32 v12, v14, v15
	v_cvt_pk_bf16_f32 v13, v116, v117
	v_cvt_pk_bf16_f32 v14, v70, v71
	v_cvt_pk_bf16_f32 v15, v72, v73
	v_cvt_pk_bf16_f32 v70, v86, v87
	v_cvt_pk_bf16_f32 v71, v88, v89
	v_cvt_pk_bf16_f32 v72, v90, v91
	v_cvt_pk_bf16_f32 v73, v92, v93
	v_cvt_pk_bf16_f32 v86, v94, v95
	v_cvt_pk_bf16_f32 v87, v96, v97
	v_cvt_pk_bf16_f32 v88, v98, v99
	v_cvt_pk_bf16_f32 v89, v100, v101
	v_cvt_pk_bf16_f32 v90, v102, v103
	v_cvt_pk_bf16_f32 v91, v104, v105
	global_store_dwordx2 v[18:19], v[10:11], off offset:512
	global_store_dwordx2 v[18:19], v[12:13], off offset:2560
	global_store_dwordx2 v[20:21], v[14:15], off offset:512
	global_store_dwordx2 v[20:21], v[70:71], off offset:2560
	global_store_dwordx2 v[22:23], v[72:73], off offset:512
	global_store_dwordx2 v[22:23], v[86:87], off offset:2560
	global_store_dwordx2 v[106:107], v[88:89], off offset:512
	global_store_dwordx2 v[106:107], v[90:91], off offset:2560
	global_load_dwordx4 v[10:13], v[132:133], off offset:2048 nt
	s_nop 0
	global_load_dwordx4 v[70:73], v[134:135], off offset:2048 nt
	v_pk_mul_f32 v[14:15], v[48:49], v[84:85] op_sel_hi:[1,0]
	v_pk_mul_f32 v[48:49], v[60:61], v[120:121] op_sel_hi:[1,0]
	v_pk_mul_f32 v[60:61], v[64:65], v[124:125] op_sel_hi:[1,0]
	v_pk_mul_f32 v[64:65], v[68:69], v[128:129] op_sel_hi:[1,0]
	v_pk_mul_f32 v[68:69], v[76:77], v[150:151] op_sel_hi:[1,0]
	v_pk_mul_f32 v[76:77], v[80:81], v[152:153] op_sel_hi:[1,0]
	v_pk_mul_f32 v[80:81], v[82:83], v[154:155] op_sel_hi:[1,0]
	s_waitcnt vmcnt(0) lgkmcnt(0)
	v_pk_fma_f32 v[8:9], v[8:9], v[12:13], v[72:73]
	v_pk_fma_f32 v[6:7], v[6:7], v[10:11], v[70:71]
	v_pk_fma_f32 v[14:15], v[14:15], v[12:13], v[72:73]
	v_pk_fma_f32 v[46:47], v[46:47], v[10:11], v[70:71]
	v_pk_fma_f32 v[48:49], v[48:49], v[12:13], v[72:73]
	v_pk_fma_f32 v[58:59], v[58:59], v[10:11], v[70:71]
	v_pk_fma_f32 v[60:61], v[60:61], v[12:13], v[72:73]
	v_pk_fma_f32 v[62:63], v[62:63], v[10:11], v[70:71]
	v_pk_fma_f32 v[64:65], v[64:65], v[12:13], v[72:73]
	v_pk_fma_f32 v[66:67], v[66:67], v[10:11], v[70:71]
	v_pk_fma_f32 v[68:69], v[68:69], v[12:13], v[72:73]
	v_pk_fma_f32 v[74:75], v[74:75], v[10:11], v[70:71]
	v_pk_fma_f32 v[76:77], v[76:77], v[12:13], v[72:73]
	v_pk_fma_f32 v[78:79], v[78:79], v[10:11], v[70:71]
	v_pk_fma_f32 v[12:13], v[52:53], v[12:13], v[72:73]
	v_pk_fma_f32 v[10:11], v[80:81], v[10:11], v[70:71]
	v_cvt_pk_bf16_f32 v6, v6, v7
	v_cvt_pk_bf16_f32 v7, v8, v9
	v_cvt_pk_bf16_f32 v8, v46, v47
	v_cvt_pk_bf16_f32 v9, v14, v15
	v_cvt_pk_bf16_f32 v14, v58, v59
	v_cvt_pk_bf16_f32 v15, v48, v49
	v_cvt_pk_bf16_f32 v46, v62, v63
	v_cvt_pk_bf16_f32 v47, v60, v61
	v_cvt_pk_bf16_f32 v48, v66, v67
	v_cvt_pk_bf16_f32 v49, v64, v65
	v_cvt_pk_bf16_f32 v52, v74, v75
	v_cvt_pk_bf16_f32 v53, v68, v69
	v_cvt_pk_bf16_f32 v58, v78, v79
	v_cvt_pk_bf16_f32 v59, v76, v77
	v_cvt_pk_bf16_f32 v10, v10, v11
	v_cvt_pk_bf16_f32 v11, v12, v13
	global_store_dwordx2 v[18:19], v[6:7], off offset:1024
	global_store_dwordx2 v[18:19], v[8:9], off offset:3072
	global_store_dwordx2 v[20:21], v[14:15], off offset:1024
	global_store_dwordx2 v[20:21], v[46:47], off offset:3072
	global_store_dwordx2 v[22:23], v[48:49], off offset:1024
	global_store_dwordx2 v[22:23], v[52:53], off offset:3072
	global_store_dwordx2 v[106:107], v[58:59], off offset:1024
	global_store_dwordx2 v[106:107], v[10:11], off offset:3072
	global_load_dwordx4 v[6:9], v[132:133], off offset:3072 nt
	s_nop 0
	global_load_dwordx4 v[10:13], v[134:135], off offset:3072 nt
	v_pk_mul_f32 v[14:15], v[16:17], v[84:85] op_sel_hi:[1,0]
	v_pk_mul_f32 v[16:17], v[26:27], v[84:85] op_sel_hi:[1,0]
	v_pk_mul_f32 v[26:27], v[30:31], v[120:121] op_sel_hi:[1,0]
	v_pk_mul_f32 v[30:31], v[34:35], v[124:125] op_sel_hi:[1,0]
	v_pk_mul_f32 v[34:35], v[38:39], v[128:129] op_sel_hi:[1,0]
	v_pk_mul_f32 v[38:39], v[42:43], v[150:151] op_sel_hi:[1,0]
	v_pk_mul_f32 v[42:43], v[50:51], v[152:153] op_sel_hi:[1,0]
	v_pk_mul_f32 v[46:47], v[54:55], v[154:155] op_sel_hi:[1,0]
	s_waitcnt vmcnt(0) lgkmcnt(0)
	v_pk_fma_f32 v[4:5], v[4:5], v[8:9], v[12:13]
	v_pk_fma_f32 v[2:3], v[2:3], v[6:7], v[10:11]
	v_pk_fma_f32 v[14:15], v[14:15], v[8:9], v[12:13]
	v_pk_fma_f32 v[16:17], v[16:17], v[6:7], v[10:11]
	v_pk_fma_f32 v[24:25], v[24:25], v[8:9], v[12:13]
	v_pk_fma_f32 v[26:27], v[26:27], v[6:7], v[10:11]
	v_pk_fma_f32 v[28:29], v[28:29], v[8:9], v[12:13]
	v_pk_fma_f32 v[30:31], v[30:31], v[6:7], v[10:11]
	v_pk_fma_f32 v[32:33], v[32:33], v[8:9], v[12:13]
	v_pk_fma_f32 v[34:35], v[34:35], v[6:7], v[10:11]
	v_pk_fma_f32 v[36:37], v[36:37], v[8:9], v[12:13]
	v_pk_fma_f32 v[38:39], v[38:39], v[6:7], v[10:11]
	v_pk_fma_f32 v[40:41], v[40:41], v[8:9], v[12:13]
	v_pk_fma_f32 v[42:43], v[42:43], v[6:7], v[10:11]
	v_pk_fma_f32 v[8:9], v[44:45], v[8:9], v[12:13]
	v_pk_fma_f32 v[6:7], v[46:47], v[6:7], v[10:11]
	v_cvt_pk_bf16_f32 v2, v2, v3
	v_cvt_pk_bf16_f32 v3, v4, v5
	v_cvt_pk_bf16_f32 v4, v16, v17
	v_cvt_pk_bf16_f32 v5, v14, v15
	v_cvt_pk_bf16_f32 v10, v26, v27
	v_cvt_pk_bf16_f32 v11, v24, v25
	v_cvt_pk_bf16_f32 v12, v30, v31
	v_cvt_pk_bf16_f32 v13, v28, v29
	v_cvt_pk_bf16_f32 v14, v34, v35
	v_cvt_pk_bf16_f32 v15, v32, v33
	v_cvt_pk_bf16_f32 v16, v38, v39
	v_cvt_pk_bf16_f32 v17, v36, v37
	v_cvt_pk_bf16_f32 v24, v42, v43
	v_cvt_pk_bf16_f32 v25, v40, v41
	v_cvt_pk_bf16_f32 v6, v6, v7
	v_cvt_pk_bf16_f32 v7, v8, v9
	global_store_dwordx2 v[18:19], v[2:3], off offset:1536
	global_store_dwordx2 v[18:19], v[4:5], off offset:3584
	global_store_dwordx2 v[20:21], v[10:11], off offset:1536
	global_store_dwordx2 v[20:21], v[12:13], off offset:3584
	global_store_dwordx2 v[22:23], v[14:15], off offset:1536
	global_store_dwordx2 v[22:23], v[16:17], off offset:3584
	global_store_dwordx2 v[106:107], v[24:25], off offset:1536
	global_store_dwordx2 v[106:107], v[6:7], off offset:3584
	s_cbranch_scc0 .LBB0_149
.LBB0_133:
	v_add_co_u32_e32 v2, vcc, 0xffff8400, v138
	s_nop 1
	v_addc_co_u32_e32 v3, vcc, -1, v139, vcc
	v_add_co_u32_e32 v4, vcc, 0xffff8800, v138
	s_nop 1
	v_addc_co_u32_e32 v5, vcc, -1, v139, vcc
	global_load_dwordx4 v[18:21], v[2:3], off nt
	global_load_dwordx4 v[10:13], v[4:5], off nt
	v_add_co_u32_e32 v2, vcc, 0xffff8c00, v138
	s_waitcnt vmcnt(0) lgkmcnt(0)
	v_add_f32_e32 v33, v12, v13
	v_addc_co_u32_e32 v3, vcc, -1, v139, vcc
	global_load_dwordx4 v[6:9], v[2:3], off nt
	v_add_co_u32_e32 v2, vcc, 0xffff9000, v138
	s_waitcnt vmcnt(0) lgkmcnt(0)
	v_add_f32_e32 v35, v8, v9
	v_addc_co_u32_e32 v3, vcc, -1, v139, vcc
	global_load_dwordx4 v[2:5], v[2:3], off nt
	v_add_co_u32_e32 v26, vcc, 0xffff9400, v138
	s_nop 1
	v_addc_co_u32_e32 v27, vcc, -1, v139, vcc
	v_add_co_u32_e32 v30, vcc, 0xffff9800, v138
	s_nop 1
	v_addc_co_u32_e32 v31, vcc, -1, v139, vcc
	global_load_dwordx4 v[22:25], v[26:27], off nt
	global_load_dwordx4 v[14:17], v[30:31], off nt
	v_add_f32_e32 v27, v18, v19
	v_add_f32_e32 v31, v20, v21
	v_add_f32_e32 v27, v27, v31
	v_add_f32_e32 v31, v10, v11
	v_add_f32_e32 v27, 0, v27
	v_add_f32_e32 v31, v31, v33
	v_add_f32_e32 v33, v6, v7
	v_add_f32_e32 v27, v27, v31
	v_add_f32_e32 v31, v33, v35
	v_add_f32_e32 v27, v27, v31
	v_add_co_u32_e32 v28, vcc, 0xffff9c00, v138
	s_waitcnt vmcnt(0) lgkmcnt(0)
	v_add_f32_e32 v33, v2, v3
	v_add_f32_e32 v35, v4, v5
	v_add_f32_e32 v31, v33, v35
	v_add_f32_e32 v27, v27, v31
	ds_swizzle_b32 v31, v27 offset:swizzle(SWAP,1)
	v_addc_co_u32_e32 v29, vcc, -1, v139, vcc
	v_add_co_u32_e32 v26, vcc, 0xffffa000, v138
	s_waitcnt lgkmcnt(0)
	v_add_f32_e32 v27, v27, v31
	ds_swizzle_b32 v31, v27 offset:swizzle(SWAP,2)
	s_mov_b64 s[8:9], vcc
	v_add_co_u32_e32 v32, vcc, 0xffffa400, v138
	s_mov_b64 s[6:7], vcc
	s_waitcnt lgkmcnt(0)
	v_add_f32_e32 v27, v27, v31
	ds_swizzle_b32 v31, v27 offset:swizzle(SWAP,4)
	v_add_co_u32_e32 v34, vcc, 0xffffa800, v138
	s_mov_b64 s[4:5], vcc
	v_add_co_u32_e32 v30, vcc, 0xffffac00, v138
	s_waitcnt lgkmcnt(0)
	v_add_f32_e32 v27, v27, v31
	ds_swizzle_b32 v31, v27 offset:swizzle(SWAP,8)
	s_mov_b64 s[2:3], vcc
	v_add_co_u32_e32 v62, vcc, 0xffffb000, v138
	s_mov_b64 s[28:29], vcc
	s_waitcnt lgkmcnt(0)
	v_add_f32_e32 v27, v27, v31
	ds_swizzle_b32 v31, v27 offset:swizzle(SWAP,16)
	v_add_co_u32_e32 v54, vcc, 0xffffb400, v138
	s_mov_b64 s[24:25], vcc
	v_add_co_u32_e32 v56, vcc, 0xffffb800, v138
	s_waitcnt lgkmcnt(0)
	v_add_f32_e32 v27, v27, v31
	v_mov_b32_e32 v31, v27
	s_nop 1
	v_permlane32_swap_b32_e32 v27, v31
	v_add_f32_e32 v150, v27, v31
	v_fmamk_f32 v21, v150, 0xba800000, v21
	v_fmamk_f32 v19, v150, 0xba800000, v19
	v_fmamk_f32 v20, v150, 0xba800000, v20
	v_fmac_f32_e32 v18, 0xba800000, v150
	v_mul_f32_e32 v27, v19, v19
	v_mul_f32_e32 v31, v21, v21
	v_fmamk_f32 v13, v150, 0xba800000, v13
	v_fmamk_f32 v11, v150, 0xba800000, v11
	v_fmac_f32_e32 v27, v18, v18
	v_fmac_f32_e32 v31, v20, v20
	v_fmamk_f32 v12, v150, 0xba800000, v12
	v_fmac_f32_e32 v10, 0xba800000, v150
	v_add_f32_e32 v27, v27, v31
	v_mul_f32_e32 v31, v11, v11
	v_mul_f32_e32 v33, v13, v13
	v_fmac_f32_e32 v31, v10, v10
	v_fmac_f32_e32 v33, v12, v12
	v_add_f32_e32 v31, v31, v33
	v_fmamk_f32 v9, v150, 0xba800000, v9
	v_fmamk_f32 v7, v150, 0xba800000, v7
	v_add_f32_e32 v27, v27, v31
	v_fmamk_f32 v8, v150, 0xba800000, v8
	v_fmac_f32_e32 v6, 0xba800000, v150
	v_mul_f32_e32 v31, v7, v7
	v_mul_f32_e32 v33, v9, v9
	v_fmac_f32_e32 v31, v6, v6
	v_fmac_f32_e32 v33, v8, v8
	v_add_f32_e32 v31, v31, v33
	v_fmamk_f32 v5, v150, 0xba800000, v5
	v_fmamk_f32 v3, v150, 0xba800000, v3
	v_add_f32_e32 v27, v31, v27
	v_fmamk_f32 v4, v150, 0xba800000, v4
	v_fmac_f32_e32 v2, 0xba800000, v150
	v_mul_f32_e32 v31, v3, v3
	v_mul_f32_e32 v33, v5, v5
	v_fmac_f32_e32 v31, v2, v2
	v_fmac_f32_e32 v33, v4, v4
	v_add_f32_e32 v31, v31, v33
	v_add_f32_e32 v27, v31, v27
	ds_swizzle_b32 v31, v27 offset:swizzle(SWAP,1)
	s_mov_b64 s[26:27], vcc
	v_add_co_u32_e32 v36, vcc, 0xffffbc00, v138
	s_mov_b64 s[18:19], vcc
	s_waitcnt lgkmcnt(0)
	v_add_f32_e32 v27, v27, v31
	ds_swizzle_b32 v31, v27 offset:swizzle(SWAP,2)
	v_add_co_u32_e32 v52, vcc, 0xffffc000, v138
	s_mov_b64 s[22:23], vcc
	v_add_co_u32_e32 v40, vcc, 0xffffc400, v138
	s_waitcnt lgkmcnt(0)
	v_add_f32_e32 v27, v27, v31
	ds_swizzle_b32 v31, v27 offset:swizzle(SWAP,4)
	s_mov_b64 s[16:17], vcc
	v_add_co_u32_e32 v50, vcc, 0xffffc800, v138
	s_mov_b64 s[20:21], vcc
	s_waitcnt lgkmcnt(0)
	v_add_f32_e32 v27, v27, v31
	ds_swizzle_b32 v31, v27 offset:swizzle(SWAP,8)
	v_add_co_u32_e32 v38, vcc, 0xffffcc00, v138
	s_mov_b64 s[12:13], vcc
	v_add_co_u32_e32 v44, vcc, 0xffffd000, v138
	s_mov_b64 s[14:15], vcc
	v_add_co_u32_e32 v42, vcc, 0xffffd400, v138
	s_waitcnt lgkmcnt(0)
	v_add_f32_e32 v31, v27, v31
	s_mov_b64 s[10:11], vcc
	v_add_co_u32_e32 v76, vcc, 0xffffd800, v138
	ds_swizzle_b32 v33, v31 offset:swizzle(SWAP,16)
	s_mov_b64 s[42:43], vcc
	v_add_co_u32_e32 v74, vcc, 0xffffdc00, v138
	s_mov_b64 s[36:37], vcc
	v_add_co_u32_e32 v84, vcc, 0xffffe000, v138
	s_mov_b64 s[40:41], vcc
	v_add_co_u32_e32 v80, vcc, 0xffffe400, v138
	s_mov_b64 s[34:35], vcc
	v_add_co_u32_e32 v82, vcc, 0xffffe800, v138
	global_load_dwordx4 v[46:49], v[28:29], off nt
	s_mov_b64 s[38:39], vcc
	v_add_co_u32_e32 v78, vcc, 0xffffec00, v138
	s_waitcnt lgkmcnt(0)
	v_add_f32_e32 v31, v31, v33
	s_mov_b64 s[30:31], vcc
	v_add_co_u32_e32 v102, vcc, 0xfffff000, v138
	v_mov_b32_e32 v33, v31
	s_mov_b64 s[48:49], vcc
	v_add_co_u32_e32 v104, vcc, 0xfffff400, v138
	v_permlane32_swap_b32_e32 v31, v33
	s_mov_b64 s[44:45], vcc
	v_add_co_u32_e32 v140, vcc, 0xfffff800, v138
	v_add_f32_e32 v31, v31, v33
	s_mov_b64 s[46:47], vcc
	v_addc_co_u32_e64 v27, vcc, -1, v139, s[8:9]
	v_fmamk_f32 v31, v31, 0x3a800000, v1
	v_add_f32_e32 v35, v22, v23
	v_add_f32_e32 v37, v24, v25
	v_mul_f32_e32 v33, 0x4f800000, v31
	v_cmp_gt_f32_e32 vcc, s57, v31
	v_add_f32_e32 v41, v14, v15
	s_nop 0
	v_cndmask_b32_e32 v31, v31, v33, vcc
	v_add_f32_e32 v33, v35, v37
	v_add_f32_e32 v37, 0, v33
	v_addc_co_u32_e64 v33, s[6:7], -1, v139, s[6:7]
	global_load_dwordx4 v[106:109], v[32:33], off nt
	v_sqrt_f32_e32 v39, v31
	global_load_dwordx4 v[26:29], v[26:27], off nt
	v_addc_co_u32_e64 v35, s[4:5], -1, v139, s[4:5]
	v_add_u32_e32 v32, -1, v39
	v_fma_f32 v33, -v32, v39, v31
	v_cmp_ge_f32_e64 s[6:7], 0, v33
	v_add_u32_e32 v33, 1, v39
	global_load_dwordx4 v[70:73], v[34:35], off nt
	v_cndmask_b32_e64 v32, v39, v32, s[6:7]
	v_fma_f32 v39, -v33, v39, v31
	v_cmp_lt_f32_e64 s[4:5], 0, v39
	s_nop 1
	v_cndmask_b32_e64 v32, v32, v33, s[4:5]
	v_mul_f32_e32 v33, 0x37800000, v32
	v_cndmask_b32_e32 v32, v32, v33, vcc
	v_cmp_class_f32_e32 vcc, v31, v131
	s_nop 1
	v_cndmask_b32_e32 v151, v32, v31, vcc
	v_div_scale_f32 v32, s[4:5], v151, v151, 1.0
	v_rcp_f32_e32 v34, v32
	v_add_f32_e32 v31, v16, v17
	v_add_f32_e32 v31, v41, v31
	v_add_f32_e32 v39, v37, v31
	v_fma_f32 v31, -v32, v34, 1.0
	v_fmac_f32_e32 v34, v31, v34
	v_addc_co_u32_e64 v31, vcc, -1, v139, s[2:3]
	global_load_dwordx4 v[58:61], v[30:31], off nt
	v_div_scale_f32 v30, s[4:5], 1.0, v151, 1.0
	v_mul_f32_e32 v35, v30, v34
	v_fma_f32 v31, -v32, v35, v30
	v_fmac_f32_e32 v35, v31, v34
	v_addc_co_u32_e64 v63, vcc, -1, v139, s[28:29]
	v_fma_f32 v37, -v32, v35, v30
	global_load_dwordx4 v[30:33], v[62:63], off nt
	v_add_co_u32_e32 v142, vcc, 0xfffffc00, v138
	s_mov_b64 s[2:3], vcc
	v_addc_co_u32_e64 v55, vcc, -1, v139, s[24:25]
	v_addc_co_u32_e64 v57, vcc, -1, v139, s[26:27]
	global_load_dwordx4 v[110:113], v[54:55], off nt
	global_load_dwordx4 v[86:89], v[56:57], off nt
	s_mov_b64 vcc, s[4:5]
	s_nop 0
	v_div_fmas_f32 v152, v37, v34, v35
	s_waitcnt vmcnt(0)
	v_add_f32_e32 v34, v46, v47
	v_add_f32_e32 v35, v48, v49
	v_addc_co_u32_e64 v37, vcc, -1, v139, s[18:19]
	global_load_dwordx4 v[62:65], v[36:37], off nt
	v_add_f32_e32 v41, v34, v35
	v_addc_co_u32_e64 v53, vcc, -1, v139, s[22:23]
	v_add_f32_e32 v43, v39, v41
	v_addc_co_u32_e64 v39, vcc, -1, v139, s[12:13]
	global_load_dwordx4 v[66:69], v[38:39], off nt
	global_load_dwordx4 v[34:37], v[52:53], off nt
	v_addc_co_u32_e64 v41, vcc, -1, v139, s[16:17]
	global_load_dwordx4 v[114:117], v[40:41], off nt
	v_addc_co_u32_e64 v51, vcc, -1, v139, s[20:21]
	global_load_dwordx4 v[90:93], v[50:51], off nt
	v_addc_co_u32_e64 v45, vcc, -1, v139, s[14:15]
	v_addc_co_u32_e64 v77, vcc, -1, v139, s[42:43]
	global_load_dwordx4 v[94:97], v[76:77], off nt
	v_addc_co_u32_e64 v75, vcc, -1, v139, s[36:37]
	v_addc_co_u32_e64 v81, vcc, -1, v139, s[34:35]
	v_addc_co_u32_e64 v83, vcc, -1, v139, s[38:39]
	s_waitcnt lgkmcnt(0)
	v_add_f32_e32 v40, v26, v27
	v_add_f32_e32 v41, v28, v29
	v_add_f32_e32 v50, v40, v41
	global_load_dwordx4 v[38:41], v[44:45], off nt
	v_add_f32_e32 v144, v43, v50
	v_addc_co_u32_e64 v43, vcc, -1, v139, s[10:11]
	global_load_dwordx4 v[118:121], v[42:43], off nt
	v_addc_co_u32_e64 v79, vcc, -1, v139, s[30:31]
	global_load_dwordx4 v[122:125], v[80:81], off nt
	global_load_dwordx4 v[98:101], v[82:83], off nt
	v_add_f32_e32 v42, v106, v107
	global_load_dwordx4 v[78:81], v[78:79], off nt
	v_add_f32_e32 v43, v108, v109
	global_load_dwordx4 v[74:77], v[74:75], off nt
	v_addc_co_u32_e64 v85, vcc, -1, v139, s[40:41]
	v_add_f32_e32 v50, v42, v43
	global_load_dwordx4 v[42:45], v[84:85], off nt
	v_add_f32_e32 v51, v70, v71
	v_add_f32_e32 v52, v72, v73
	v_addc_co_u32_e64 v103, vcc, -1, v139, s[48:49]
	v_add_f32_e32 v54, v51, v52
	v_add_f32_e32 v55, 0, v50
	global_load_dwordx4 v[50:53], v[102:103], off nt
	v_addc_co_u32_e64 v105, vcc, -1, v139, s[44:45]
	global_load_dwordx4 v[126:129], v[104:105], off nt
	v_addc_co_u32_e64 v141, vcc, -1, v139, s[46:47]
	v_addc_co_u32_e64 v143, vcc, -1, v139, s[2:3]
	global_load_dwordx4 v[82:85], v[142:143], off nt
	global_load_dwordx4 v[102:105], v[140:141], off nt
	v_add_f32_e32 v54, v55, v54
	v_add_f32_e32 v55, v58, v59
	v_add_f32_e32 v56, v60, v61
	v_add_f32_e32 v55, v55, v56
	v_add_f32_e32 v54, v54, v55
	v_add_f32_e32 v55, v30, v31
	v_add_f32_e32 v56, v32, v33
	v_add_f32_e32 v55, v55, v56
	v_add_f32_e32 v140, v54, v55
	s_add_u32 s5, s54, s60
	v_add_f32_e32 v54, v110, v111
	v_add_f32_e32 v55, v112, v113
	v_add_f32_e32 v141, v54, v55
	global_load_dwordx4 v[54:57], v[138:139], off nt
	v_add_f32_e32 v142, v86, v87
	v_add_f32_e32 v143, v88, v89
	v_add_f32_e32 v142, v142, v143
	v_add_f32_e32 v141, 0, v141
	v_add_f32_e32 v141, v141, v142
	s_waitcnt vmcnt(0)
	v_add_f32_e32 v142, v62, v63
	v_add_f32_e32 v143, v64, v65
	v_add_f32_e32 v142, v142, v143
	v_add_f32_e32 v141, v141, v142
	s_addc_u32 s4, s55, s61
	v_add_f32_e32 v142, v34, v35
	v_add_f32_e32 v143, v36, v37
	v_add_f32_e32 v142, v142, v143
	v_add_f32_e32 v141, v141, v142
	v_add_f32_e32 v142, v114, v115
	v_add_f32_e32 v143, v116, v117
	v_add_f32_e32 v142, v142, v143
	v_add_f32_e32 v143, v90, v91
	v_add_f32_e32 v145, v92, v93
	v_add_f32_e32 v143, v143, v145
	v_add_f32_e32 v142, 0, v142
	v_add_f32_e32 v142, v142, v143
	v_add_f32_e32 v143, v66, v67
	v_add_f32_e32 v145, v68, v69
	v_add_f32_e32 v143, v143, v145
	v_add_f32_e32 v142, v142, v143
	v_add_f32_e32 v146, v96, v97
	s_waitcnt lgkmcnt(0)
	v_add_f32_e32 v143, v38, v39
	v_add_f32_e32 v145, v40, v41
	v_add_f32_e32 v143, v143, v145
	v_add_f32_e32 v142, v142, v143
	v_add_f32_e32 v143, v118, v119
	v_add_f32_e32 v145, v120, v121
	v_add_f32_e32 v143, v143, v145
	v_add_f32_e32 v145, v94, v95
	v_add_f32_e32 v145, v145, v146
	v_add_f32_e32 v143, 0, v143
	v_add_f32_e32 v143, v143, v145
	v_add_f32_e32 v147, v100, v101
	v_add_f32_e32 v145, v74, v75
	v_add_f32_e32 v146, v76, v77
	v_add_f32_e32 v145, v145, v146
	v_add_f32_e32 v143, v143, v145
	v_add_f32_e32 v145, v42, v43
	v_add_f32_e32 v146, v44, v45
	v_add_f32_e32 v145, v145, v146
	v_add_f32_e32 v143, v143, v145
	v_add_f32_e32 v145, v122, v123
	v_add_f32_e32 v146, v124, v125
	v_add_f32_e32 v145, v145, v146
	v_add_f32_e32 v146, v98, v99
	v_add_f32_e32 v146, v146, v147
	v_add_f32_e32 v145, 0, v145
	v_add_f32_e32 v145, v145, v146
	v_add_f32_e32 v146, v78, v79
	v_add_f32_e32 v147, v80, v81
	v_add_f32_e32 v146, v146, v147
	ds_swizzle_b32 v147, v144 offset:swizzle(SWAP,1)
	v_add_f32_e32 v145, v145, v146
	v_add_f32_e32 v146, v50, v51
	v_add_f32_e32 v148, v52, v53
	v_add_f32_e32 v146, v146, v148
	s_waitcnt lgkmcnt(0)
	v_add_f32_e32 v144, v144, v147
	ds_swizzle_b32 v147, v144 offset:swizzle(SWAP,2)
	v_add_f32_e32 v145, v145, v146
	v_add_f32_e32 v146, v126, v127
	v_add_f32_e32 v148, v128, v129
	v_add_f32_e32 v146, v146, v148
	s_waitcnt lgkmcnt(0)
	v_add_f32_e32 v144, v144, v147
	ds_swizzle_b32 v147, v144 offset:swizzle(SWAP,4)
	v_add_f32_e32 v148, v102, v103
	v_add_f32_e32 v149, v104, v105
	v_add_f32_e32 v148, v148, v149
	v_add_f32_e32 v146, 0, v146
	s_waitcnt lgkmcnt(0)
	v_add_f32_e32 v144, v144, v147
	ds_swizzle_b32 v147, v144 offset:swizzle(SWAP,8)
	v_add_f32_e32 v146, v146, v148
	v_add_f32_e32 v148, v82, v83
	v_add_f32_e32 v149, v84, v85
	v_add_f32_e32 v148, v148, v149
	s_waitcnt lgkmcnt(0)
	v_add_f32_e32 v144, v144, v147
	ds_swizzle_b32 v147, v144 offset:swizzle(SWAP,16)
	ds_swizzle_b32 v149, v140 offset:swizzle(SWAP,1)
	v_add_f32_e32 v146, v146, v148
	v_add_f32_e32 v148, v54, v55
	v_add_f32_e32 v153, v56, v57
	v_add_f32_e32 v148, v148, v153
	s_waitcnt lgkmcnt(1)
	v_add_f32_e32 v144, v144, v147
	s_waitcnt lgkmcnt(0)
	v_add_f32_e32 v140, v140, v149
	ds_swizzle_b32 v149, v141 offset:swizzle(SWAP,1)
	v_add_f32_e32 v146, v146, v148
	v_mov_b32_e32 v148, v144
	s_nop 1
	v_permlane32_swap_b32_e32 v144, v148
	ds_swizzle_b32 v147, v140 offset:swizzle(SWAP,2)
	v_add_f32_e32 v159, v144, v148
	ds_swizzle_b32 v144, v142 offset:swizzle(SWAP,1)
	s_waitcnt lgkmcnt(2)
	v_add_f32_e32 v141, v141, v149
	ds_swizzle_b32 v149, v141 offset:swizzle(SWAP,2)
	s_waitcnt lgkmcnt(2)
	v_add_f32_e32 v140, v140, v147
	ds_swizzle_b32 v147, v140 offset:swizzle(SWAP,4)
	s_waitcnt lgkmcnt(2)
	v_add_f32_e32 v142, v142, v144
	ds_swizzle_b32 v144, v142 offset:swizzle(SWAP,2)
	s_waitcnt lgkmcnt(2)
	v_add_f32_e32 v141, v141, v149
	ds_swizzle_b32 v148, v141 offset:swizzle(SWAP,4)
	s_waitcnt lgkmcnt(2)
	v_add_f32_e32 v140, v140, v147
	ds_swizzle_b32 v147, v140 offset:swizzle(SWAP,8)
	s_waitcnt lgkmcnt(2)
	v_add_f32_e32 v142, v142, v144
	ds_swizzle_b32 v144, v142 offset:swizzle(SWAP,4)
	s_waitcnt lgkmcnt(2)
	v_add_f32_e32 v141, v141, v148
	ds_swizzle_b32 v148, v141 offset:swizzle(SWAP,8)
	s_waitcnt lgkmcnt(2)
	v_add_f32_e32 v140, v140, v147
	ds_swizzle_b32 v147, v140 offset:swizzle(SWAP,16)
	s_waitcnt lgkmcnt(2)
	v_add_f32_e32 v142, v142, v144
	ds_swizzle_b32 v144, v142 offset:swizzle(SWAP,8)
	s_waitcnt lgkmcnt(2)
	v_add_f32_e32 v141, v141, v148
	ds_swizzle_b32 v148, v141 offset:swizzle(SWAP,16)
	s_waitcnt lgkmcnt(2)
	v_add_f32_e32 v140, v140, v147
	v_mov_b32_e32 v147, v140
	s_waitcnt lgkmcnt(1)
	v_add_f32_e32 v142, v142, v144
	ds_swizzle_b32 v144, v142 offset:swizzle(SWAP,16)
	v_permlane32_swap_b32_e32 v140, v147
	v_add_f32_e32 v158, v140, v147
	s_waitcnt lgkmcnt(1)
	v_add_f32_e32 v140, v141, v148
	ds_swizzle_b32 v147, v143 offset:swizzle(SWAP,1)
	v_mov_b32_e32 v141, v140
	s_nop 1
	v_permlane32_swap_b32_e32 v140, v141
	v_add_f32_e32 v157, v140, v141
	s_waitcnt lgkmcnt(1)
	v_add_f32_e32 v140, v142, v144
	ds_swizzle_b32 v144, v145 offset:swizzle(SWAP,1)
	s_waitcnt lgkmcnt(1)
	v_add_f32_e32 v141, v143, v147
	ds_swizzle_b32 v142, v141 offset:swizzle(SWAP,2)
	v_mov_b32_e32 v143, v140
	s_nop 1
	v_permlane32_swap_b32_e32 v140, v143
	s_waitcnt lgkmcnt(1)
	v_add_f32_e32 v144, v145, v144
	v_add_f32_e32 v156, v140, v143
	ds_swizzle_b32 v140, v146 offset:swizzle(SWAP,1)
	ds_swizzle_b32 v145, v144 offset:swizzle(SWAP,2)
	s_waitcnt lgkmcnt(2)
	v_add_f32_e32 v141, v141, v142
	ds_swizzle_b32 v142, v141 offset:swizzle(SWAP,4)
	v_fmamk_f32 v23, v159, 0xba800000, v23
	s_waitcnt lgkmcnt(2)
	v_add_f32_e32 v140, v146, v140
	s_waitcnt lgkmcnt(1)
	v_add_f32_e32 v143, v144, v145
	ds_swizzle_b32 v145, v140 offset:swizzle(SWAP,2)
	s_waitcnt lgkmcnt(1)
	v_add_f32_e32 v141, v141, v142
	ds_swizzle_b32 v142, v141 offset:swizzle(SWAP,8)
	ds_swizzle_b32 v144, v143 offset:swizzle(SWAP,4)
	v_fmamk_f32 v15, v159, 0xba800000, v15
	s_waitcnt lgkmcnt(2)
	v_add_f32_e32 v140, v140, v145
	ds_swizzle_b32 v145, v140 offset:swizzle(SWAP,4)
	s_waitcnt lgkmcnt(2)
	v_add_f32_e32 v141, v141, v142
	s_waitcnt lgkmcnt(1)
	v_add_f32_e32 v143, v143, v144
	ds_swizzle_b32 v142, v141 offset:swizzle(SWAP,16)
	ds_swizzle_b32 v144, v143 offset:swizzle(SWAP,8)
	s_waitcnt lgkmcnt(2)
	v_add_f32_e32 v140, v140, v145
	ds_swizzle_b32 v145, v140 offset:swizzle(SWAP,8)
	v_fmac_f32_e32 v22, 0xba800000, v159
	s_waitcnt lgkmcnt(2)
	v_add_f32_e32 v141, v141, v142
	s_waitcnt lgkmcnt(1)
	v_add_f32_e32 v143, v143, v144
	v_mov_b32_e32 v142, v141
	ds_swizzle_b32 v144, v143 offset:swizzle(SWAP,16)
	s_nop 0
	v_permlane32_swap_b32_e32 v141, v142
	s_waitcnt lgkmcnt(1)
	v_add_f32_e32 v140, v140, v145
	v_add_f32_e32 v155, v141, v142
	ds_swizzle_b32 v142, v140 offset:swizzle(SWAP,16)
	s_waitcnt lgkmcnt(1)
	v_add_f32_e32 v141, v143, v144
	v_mov_b32_e32 v143, v141
	s_nop 1
	v_permlane32_swap_b32_e32 v141, v143
	s_waitcnt lgkmcnt(0)
	v_add_f32_e32 v140, v140, v142
	v_add_f32_e32 v154, v141, v143
	v_mov_b32_e32 v141, v140
	s_nop 1
	v_permlane32_swap_b32_e32 v140, v141
	v_add_f32_e32 v153, v140, v141
	v_fmamk_f32 v143, v159, 0xba800000, v25
	v_fmamk_f32 v141, v159, 0xba800000, v17
	v_fmamk_f32 v142, v159, 0xba800000, v24
	v_mul_f32_e32 v24, v23, v23
	v_mul_f32_e32 v25, v143, v143
	v_fmamk_f32 v140, v159, 0xba800000, v16
	v_fmac_f32_e32 v14, 0xba800000, v159
	v_mul_f32_e32 v16, v15, v15
	v_mul_f32_e32 v17, v141, v141
	v_fmac_f32_e32 v24, v22, v22
	v_fmac_f32_e32 v25, v142, v142
	v_fmac_f32_e32 v16, v14, v14
	v_fmac_f32_e32 v17, v140, v140
	v_add_f32_e32 v24, v24, v25
	v_add_f32_e32 v16, v16, v17
	v_fmamk_f32 v49, v159, 0xba800000, v49
	v_fmamk_f32 v47, v159, 0xba800000, v47
	v_add_f32_e32 v16, v24, v16
	v_fmamk_f32 v48, v159, 0xba800000, v48
	v_fmac_f32_e32 v46, 0xba800000, v159
	v_mul_f32_e32 v17, v47, v47
	v_mul_f32_e32 v24, v49, v49
	v_fmac_f32_e32 v17, v46, v46
	v_fmac_f32_e32 v24, v48, v48
	v_add_f32_e32 v17, v17, v24
	v_add_f32_e32 v24, v17, v16
	v_fmamk_f32 v17, v159, 0xba800000, v29
	v_fmamk_f32 v27, v159, 0xba800000, v27
	v_fmamk_f32 v16, v159, 0xba800000, v28
	v_fmac_f32_e32 v26, 0xba800000, v159
	v_mul_f32_e32 v25, v27, v27
	v_mul_f32_e32 v28, v17, v17
	v_fmac_f32_e32 v25, v26, v26
	v_fmac_f32_e32 v28, v16, v16
	v_add_f32_e32 v25, v25, v28
	v_fmamk_f32 v109, v158, 0xba800000, v109
	v_fmamk_f32 v107, v158, 0xba800000, v107
	v_add_f32_e32 v160, v25, v24
	v_fmamk_f32 v108, v158, 0xba800000, v108
	v_fmac_f32_e32 v106, 0xba800000, v158
	v_mul_f32_e32 v24, v107, v107
	v_mul_f32_e32 v25, v109, v109
	v_fmac_f32_e32 v24, v106, v106
	v_fmac_f32_e32 v25, v108, v108
	v_fmamk_f32 v73, v158, 0xba800000, v73
	v_fmamk_f32 v71, v158, 0xba800000, v71
	v_add_f32_e32 v24, v24, v25
	v_fmamk_f32 v72, v158, 0xba800000, v72
	v_fmac_f32_e32 v70, 0xba800000, v158
	v_mul_f32_e32 v25, v71, v71
	v_mul_f32_e32 v28, v73, v73
	v_fmac_f32_e32 v25, v70, v70
	v_fmac_f32_e32 v28, v72, v72
	v_add_f32_e32 v25, v25, v28
	v_fmamk_f32 v61, v158, 0xba800000, v61
	v_fmamk_f32 v59, v158, 0xba800000, v59
	v_add_f32_e32 v24, v24, v25
	v_fmamk_f32 v60, v158, 0xba800000, v60
	v_fmac_f32_e32 v58, 0xba800000, v158
	v_mul_f32_e32 v25, v59, v59
	v_mul_f32_e32 v28, v61, v61
	v_fmac_f32_e32 v25, v58, v58
	v_fmac_f32_e32 v28, v60, v60
	v_add_f32_e32 v25, v25, v28
	v_add_f32_e32 v28, v25, v24
	v_fmamk_f32 v25, v158, 0xba800000, v33
	v_fmamk_f32 v31, v158, 0xba800000, v31
	v_fmamk_f32 v24, v158, 0xba800000, v32
	v_fmac_f32_e32 v30, 0xba800000, v158
	v_mul_f32_e32 v29, v31, v31
	v_mul_f32_e32 v32, v25, v25
	v_fmac_f32_e32 v29, v30, v30
	v_fmac_f32_e32 v32, v24, v24
	v_add_f32_e32 v29, v29, v32
	v_fmamk_f32 v113, v157, 0xba800000, v113
	v_fmamk_f32 v111, v157, 0xba800000, v111
	v_add_f32_e32 v161, v29, v28
	v_fmamk_f32 v112, v157, 0xba800000, v112
	v_fmac_f32_e32 v110, 0xba800000, v157
	v_mul_f32_e32 v28, v111, v111
	v_mul_f32_e32 v29, v113, v113
	v_fmac_f32_e32 v28, v110, v110
	v_fmac_f32_e32 v29, v112, v112
	v_fmamk_f32 v89, v157, 0xba800000, v89
	v_fmamk_f32 v87, v157, 0xba800000, v87
	v_add_f32_e32 v28, v28, v29
	v_fmamk_f32 v88, v157, 0xba800000, v88
	v_fmac_f32_e32 v86, 0xba800000, v157
	v_mul_f32_e32 v29, v87, v87
	v_mul_f32_e32 v32, v89, v89
	v_fmac_f32_e32 v29, v86, v86
	v_fmac_f32_e32 v32, v88, v88
	v_add_f32_e32 v29, v29, v32
	v_fmamk_f32 v65, v157, 0xba800000, v65
	v_fmamk_f32 v63, v157, 0xba800000, v63
	v_add_f32_e32 v28, v28, v29
	v_fmamk_f32 v64, v157, 0xba800000, v64
	v_fmac_f32_e32 v62, 0xba800000, v157
	v_mul_f32_e32 v29, v63, v63
	v_mul_f32_e32 v32, v65, v65
	v_fmac_f32_e32 v29, v62, v62
	v_fmac_f32_e32 v32, v64, v64
	v_add_f32_e32 v29, v29, v32
	v_add_f32_e32 v32, v29, v28
	v_fmamk_f32 v29, v157, 0xba800000, v37
	v_fmamk_f32 v35, v157, 0xba800000, v35
	v_fmamk_f32 v28, v157, 0xba800000, v36
	v_fmac_f32_e32 v34, 0xba800000, v157
	v_mul_f32_e32 v33, v35, v35
	v_mul_f32_e32 v36, v29, v29
	v_fmac_f32_e32 v33, v34, v34
	v_fmac_f32_e32 v36, v28, v28
	v_add_f32_e32 v33, v33, v36
	v_fmamk_f32 v117, v156, 0xba800000, v117
	v_fmamk_f32 v115, v156, 0xba800000, v115
	v_add_f32_e32 v162, v33, v32
	v_fmamk_f32 v116, v156, 0xba800000, v116
	v_fmac_f32_e32 v114, 0xba800000, v156
	v_mul_f32_e32 v32, v115, v115
	v_mul_f32_e32 v33, v117, v117
	v_fmac_f32_e32 v32, v114, v114
	v_fmac_f32_e32 v33, v116, v116
	v_fmamk_f32 v93, v156, 0xba800000, v93
	v_fmamk_f32 v91, v156, 0xba800000, v91
	v_add_f32_e32 v32, v32, v33
	v_fmamk_f32 v92, v156, 0xba800000, v92
	v_fmac_f32_e32 v90, 0xba800000, v156
	v_mul_f32_e32 v33, v91, v91
	v_mul_f32_e32 v36, v93, v93
	v_fmac_f32_e32 v33, v90, v90
	v_fmac_f32_e32 v36, v92, v92
	v_add_f32_e32 v33, v33, v36
	v_fmamk_f32 v69, v156, 0xba800000, v69
	v_fmamk_f32 v67, v156, 0xba800000, v67
	v_add_f32_e32 v32, v32, v33
	v_fmamk_f32 v68, v156, 0xba800000, v68
	v_fmac_f32_e32 v66, 0xba800000, v156
	v_mul_f32_e32 v33, v67, v67
	v_mul_f32_e32 v36, v69, v69
	v_fmac_f32_e32 v33, v66, v66
	v_fmac_f32_e32 v36, v68, v68
	v_add_f32_e32 v33, v33, v36
	v_add_f32_e32 v36, v33, v32
	v_fmamk_f32 v33, v156, 0xba800000, v41
	v_fmamk_f32 v39, v156, 0xba800000, v39
	v_fmamk_f32 v32, v156, 0xba800000, v40
	v_fmac_f32_e32 v38, 0xba800000, v156
	v_mul_f32_e32 v37, v39, v39
	v_mul_f32_e32 v40, v33, v33
	v_fmac_f32_e32 v37, v38, v38
	v_fmac_f32_e32 v40, v32, v32
	v_add_f32_e32 v37, v37, v40
	v_fmamk_f32 v145, v155, 0xba800000, v121
	v_fmamk_f32 v119, v155, 0xba800000, v119
	v_add_f32_e32 v163, v37, v36
	v_fmamk_f32 v144, v155, 0xba800000, v120
	v_fmac_f32_e32 v118, 0xba800000, v155
	v_mul_f32_e32 v36, v119, v119
	v_mul_f32_e32 v37, v145, v145
	v_fmac_f32_e32 v36, v118, v118
	v_fmac_f32_e32 v37, v144, v144
	v_fmamk_f32 v97, v155, 0xba800000, v97
	v_fmamk_f32 v95, v155, 0xba800000, v95
	v_add_f32_e32 v36, v36, v37
	v_fmamk_f32 v96, v155, 0xba800000, v96
	v_fmac_f32_e32 v94, 0xba800000, v155
	v_mul_f32_e32 v37, v95, v95
	v_mul_f32_e32 v40, v97, v97
	v_fmac_f32_e32 v37, v94, v94
	v_fmac_f32_e32 v40, v96, v96
	v_add_f32_e32 v37, v37, v40
	v_fmamk_f32 v77, v155, 0xba800000, v77
	v_fmamk_f32 v75, v155, 0xba800000, v75
	v_add_f32_e32 v36, v36, v37
	v_fmamk_f32 v76, v155, 0xba800000, v76
	v_fmac_f32_e32 v74, 0xba800000, v155
	v_mul_f32_e32 v37, v75, v75
	v_mul_f32_e32 v40, v77, v77
	v_fmac_f32_e32 v37, v74, v74
	v_fmac_f32_e32 v40, v76, v76
	v_add_f32_e32 v37, v37, v40
	v_add_f32_e32 v40, v37, v36
	v_fmamk_f32 v37, v155, 0xba800000, v45
	v_fmamk_f32 v43, v155, 0xba800000, v43
	v_fmamk_f32 v36, v155, 0xba800000, v44
	v_fmac_f32_e32 v42, 0xba800000, v155
	v_mul_f32_e32 v41, v43, v43
	v_mul_f32_e32 v44, v37, v37
	v_fmac_f32_e32 v41, v42, v42
	v_fmac_f32_e32 v44, v36, v36
	v_add_f32_e32 v41, v41, v44
	v_fmamk_f32 v147, v154, 0xba800000, v125
	v_fmamk_f32 v123, v154, 0xba800000, v123
	v_add_f32_e32 v121, v41, v40
	v_fmamk_f32 v146, v154, 0xba800000, v124
	v_fmac_f32_e32 v122, 0xba800000, v154
	v_mul_f32_e32 v40, v123, v123
	v_mul_f32_e32 v41, v147, v147
	v_fmac_f32_e32 v40, v122, v122
	v_fmac_f32_e32 v41, v146, v146
	v_fmamk_f32 v101, v154, 0xba800000, v101
	v_fmamk_f32 v99, v154, 0xba800000, v99
	v_add_f32_e32 v40, v40, v41
	v_fmamk_f32 v100, v154, 0xba800000, v100
	v_fmac_f32_e32 v98, 0xba800000, v154
	v_mul_f32_e32 v41, v99, v99
	v_mul_f32_e32 v44, v101, v101
	v_fmac_f32_e32 v41, v98, v98
	v_fmac_f32_e32 v44, v100, v100
	v_add_f32_e32 v41, v41, v44
	v_fmamk_f32 v81, v154, 0xba800000, v81
	v_fmamk_f32 v79, v154, 0xba800000, v79
	v_add_f32_e32 v40, v40, v41
	v_fmamk_f32 v80, v154, 0xba800000, v80
	v_fmac_f32_e32 v78, 0xba800000, v154
	v_mul_f32_e32 v41, v79, v79
	v_mul_f32_e32 v44, v81, v81
	v_fmac_f32_e32 v41, v78, v78
	v_fmac_f32_e32 v44, v80, v80
	v_add_f32_e32 v41, v41, v44
	v_add_f32_e32 v44, v41, v40
	v_fmamk_f32 v41, v154, 0xba800000, v53
	v_fmamk_f32 v51, v154, 0xba800000, v51
	v_fmamk_f32 v40, v154, 0xba800000, v52
	v_fmac_f32_e32 v50, 0xba800000, v154
	v_mul_f32_e32 v45, v51, v51
	v_mul_f32_e32 v52, v41, v41
	v_fmac_f32_e32 v45, v50, v50
	v_fmac_f32_e32 v52, v40, v40
	v_add_f32_e32 v45, v45, v52
	v_fmamk_f32 v149, v153, 0xba800000, v129
	v_fmamk_f32 v127, v153, 0xba800000, v127
	v_add_f32_e32 v124, v45, v44
	v_fmamk_f32 v148, v153, 0xba800000, v128
	v_fmac_f32_e32 v126, 0xba800000, v153
	v_mul_f32_e32 v44, v127, v127
	v_mul_f32_e32 v45, v149, v149
	v_fmac_f32_e32 v44, v126, v126
	v_fmac_f32_e32 v45, v148, v148
	v_fmamk_f32 v105, v153, 0xba800000, v105
	v_fmamk_f32 v103, v153, 0xba800000, v103
	v_add_f32_e32 v44, v44, v45
	v_fmamk_f32 v104, v153, 0xba800000, v104
	v_fmac_f32_e32 v102, 0xba800000, v153
	v_mul_f32_e32 v45, v103, v103
	v_mul_f32_e32 v52, v105, v105
	v_fmac_f32_e32 v45, v102, v102
	v_fmac_f32_e32 v52, v104, v104
	v_fmamk_f32 v53, v153, 0xba800000, v85
	ds_swizzle_b32 v85, v160 offset:swizzle(SWAP,1)
	v_add_f32_e32 v45, v45, v52
	v_fmamk_f32 v83, v153, 0xba800000, v83
	v_add_f32_e32 v44, v44, v45
	v_fmamk_f32 v52, v153, 0xba800000, v84
	v_fmac_f32_e32 v82, 0xba800000, v153
	v_mul_f32_e32 v45, v83, v83
	v_mul_f32_e32 v84, v53, v53
	v_fmac_f32_e32 v45, v82, v82
	v_fmac_f32_e32 v84, v52, v52
	v_add_f32_e32 v45, v45, v84
	v_add_f32_e32 v84, v45, v44
	v_fmamk_f32 v44, v153, 0xba800000, v56
	s_waitcnt lgkmcnt(0)
	v_add_f32_e32 v56, v160, v85
	v_fmamk_f32 v45, v153, 0xba800000, v57
	ds_swizzle_b32 v57, v56 offset:swizzle(SWAP,2)
	ds_swizzle_b32 v120, v161 offset:swizzle(SWAP,1)
	v_fmamk_f32 v55, v153, 0xba800000, v55
	v_fmac_f32_e32 v54, 0xba800000, v153
	v_mul_f32_e32 v85, v55, v55
	s_waitcnt lgkmcnt(1)
	v_add_f32_e32 v56, v56, v57
	ds_swizzle_b32 v57, v56 offset:swizzle(SWAP,4)
	s_waitcnt lgkmcnt(1)
	v_add_f32_e32 v120, v161, v120
	ds_swizzle_b32 v128, v120 offset:swizzle(SWAP,2)
	v_mul_f32_e32 v125, v45, v45
	v_fmac_f32_e32 v85, v54, v54
	s_waitcnt lgkmcnt(1)
	v_add_f32_e32 v56, v56, v57
	ds_swizzle_b32 v57, v56 offset:swizzle(SWAP,8)
	v_fmac_f32_e32 v125, v44, v44
	s_waitcnt lgkmcnt(1)
	v_add_f32_e32 v120, v120, v128
	v_add_f32_e32 v85, v85, v125
	ds_swizzle_b32 v125, v120 offset:swizzle(SWAP,4)
	s_waitcnt lgkmcnt(1)
	v_add_f32_e32 v56, v56, v57
	ds_swizzle_b32 v57, v163 offset:swizzle(SWAP,1)
	ds_swizzle_b32 v128, v162 offset:swizzle(SWAP,1)
	v_add_f32_e32 v85, v85, v84
	s_waitcnt lgkmcnt(2)
	v_add_f32_e32 v84, v120, v125
	ds_swizzle_b32 v160, v56 offset:swizzle(SWAP,16)
	s_waitcnt lgkmcnt(2)
	v_add_f32_e32 v57, v163, v57
	ds_swizzle_b32 v129, v57 offset:swizzle(SWAP,2)
	s_waitcnt lgkmcnt(2)
	v_add_f32_e32 v120, v162, v128
	ds_swizzle_b32 v125, v120 offset:swizzle(SWAP,2)
	ds_swizzle_b32 v128, v84 offset:swizzle(SWAP,8)
	s_waitcnt lgkmcnt(2)
	v_add_f32_e32 v57, v57, v129
	ds_swizzle_b32 v129, v57 offset:swizzle(SWAP,4)
	s_waitcnt lgkmcnt(2)
	v_add_f32_e32 v120, v120, v125
	s_waitcnt lgkmcnt(1)
	v_add_f32_e32 v128, v84, v128
	v_add_f32_e32 v84, v56, v160
	ds_swizzle_b32 v125, v120 offset:swizzle(SWAP,4)
	s_waitcnt lgkmcnt(1)
	v_add_f32_e32 v56, v57, v129
	ds_swizzle_b32 v161, v128 offset:swizzle(SWAP,16)
	ds_swizzle_b32 v57, v56 offset:swizzle(SWAP,8)
	ds_swizzle_b32 v129, v121 offset:swizzle(SWAP,1)
	s_waitcnt lgkmcnt(3)
	v_add_f32_e32 v125, v120, v125
	ds_swizzle_b32 v162, v125 offset:swizzle(SWAP,8)
	s_waitcnt lgkmcnt(3)
	v_add_f32_e32 v120, v128, v161
	s_waitcnt lgkmcnt(2)
	v_add_f32_e32 v56, v56, v57
	ds_swizzle_b32 v57, v124 offset:swizzle(SWAP,1)
	ds_swizzle_b32 v161, v85 offset:swizzle(SWAP,1)
	s_waitcnt lgkmcnt(3)
	v_add_f32_e32 v121, v121, v129
	ds_swizzle_b32 v129, v121 offset:swizzle(SWAP,2)
	s_waitcnt lgkmcnt(3)
	v_add_f32_e32 v125, v125, v162
	s_waitcnt lgkmcnt(2)
	v_add_f32_e32 v57, v124, v57
	s_waitcnt lgkmcnt(1)
	v_add_f32_e32 v85, v85, v161
	ds_swizzle_b32 v124, v57 offset:swizzle(SWAP,2)
	ds_swizzle_b32 v161, v85 offset:swizzle(SWAP,2)
	s_waitcnt lgkmcnt(2)
	v_add_f32_e32 v121, v121, v129
	ds_swizzle_b32 v129, v121 offset:swizzle(SWAP,4)
	ds_swizzle_b32 v128, v125 offset:swizzle(SWAP,16)
	s_waitcnt lgkmcnt(3)
	v_add_f32_e32 v57, v57, v124
	s_waitcnt lgkmcnt(2)
	v_add_f32_e32 v85, v85, v161
	ds_swizzle_b32 v124, v57 offset:swizzle(SWAP,4)
	ds_swizzle_b32 v161, v85 offset:swizzle(SWAP,4)
	s_waitcnt lgkmcnt(3)
	v_add_f32_e32 v121, v121, v129
	ds_swizzle_b32 v129, v121 offset:swizzle(SWAP,8)
	ds_swizzle_b32 v160, v56 offset:swizzle(SWAP,16)
	s_waitcnt lgkmcnt(3)
	v_add_f32_e32 v57, v57, v124
	s_waitcnt lgkmcnt(2)
	v_add_f32_e32 v85, v85, v161
	ds_swizzle_b32 v124, v57 offset:swizzle(SWAP,8)
	ds_swizzle_b32 v161, v85 offset:swizzle(SWAP,8)
	s_waitcnt lgkmcnt(3)
	v_add_f32_e32 v121, v121, v129
	ds_swizzle_b32 v129, v121 offset:swizzle(SWAP,16)
	v_mov_b32_e32 v164, v84
	s_waitcnt lgkmcnt(2)
	v_add_f32_e32 v57, v57, v124
	s_waitcnt lgkmcnt(1)
	v_add_f32_e32 v85, v85, v161
	ds_swizzle_b32 v162, v57 offset:swizzle(SWAP,16)
	ds_swizzle_b32 v161, v85 offset:swizzle(SWAP,16)
	v_add_f32_e32 v124, v125, v128
	v_add_f32_e32 v128, v56, v160
	s_waitcnt lgkmcnt(2)
	v_add_f32_e32 v129, v121, v129
	s_waitcnt lgkmcnt(1)
	v_add_f32_e32 v121, v57, v162
	s_waitcnt lgkmcnt(0)
	v_add_f32_e32 v57, v85, v161
	v_mov_b32_e32 v163, v120
	v_mov_b32_e32 v162, v124
	v_mov_b32_e32 v161, v128
	v_mov_b32_e32 v160, v129
	v_mov_b32_e32 v125, v121
	v_mov_b32_e32 v85, v57
	v_permlane32_swap_b32_e32 v84, v164
	v_permlane32_swap_b32_e32 v120, v163
	v_permlane32_swap_b32_e32 v124, v162
	v_permlane32_swap_b32_e32 v128, v161
	v_permlane32_swap_b32_e32 v129, v160
	v_permlane32_swap_b32_e32 v121, v125
	v_permlane32_swap_b32_e32 v57, v85
	v_div_fixup_f32 v56, v152, v151, 1.0
	s_and_saveexec_b64 s[2:3], s[0:1]
	s_cbranch_execz .LBB0_135
	v_mov_b32_e32 v151, s5
	v_add_co_u32_e32 v166, vcc, 0x1fa00000, v151
	v_mov_b32_e32 v151, s4
	v_mul_f32_e32 v150, 0x3a800000, v150
	v_addc_co_u32_e32 v167, vcc, 0, v151, vcc
	v_mov_b32_e32 v151, v56
	global_store_dwordx2 v[166:167], v[150:151], off

.LBB0_1222:
	s_or_b64 exec, exec, s[6:7]
	global_load_dwordx4 v[126:129], v[134:135], off nt
	global_load_dwordx4 v[130:133], v[136:137], off nt
	v_pk_mul_f32 v[94:95], v[150:151], v[74:75] op_sel_hi:[1,0]
	v_pk_mul_f32 v[104:105], v[104:105], v[74:75] op_sel_hi:[1,0]
	v_lshl_add_u64 v[62:63], s[8:9], 0, v[138:139]
	s_mov_b32 s6, 0x3a00000
	v_pk_mul_f32 v[96:97], v[96:97], v[78:79] op_sel_hi:[1,0]
	v_pk_mul_f32 v[64:65], v[64:65], v[74:75] op_sel_hi:[1,0]
	v_pk_mul_f32 v[34:35], v[34:35], v[74:75] op_sel_hi:[1,0]
	v_pk_mul_f32 v[32:33], v[32:33], v[74:75] op_sel_hi:[1,0]
	v_pk_mul_f32 v[2:3], v[2:3], v[74:75] op_sel_hi:[1,0]
	v_pk_mul_f32 v[0:1], v[0:1], v[74:75] op_sel_hi:[1,0]
	s_add_i32 s10, s10, s12
	s_add_u32 s14, s14, s16
	s_addc_u32 s15, s15, s17
	v_lshl_add_u64 v[138:139], v[138:139], 0, s[18:19]
	v_lshl_add_u64 v[140:141], v[140:141], 0, s[20:21]
	s_cmp_lt_i32 s10, 0x8000
	s_waitcnt vmcnt(0) lgkmcnt(0)
	v_pk_fma_f32 v[94:95], v[94:95], v[128:129], v[132:133]
	v_pk_fma_f32 v[104:105], v[104:105], v[126:127], v[130:131]
	v_cvt_pk_bf16_f32 v151, v94, v95
	v_pk_mul_f32 v[94:95], v[98:99], v[78:79] op_sel_hi:[1,0]
	v_cvt_pk_bf16_f32 v150, v104, v105
	v_add_co_u32_e32 v104, vcc, s6, v62
	v_pk_fma_f32 v[94:95], v[94:95], v[128:129], v[132:133]
	v_pk_fma_f32 v[96:97], v[96:97], v[126:127], v[130:131]
	v_addc_co_u32_e32 v105, vcc, 0, v63, vcc
	v_cvt_pk_bf16_f32 v96, v96, v97
	v_cvt_pk_bf16_f32 v97, v94, v95
	global_store_dwordx2 v[104:105], v[96:97], off offset:2048
	v_pk_mul_f32 v[94:95], v[152:153], v[82:83] op_sel_hi:[1,0]
	v_pk_mul_f32 v[96:97], v[108:109], v[82:83] op_sel_hi:[1,0]
	s_mov_b32 s6, 0x3a01000
	v_pk_fma_f32 v[94:95], v[94:95], v[128:129], v[132:133]
	v_pk_fma_f32 v[96:97], v[96:97], v[126:127], v[130:131]
	v_add_co_u32_e32 v108, vcc, s6, v62
	v_cvt_pk_bf16_f32 v96, v96, v97
	v_cvt_pk_bf16_f32 v97, v94, v95
	v_addc_co_u32_e32 v109, vcc, 0, v63, vcc
	global_store_dwordx2 v[108:109], v[96:97], off
	v_pk_mul_f32 v[94:95], v[154:155], v[86:87] op_sel_hi:[1,0]
	v_pk_mul_f32 v[96:97], v[100:101], v[86:87] op_sel_hi:[1,0]
	v_pk_fma_f32 v[94:95], v[94:95], v[128:129], v[132:133]
	v_pk_fma_f32 v[96:97], v[96:97], v[126:127], v[130:131]
	s_mov_b32 s6, 0x3a02000
	v_cvt_pk_bf16_f32 v96, v96, v97
	v_cvt_pk_bf16_f32 v97, v94, v95
	global_store_dwordx2 v[108:109], v[96:97], off offset:2048
	v_pk_mul_f32 v[94:95], v[156:157], v[90:91] op_sel_hi:[1,0]
	v_pk_mul_f32 v[96:97], v[116:117], v[90:91] op_sel_hi:[1,0]
	v_pk_fma_f32 v[94:95], v[94:95], v[128:129], v[132:133]
	v_pk_fma_f32 v[96:97], v[96:97], v[126:127], v[130:131]
	v_add_co_u32_e32 v116, vcc, s6, v62
	v_cvt_pk_bf16_f32 v96, v96, v97
	v_cvt_pk_bf16_f32 v97, v94, v95
	v_addc_co_u32_e32 v117, vcc, 0, v63, vcc
	global_store_dwordx2 v[116:117], v[96:97], off
	v_pk_mul_f32 v[94:95], v[158:159], v[102:103] op_sel_hi:[1,0]
	v_pk_mul_f32 v[96:97], v[112:113], v[102:103] op_sel_hi:[1,0]
	v_pk_fma_f32 v[94:95], v[94:95], v[128:129], v[132:133]
	v_pk_fma_f32 v[96:97], v[96:97], v[126:127], v[130:131]
	s_mov_b32 s6, 0x3a03000
	v_cvt_pk_bf16_f32 v96, v96, v97
	v_cvt_pk_bf16_f32 v97, v94, v95
	global_store_dwordx2 v[116:117], v[96:97], off offset:2048
	v_pk_mul_f32 v[94:95], v[160:161], v[114:115] op_sel_hi:[1,0]
	v_pk_mul_f32 v[96:97], v[124:125], v[114:115] op_sel_hi:[1,0]
	v_pk_fma_f32 v[94:95], v[94:95], v[128:129], v[132:133]
	v_pk_fma_f32 v[96:97], v[96:97], v[126:127], v[130:131]
	v_add_co_u32_e32 v112, vcc, s6, v62
	v_cvt_pk_bf16_f32 v96, v96, v97
	v_cvt_pk_bf16_f32 v97, v94, v95
	v_addc_co_u32_e32 v113, vcc, 0, v63, vcc
	v_pk_mul_f32 v[62:63], v[162:163], v[118:119] op_sel_hi:[1,0]
	v_pk_mul_f32 v[94:95], v[120:121], v[118:119] op_sel_hi:[1,0]
	v_pk_fma_f32 v[62:63], v[62:63], v[128:129], v[132:133]
	v_pk_fma_f32 v[94:95], v[94:95], v[126:127], v[130:131]
	global_store_dwordx2 v[104:105], v[150:151], off
	v_cvt_pk_bf16_f32 v94, v94, v95
	v_cvt_pk_bf16_f32 v95, v62, v63
	global_store_dwordx2 v[112:113], v[96:97], off
	global_store_dwordx2 v[112:113], v[94:95], off offset:2048
	global_load_dwordx4 v[94:97], v[134:135], off offset:1024 nt
	s_nop 0
	global_load_dwordx4 v[98:101], v[136:137], off offset:1024 nt
	v_pk_mul_f32 v[62:63], v[66:67], v[74:75] op_sel_hi:[1,0]
	s_waitcnt vmcnt(0) lgkmcnt(0)
	v_pk_fma_f32 v[64:65], v[64:65], v[94:95], v[98:99]
	v_pk_fma_f32 v[62:63], v[62:63], v[96:97], v[100:101]
	v_cvt_pk_bf16_f32 v64, v64, v65
	v_cvt_pk_bf16_f32 v65, v62, v63
	global_store_dwordx2 v[104:105], v[64:65], off offset:512
	v_pk_mul_f32 v[62:63], v[106:107], v[78:79] op_sel_hi:[1,0]
	v_pk_mul_f32 v[64:65], v[68:69], v[78:79] op_sel_hi:[1,0]
	v_pk_fma_f32 v[62:63], v[62:63], v[96:97], v[100:101]
	v_pk_fma_f32 v[64:65], v[64:65], v[94:95], v[98:99]
	s_nop 0
	v_cvt_pk_bf16_f32 v64, v64, v65
	v_cvt_pk_bf16_f32 v65, v62, v63
	global_store_dwordx2 v[104:105], v[64:65], off offset:2560
	v_pk_mul_f32 v[62:63], v[110:111], v[82:83] op_sel_hi:[1,0]
	v_pk_mul_f32 v[64:65], v[72:73], v[82:83] op_sel_hi:[1,0]
	v_pk_fma_f32 v[62:63], v[62:63], v[96:97], v[100:101]
	v_pk_fma_f32 v[64:65], v[64:65], v[94:95], v[98:99]
	s_nop 0
	v_cvt_pk_bf16_f32 v64, v64, v65
	v_cvt_pk_bf16_f32 v65, v62, v63
	global_store_dwordx2 v[108:109], v[64:65], off offset:512
	v_pk_mul_f32 v[62:63], v[142:143], v[86:87] op_sel_hi:[1,0]
	v_pk_mul_f32 v[64:65], v[76:77], v[86:87] op_sel_hi:[1,0]
	v_pk_fma_f32 v[62:63], v[62:63], v[96:97], v[100:101]
	v_pk_fma_f32 v[64:65], v[64:65], v[94:95], v[98:99]
	s_nop 0
	v_cvt_pk_bf16_f32 v64, v64, v65
	v_cvt_pk_bf16_f32 v65, v62, v63
	global_store_dwordx2 v[108:109], v[64:65], off offset:2560
	v_pk_mul_f32 v[62:63], v[144:145], v[90:91] op_sel_hi:[1,0]
	v_pk_mul_f32 v[64:65], v[80:81], v[90:91] op_sel_hi:[1,0]
	v_pk_fma_f32 v[62:63], v[62:63], v[96:97], v[100:101]
	v_pk_fma_f32 v[64:65], v[64:65], v[94:95], v[98:99]
	s_nop 0
	v_cvt_pk_bf16_f32 v64, v64, v65
	v_cvt_pk_bf16_f32 v65, v62, v63
	global_store_dwordx2 v[116:117], v[64:65], off offset:512
	v_pk_mul_f32 v[62:63], v[146:147], v[102:103] op_sel_hi:[1,0]
	v_pk_mul_f32 v[64:65], v[84:85], v[102:103] op_sel_hi:[1,0]
	v_pk_fma_f32 v[62:63], v[62:63], v[96:97], v[100:101]
	v_pk_fma_f32 v[64:65], v[64:65], v[94:95], v[98:99]
	s_nop 0
	v_cvt_pk_bf16_f32 v64, v64, v65
	v_cvt_pk_bf16_f32 v65, v62, v63
	global_store_dwordx2 v[116:117], v[64:65], off offset:2560
	v_pk_mul_f32 v[62:63], v[148:149], v[114:115] op_sel_hi:[1,0]
	v_pk_mul_f32 v[64:65], v[88:89], v[114:115] op_sel_hi:[1,0]
	v_pk_fma_f32 v[62:63], v[62:63], v[96:97], v[100:101]
	v_pk_fma_f32 v[64:65], v[64:65], v[94:95], v[98:99]
	s_nop 0
	v_cvt_pk_bf16_f32 v64, v64, v65
	v_cvt_pk_bf16_f32 v65, v62, v63
	global_store_dwordx2 v[112:113], v[64:65], off offset:512
	v_pk_mul_f32 v[62:63], v[122:123], v[118:119] op_sel_hi:[1,0]
	v_pk_mul_f32 v[64:65], v[92:93], v[118:119] op_sel_hi:[1,0]
	v_pk_fma_f32 v[62:63], v[62:63], v[96:97], v[100:101]
	v_pk_fma_f32 v[64:65], v[64:65], v[94:95], v[98:99]
	s_nop 0
	v_cvt_pk_bf16_f32 v64, v64, v65
	v_cvt_pk_bf16_f32 v65, v62, v63
	global_store_dwordx2 v[112:113], v[64:65], off offset:2560
	global_load_dwordx4 v[62:65], v[134:135], off offset:2048 nt
	s_nop 0
	global_load_dwordx4 v[66:69], v[136:137], off offset:2048 nt
	s_waitcnt vmcnt(0) lgkmcnt(0)
	v_pk_fma_f32 v[34:35], v[34:35], v[64:65], v[68:69]
	v_pk_fma_f32 v[32:33], v[32:33], v[62:63], v[66:67]
	s_nop 0
	v_cvt_pk_bf16_f32 v32, v32, v33
	v_cvt_pk_bf16_f32 v33, v34, v35
	global_store_dwordx2 v[104:105], v[32:33], off offset:1024
	v_pk_mul_f32 v[32:33], v[38:39], v[78:79] op_sel_hi:[1,0]
	v_pk_mul_f32 v[34:35], v[36:37], v[78:79] op_sel_hi:[1,0]
	v_pk_fma_f32 v[32:33], v[32:33], v[64:65], v[68:69]
	v_pk_fma_f32 v[34:35], v[34:35], v[62:63], v[66:67]
	s_nop 0
	v_cvt_pk_bf16_f32 v34, v34, v35
	v_cvt_pk_bf16_f32 v35, v32, v33
	global_store_dwordx2 v[104:105], v[34:35], off offset:3072
	v_pk_mul_f32 v[32:33], v[42:43], v[82:83] op_sel_hi:[1,0]
	v_pk_mul_f32 v[34:35], v[40:41], v[82:83] op_sel_hi:[1,0]
	v_pk_fma_f32 v[32:33], v[32:33], v[64:65], v[68:69]
	v_pk_fma_f32 v[34:35], v[34:35], v[62:63], v[66:67]
	s_nop 0
	v_cvt_pk_bf16_f32 v34, v34, v35
	v_cvt_pk_bf16_f32 v35, v32, v33
	global_store_dwordx2 v[108:109], v[34:35], off offset:1024
	v_pk_mul_f32 v[32:33], v[46:47], v[86:87] op_sel_hi:[1,0]
	v_pk_mul_f32 v[34:35], v[44:45], v[86:87] op_sel_hi:[1,0]
	v_pk_fma_f32 v[32:33], v[32:33], v[64:65], v[68:69]
	v_pk_fma_f32 v[34:35], v[34:35], v[62:63], v[66:67]
	s_nop 0
	v_cvt_pk_bf16_f32 v34, v34, v35
	v_cvt_pk_bf16_f32 v35, v32, v33
	global_store_dwordx2 v[108:109], v[34:35], off offset:3072
	v_pk_mul_f32 v[32:33], v[50:51], v[90:91] op_sel_hi:[1,0]
	v_pk_mul_f32 v[34:35], v[48:49], v[90:91] op_sel_hi:[1,0]
	v_pk_fma_f32 v[32:33], v[32:33], v[64:65], v[68:69]
	v_pk_fma_f32 v[34:35], v[34:35], v[62:63], v[66:67]
	s_nop 0
	v_cvt_pk_bf16_f32 v34, v34, v35
	v_cvt_pk_bf16_f32 v35, v32, v33
	global_store_dwordx2 v[116:117], v[34:35], off offset:1024
	v_pk_mul_f32 v[32:33], v[54:55], v[102:103] op_sel_hi:[1,0]
	v_pk_mul_f32 v[34:35], v[52:53], v[102:103] op_sel_hi:[1,0]
	v_pk_fma_f32 v[32:33], v[32:33], v[64:65], v[68:69]
	v_pk_fma_f32 v[34:35], v[34:35], v[62:63], v[66:67]
	s_nop 0
	v_cvt_pk_bf16_f32 v34, v34, v35
	v_cvt_pk_bf16_f32 v35, v32, v33
	global_store_dwordx2 v[116:117], v[34:35], off offset:3072
	v_pk_mul_f32 v[32:33], v[58:59], v[114:115] op_sel_hi:[1,0]
	v_pk_mul_f32 v[34:35], v[56:57], v[114:115] op_sel_hi:[1,0]
	v_pk_fma_f32 v[32:33], v[32:33], v[64:65], v[68:69]
	v_pk_fma_f32 v[34:35], v[34:35], v[62:63], v[66:67]
	s_nop 0
	v_cvt_pk_bf16_f32 v34, v34, v35
	v_cvt_pk_bf16_f32 v35, v32, v33
	global_store_dwordx2 v[112:113], v[34:35], off offset:1024
	v_pk_mul_f32 v[32:33], v[70:71], v[118:119] op_sel_hi:[1,0]
	v_pk_mul_f32 v[34:35], v[60:61], v[118:119] op_sel_hi:[1,0]
	v_pk_fma_f32 v[32:33], v[32:33], v[64:65], v[68:69]
	v_pk_fma_f32 v[34:35], v[34:35], v[62:63], v[66:67]
	s_nop 0
	v_cvt_pk_bf16_f32 v34, v34, v35
	v_cvt_pk_bf16_f32 v35, v32, v33
	global_store_dwordx2 v[112:113], v[34:35], off offset:3072
	global_load_dwordx4 v[32:35], v[134:135], off offset:3072 nt
	s_nop 0
	global_load_dwordx4 v[36:39], v[136:137], off offset:3072 nt
	s_waitcnt vmcnt(0) lgkmcnt(0)
	v_pk_fma_f32 v[2:3], v[2:3], v[34:35], v[38:39]
	v_pk_fma_f32 v[0:1], v[0:1], v[32:33], v[36:37]
	s_nop 0
	v_cvt_pk_bf16_f32 v0, v0, v1
	v_cvt_pk_bf16_f32 v1, v2, v3
	global_store_dwordx2 v[104:105], v[0:1], off offset:1536
	v_pk_mul_f32 v[0:1], v[6:7], v[78:79] op_sel_hi:[1,0]
	v_pk_mul_f32 v[2:3], v[4:5], v[78:79] op_sel_hi:[1,0]
	v_pk_fma_f32 v[0:1], v[0:1], v[34:35], v[38:39]
	v_pk_fma_f32 v[2:3], v[2:3], v[32:33], v[36:37]
	s_nop 0
	v_cvt_pk_bf16_f32 v2, v2, v3
	v_cvt_pk_bf16_f32 v3, v0, v1
	global_store_dwordx2 v[104:105], v[2:3], off offset:3584
	v_pk_mul_f32 v[0:1], v[10:11], v[82:83] op_sel_hi:[1,0]
	v_pk_mul_f32 v[2:3], v[8:9], v[82:83] op_sel_hi:[1,0]
	v_pk_fma_f32 v[0:1], v[0:1], v[34:35], v[38:39]
	v_pk_fma_f32 v[2:3], v[2:3], v[32:33], v[36:37]
	s_nop 0
	v_cvt_pk_bf16_f32 v2, v2, v3
	v_cvt_pk_bf16_f32 v3, v0, v1
	global_store_dwordx2 v[108:109], v[2:3], off offset:1536
	v_pk_mul_f32 v[0:1], v[14:15], v[86:87] op_sel_hi:[1,0]
	v_pk_mul_f32 v[2:3], v[12:13], v[86:87] op_sel_hi:[1,0]
	v_pk_fma_f32 v[0:1], v[0:1], v[34:35], v[38:39]
	v_pk_fma_f32 v[2:3], v[2:3], v[32:33], v[36:37]
	s_nop 0
	v_cvt_pk_bf16_f32 v2, v2, v3
	v_cvt_pk_bf16_f32 v3, v0, v1
	global_store_dwordx2 v[108:109], v[2:3], off offset:3584
	v_pk_mul_f32 v[0:1], v[18:19], v[90:91] op_sel_hi:[1,0]
	v_pk_mul_f32 v[2:3], v[16:17], v[90:91] op_sel_hi:[1,0]
	v_pk_fma_f32 v[0:1], v[0:1], v[34:35], v[38:39]
	v_pk_fma_f32 v[2:3], v[2:3], v[32:33], v[36:37]
	s_nop 0
	v_cvt_pk_bf16_f32 v2, v2, v3
	v_cvt_pk_bf16_f32 v3, v0, v1
	global_store_dwordx2 v[116:117], v[2:3], off offset:1536
	v_pk_mul_f32 v[0:1], v[22:23], v[102:103] op_sel_hi:[1,0]
	v_pk_mul_f32 v[2:3], v[20:21], v[102:103] op_sel_hi:[1,0]
	v_pk_fma_f32 v[0:1], v[0:1], v[34:35], v[38:39]
	v_pk_fma_f32 v[2:3], v[2:3], v[32:33], v[36:37]
	s_nop 0
	v_cvt_pk_bf16_f32 v2, v2, v3
	v_cvt_pk_bf16_f32 v3, v0, v1
	global_store_dwordx2 v[116:117], v[2:3], off offset:3584
	v_pk_mul_f32 v[0:1], v[26:27], v[114:115] op_sel_hi:[1,0]
	v_pk_mul_f32 v[2:3], v[24:25], v[114:115] op_sel_hi:[1,0]
	v_pk_fma_f32 v[0:1], v[0:1], v[34:35], v[38:39]
	v_pk_fma_f32 v[2:3], v[2:3], v[32:33], v[36:37]
	s_nop 0
	v_cvt_pk_bf16_f32 v2, v2, v3
	v_cvt_pk_bf16_f32 v3, v0, v1
	global_store_dwordx2 v[112:113], v[2:3], off offset:1536
	v_pk_mul_f32 v[0:1], v[30:31], v[118:119] op_sel_hi:[1,0]
	v_pk_mul_f32 v[2:3], v[28:29], v[118:119] op_sel_hi:[1,0]
	v_pk_fma_f32 v[0:1], v[0:1], v[34:35], v[38:39]
	v_pk_fma_f32 v[2:3], v[2:3], v[32:33], v[36:37]
	s_nop 0
	v_cvt_pk_bf16_f32 v2, v2, v3
	v_cvt_pk_bf16_f32 v3, v0, v1
	global_store_dwordx2 v[112:113], v[2:3], off offset:3584
	s_cbranch_scc0 .LBB0_1239
.LBB0_1223:
	v_add_co_u32_e32 v0, vcc, 0xffff8400, v140
	s_add_u32 s13, s8, s14
	s_nop 0
	v_addc_co_u32_e32 v1, vcc, -1, v141, vcc
	v_add_co_u32_e32 v2, vcc, 0xffff8800, v140
	s_addc_u32 s11, s9, s15
	s_nop 0
	v_addc_co_u32_e32 v3, vcc, -1, v141, vcc
	global_load_dwordx4 v[104:107], v[0:1], off nt
	s_waitcnt vmcnt(0)
	global_load_dwordx4 v[64:67], v[2:3], off nt
	v_add_co_u32_e32 v0, vcc, 0xffff8c00, v140
	s_waitcnt lgkmcnt(0)
	v_add_f32_e32 v128, v104, v105
	v_addc_co_u32_e32 v1, vcc, -1, v141, vcc
	v_add_co_u32_e32 v2, vcc, 0xffff9000, v140
	v_add_f32_e32 v129, v106, v107
	s_nop 0
	v_addc_co_u32_e32 v3, vcc, -1, v141, vcc
	v_add_co_u32_e32 v4, vcc, 0xffff9400, v140
	global_load_dwordx4 v[32:35], v[0:1], off nt
	s_nop 0
	global_load_dwordx4 v[0:3], v[2:3], off nt
	v_addc_co_u32_e32 v5, vcc, -1, v141, vcc
	v_add_co_u32_e32 v6, vcc, 0xffff9800, v140
	v_add_f32_e32 v128, v128, v129
	s_nop 0
	v_addc_co_u32_e32 v7, vcc, -1, v141, vcc
	global_load_dwordx4 v[96:99], v[4:5], off nt
	global_load_dwordx4 v[68:71], v[6:7], off nt
	v_add_co_u32_e32 v4, vcc, 0xffff9c00, v140
	s_waitcnt vmcnt(0)
	v_add_f32_e32 v129, v64, v65
	v_addc_co_u32_e32 v5, vcc, -1, v141, vcc
	v_add_co_u32_e32 v6, vcc, 0xffffa000, v140
	v_add_f32_e32 v130, v66, v67
	s_nop 0
	v_addc_co_u32_e32 v7, vcc, -1, v141, vcc
	v_add_co_u32_e32 v8, vcc, 0xffffa400, v140
	global_load_dwordx4 v[36:39], v[4:5], off nt
	s_nop 0
	global_load_dwordx4 v[4:7], v[6:7], off nt
	v_addc_co_u32_e32 v9, vcc, -1, v141, vcc
	v_add_co_u32_e32 v10, vcc, 0xffffa800, v140
	v_add_f32_e32 v128, 0, v128
	s_nop 0
	v_addc_co_u32_e32 v11, vcc, -1, v141, vcc
	global_load_dwordx4 v[108:111], v[8:9], off nt
	global_load_dwordx4 v[72:75], v[10:11], off nt
	v_add_co_u32_e32 v8, vcc, 0xffffac00, v140
	v_add_f32_e32 v129, v129, v130
	s_nop 0
	v_addc_co_u32_e32 v9, vcc, -1, v141, vcc
	v_add_co_u32_e32 v10, vcc, 0xffffb000, v140
	v_add_f32_e32 v128, v128, v129
	s_nop 0
	v_addc_co_u32_e32 v11, vcc, -1, v141, vcc
	v_add_co_u32_e32 v12, vcc, 0xffffb400, v140
	global_load_dwordx4 v[40:43], v[8:9], off nt
	s_nop 0
	global_load_dwordx4 v[8:11], v[10:11], off nt
	v_addc_co_u32_e32 v13, vcc, -1, v141, vcc
	v_add_co_u32_e32 v14, vcc, 0xffffb800, v140
	s_waitcnt lgkmcnt(0)
	v_add_f32_e32 v129, v32, v33
	v_addc_co_u32_e32 v15, vcc, -1, v141, vcc
	global_load_dwordx4 v[100:103], v[12:13], off nt
	global_load_dwordx4 v[76:79], v[14:15], off nt
	v_add_co_u32_e32 v12, vcc, 0xffffbc00, v140
	v_add_f32_e32 v130, v34, v35
	s_nop 0
	v_addc_co_u32_e32 v13, vcc, -1, v141, vcc
	v_add_co_u32_e32 v14, vcc, 0xffffc000, v140
	v_add_f32_e32 v129, v129, v130
	s_nop 0
	v_addc_co_u32_e32 v15, vcc, -1, v141, vcc
	v_add_co_u32_e32 v16, vcc, 0xffffc400, v140
	global_load_dwordx4 v[44:47], v[12:13], off nt
	s_nop 0
	global_load_dwordx4 v[12:15], v[14:15], off nt
	v_addc_co_u32_e32 v17, vcc, -1, v141, vcc
	v_add_co_u32_e32 v18, vcc, 0xffffc800, v140
	v_add_f32_e32 v128, v128, v129
	s_nop 0
	v_addc_co_u32_e32 v19, vcc, -1, v141, vcc
	global_load_dwordx4 v[116:119], v[16:17], off nt
	global_load_dwordx4 v[80:83], v[18:19], off nt
	v_add_co_u32_e32 v16, vcc, 0xffffcc00, v140
	v_add_f32_e32 v129, v0, v1
	s_nop 0
	v_addc_co_u32_e32 v17, vcc, -1, v141, vcc
	v_add_co_u32_e32 v18, vcc, 0xffffd000, v140
	v_add_f32_e32 v130, v2, v3
	s_nop 0
	v_addc_co_u32_e32 v19, vcc, -1, v141, vcc
	v_add_co_u32_e32 v20, vcc, 0xffffd400, v140
	global_load_dwordx4 v[48:51], v[16:17], off nt
	s_nop 0
	global_load_dwordx4 v[16:19], v[18:19], off nt
	v_addc_co_u32_e32 v21, vcc, -1, v141, vcc
	v_add_co_u32_e32 v22, vcc, 0xffffd800, v140
	v_add_f32_e32 v129, v129, v130
	s_nop 0
	v_addc_co_u32_e32 v23, vcc, -1, v141, vcc
	global_load_dwordx4 v[112:115], v[20:21], off nt
	global_load_dwordx4 v[84:87], v[22:23], off nt
	v_add_co_u32_e32 v20, vcc, 0xffffdc00, v140
	v_add_f32_e32 v128, v128, v129
	s_nop 0
	v_addc_co_u32_e32 v21, vcc, -1, v141, vcc
	v_add_co_u32_e32 v22, vcc, 0xffffe000, v140
	v_add_f32_e32 v129, v96, v97
	s_nop 0
	v_addc_co_u32_e32 v23, vcc, -1, v141, vcc
	v_add_co_u32_e32 v24, vcc, 0xffffe400, v140
	global_load_dwordx4 v[52:55], v[20:21], off nt
	s_nop 0
	global_load_dwordx4 v[20:23], v[22:23], off nt
	v_addc_co_u32_e32 v25, vcc, -1, v141, vcc
	v_add_co_u32_e32 v26, vcc, s46, v140
	v_add_f32_e32 v130, v98, v99
	s_nop 0
	v_addc_co_u32_e32 v27, vcc, -1, v141, vcc
	global_load_dwordx4 v[124:127], v[24:25], off nt
	global_load_dwordx4 v[88:91], v[26:27], off nt
	v_add_co_u32_e32 v24, vcc, 0xffffec00, v140
	v_add_f32_e32 v129, v129, v130
	s_nop 0
	v_addc_co_u32_e32 v25, vcc, -1, v141, vcc
	v_add_co_u32_e32 v26, vcc, 0xfffff000, v140
	v_add_f32_e32 v130, v68, v69
	s_nop 0
	v_addc_co_u32_e32 v27, vcc, -1, v141, vcc
	global_load_dwordx4 v[56:59], v[24:25], off nt
	s_nop 0
	global_load_dwordx4 v[24:27], v[26:27], off nt
	v_add_co_u32_e32 v28, vcc, 0xfffff400, v140
	v_add_f32_e32 v131, v70, v71
	s_nop 0
	v_addc_co_u32_e32 v29, vcc, -1, v141, vcc
	v_add_co_u32_e32 v30, vcc, 0xfffff800, v140
	v_add_f32_e32 v129, 0, v129
	s_nop 0
	v_addc_co_u32_e32 v31, vcc, -1, v141, vcc
	global_load_dwordx4 v[120:123], v[28:29], off nt
	global_load_dwordx4 v[92:95], v[30:31], off nt
	v_add_co_u32_e32 v28, vcc, s76, v140
	v_add_f32_e32 v130, v130, v131
	s_nop 0
	v_addc_co_u32_e32 v29, vcc, -1, v141, vcc
	global_load_dwordx4 v[60:63], v[28:29], off nt
	s_nop 0
	global_load_dwordx4 v[28:31], v[140:141], off nt
	v_add_f32_e32 v129, v129, v130
	s_waitcnt vmcnt(0)
	v_add_f32_e32 v130, v36, v37
	v_add_f32_e32 v131, v38, v39
	v_add_f32_e32 v130, v130, v131
	v_add_f32_e32 v129, v129, v130
	v_add_f32_e32 v130, v4, v5
	v_add_f32_e32 v131, v6, v7
	v_add_f32_e32 v130, v130, v131
	v_add_f32_e32 v129, v129, v130
	v_add_f32_e32 v130, v108, v109
	v_add_f32_e32 v131, v110, v111
	v_add_f32_e32 v130, v130, v131
	v_add_f32_e32 v131, v72, v73
	v_add_f32_e32 v132, v74, v75
	v_add_f32_e32 v130, 0, v130
	v_add_f32_e32 v131, v131, v132
	v_add_f32_e32 v130, v130, v131
	v_add_f32_e32 v131, v40, v41
	v_add_f32_e32 v132, v42, v43
	v_add_f32_e32 v131, v131, v132
	v_add_f32_e32 v130, v130, v131
	v_add_f32_e32 v131, v8, v9
	v_add_f32_e32 v132, v10, v11
	v_add_f32_e32 v131, v131, v132
	v_add_f32_e32 v130, v130, v131
	s_waitcnt lgkmcnt(0)
	v_add_f32_e32 v131, v100, v101
	v_add_f32_e32 v132, v102, v103
	v_add_f32_e32 v131, v131, v132
	v_add_f32_e32 v132, v76, v77
	v_add_f32_e32 v133, v78, v79
	v_add_f32_e32 v131, 0, v131
	v_add_f32_e32 v132, v132, v133
	v_add_f32_e32 v131, v131, v132
	v_add_f32_e32 v132, v44, v45
	v_add_f32_e32 v133, v46, v47
	v_add_f32_e32 v132, v132, v133
	v_add_f32_e32 v131, v131, v132
	v_add_f32_e32 v132, v12, v13
	v_add_f32_e32 v133, v14, v15
	v_add_f32_e32 v132, v132, v133
	v_add_f32_e32 v131, v131, v132
	v_add_f32_e32 v132, v116, v117
	v_add_f32_e32 v133, v118, v119
	v_add_f32_e32 v132, v132, v133
	v_add_f32_e32 v133, v80, v81
	v_add_f32_e32 v142, v82, v83
	v_add_f32_e32 v132, 0, v132
	v_add_f32_e32 v133, v133, v142
	v_add_f32_e32 v132, v132, v133
	v_add_f32_e32 v133, v48, v49
	v_add_f32_e32 v142, v50, v51
	v_add_f32_e32 v133, v133, v142
	v_add_f32_e32 v132, v132, v133
	v_add_f32_e32 v133, v16, v17
	v_add_f32_e32 v142, v18, v19
	v_add_f32_e32 v133, v133, v142
	v_add_f32_e32 v132, v132, v133
	v_add_f32_e32 v133, v112, v113
	v_add_f32_e32 v142, v114, v115
	v_add_f32_e32 v133, v133, v142
	v_add_f32_e32 v142, v84, v85
	v_add_f32_e32 v143, v86, v87
	v_add_f32_e32 v133, 0, v133
	v_add_f32_e32 v142, v142, v143
	v_add_f32_e32 v133, v133, v142
	v_add_f32_e32 v142, v52, v53
	v_add_f32_e32 v143, v54, v55
	v_add_f32_e32 v142, v142, v143
	v_add_f32_e32 v133, v133, v142
	v_add_f32_e32 v142, v20, v21
	v_add_f32_e32 v143, v22, v23
	v_add_f32_e32 v142, v142, v143
	v_add_f32_e32 v142, v133, v142
	v_add_f32_e32 v133, v124, v125
	v_add_f32_e32 v143, v126, v127
	v_add_f32_e32 v133, v133, v143
	v_add_f32_e32 v143, v88, v89
	v_add_f32_e32 v144, v90, v91
	v_add_f32_e32 v133, 0, v133
	v_add_f32_e32 v143, v143, v144
	v_add_f32_e32 v133, v133, v143
	v_add_f32_e32 v143, v56, v57
	v_add_f32_e32 v144, v58, v59
	v_add_f32_e32 v143, v143, v144
	v_add_f32_e32 v133, v133, v143
	v_add_f32_e32 v143, v24, v25
	v_add_f32_e32 v144, v26, v27
	v_add_f32_e32 v143, v143, v144
	v_add_f32_e32 v143, v133, v143
	v_add_f32_e32 v133, v120, v121
	v_add_f32_e32 v144, v122, v123
	v_add_f32_e32 v133, v133, v144
	ds_swizzle_b32 v144, v128 offset:swizzle(SWAP,1)
	v_add_f32_e32 v145, v92, v93
	v_add_f32_e32 v146, v94, v95
	v_add_f32_e32 v133, 0, v133
	v_add_f32_e32 v145, v145, v146
	s_waitcnt lgkmcnt(0)
	v_add_f32_e32 v128, v128, v144
	v_add_f32_e32 v133, v133, v145
	ds_swizzle_b32 v145, v129 offset:swizzle(SWAP,1)
	ds_swizzle_b32 v144, v128 offset:swizzle(SWAP,2)
	v_add_f32_e32 v146, v60, v61
	v_add_f32_e32 v147, v62, v63
	v_add_f32_e32 v146, v146, v147
	s_waitcnt lgkmcnt(1)
	v_add_f32_e32 v129, v129, v145
	s_waitcnt lgkmcnt(0)
	v_add_f32_e32 v128, v128, v144
	ds_swizzle_b32 v145, v129 offset:swizzle(SWAP,2)
	ds_swizzle_b32 v144, v128 offset:swizzle(SWAP,4)
	v_add_f32_e32 v133, v133, v146
	v_add_f32_e32 v146, v28, v29
	v_add_f32_e32 v147, v30, v31
	s_waitcnt lgkmcnt(1)
	v_add_f32_e32 v129, v129, v145
	s_waitcnt lgkmcnt(0)
	v_add_f32_e32 v128, v128, v144
	ds_swizzle_b32 v145, v129 offset:swizzle(SWAP,4)
	ds_swizzle_b32 v144, v128 offset:swizzle(SWAP,8)
	v_add_f32_e32 v146, v146, v147
	v_add_f32_e32 v146, v133, v146
	s_waitcnt lgkmcnt(1)
	v_add_f32_e32 v129, v129, v145
	s_waitcnt lgkmcnt(0)
	v_add_f32_e32 v128, v128, v144
	ds_swizzle_b32 v145, v129 offset:swizzle(SWAP,8)
	ds_swizzle_b32 v144, v128 offset:swizzle(SWAP,16)
	s_waitcnt lgkmcnt(1)
	v_add_f32_e32 v129, v129, v145
	s_waitcnt lgkmcnt(0)
	v_add_f32_e32 v128, v128, v144
	ds_swizzle_b32 v144, v129 offset:swizzle(SWAP,16)
	ds_swizzle_b32 v145, v130 offset:swizzle(SWAP,1)
	v_mov_b32_e32 v133, v128
	s_nop 1
	v_permlane32_swap_b32_e32 v128, v133
	v_add_f32_e32 v165, v128, v133
	s_waitcnt lgkmcnt(1)
	v_add_f32_e32 v128, v129, v144
	ds_swizzle_b32 v144, v131 offset:swizzle(SWAP,1)
	s_waitcnt lgkmcnt(1)
	v_add_f32_e32 v129, v130, v145
	ds_swizzle_b32 v130, v129 offset:swizzle(SWAP,2)
	v_mov_b32_e32 v133, v128
	s_nop 1
	v_permlane32_swap_b32_e32 v128, v133
	s_waitcnt lgkmcnt(1)
	v_add_f32_e32 v131, v131, v144
	ds_swizzle_b32 v144, v131 offset:swizzle(SWAP,2)
	v_add_f32_e32 v164, v128, v133
	ds_swizzle_b32 v128, v132 offset:swizzle(SWAP,1)
	s_waitcnt lgkmcnt(2)
	v_add_f32_e32 v129, v129, v130
	ds_swizzle_b32 v130, v129 offset:swizzle(SWAP,4)
	s_waitcnt lgkmcnt(2)
	v_add_f32_e32 v131, v131, v144
	ds_swizzle_b32 v133, v131 offset:swizzle(SWAP,4)
	s_waitcnt lgkmcnt(2)
	v_add_f32_e32 v128, v132, v128
	ds_swizzle_b32 v132, v128 offset:swizzle(SWAP,2)
	s_waitcnt lgkmcnt(2)
	v_add_f32_e32 v129, v129, v130
	ds_swizzle_b32 v130, v129 offset:swizzle(SWAP,8)
	s_waitcnt lgkmcnt(2)
	v_add_f32_e32 v131, v131, v133
	ds_swizzle_b32 v133, v131 offset:swizzle(SWAP,8)
	s_waitcnt lgkmcnt(2)
	v_add_f32_e32 v128, v128, v132
	ds_swizzle_b32 v132, v128 offset:swizzle(SWAP,4)
	s_waitcnt lgkmcnt(2)
	v_add_f32_e32 v129, v129, v130
	ds_swizzle_b32 v130, v129 offset:swizzle(SWAP,16)
	s_waitcnt lgkmcnt(2)
	v_add_f32_e32 v131, v131, v133
	ds_swizzle_b32 v144, v131 offset:swizzle(SWAP,16)
	s_waitcnt lgkmcnt(2)
	v_add_f32_e32 v128, v128, v132
	ds_swizzle_b32 v132, v128 offset:swizzle(SWAP,8)
	s_waitcnt lgkmcnt(2)
	v_add_f32_e32 v129, v129, v130
	v_mov_b32_e32 v130, v129
	s_nop 1
	v_permlane32_swap_b32_e32 v129, v130
	v_add_f32_e32 v133, v129, v130
	s_waitcnt lgkmcnt(1)
	v_add_f32_e32 v129, v131, v144
	ds_swizzle_b32 v144, v142 offset:swizzle(SWAP,1)
	s_waitcnt lgkmcnt(1)
	v_add_f32_e32 v128, v128, v132
	ds_swizzle_b32 v131, v128 offset:swizzle(SWAP,16)
	v_mov_b32_e32 v130, v129
	s_nop 1
	v_permlane32_swap_b32_e32 v129, v130
	v_add_f32_e32 v132, v129, v130
	s_waitcnt lgkmcnt(1)
	v_add_f32_e32 v129, v142, v144
	ds_swizzle_b32 v142, v143 offset:swizzle(SWAP,1)
	s_waitcnt lgkmcnt(1)
	v_add_f32_e32 v128, v128, v131
	ds_swizzle_b32 v130, v129 offset:swizzle(SWAP,2)
	v_mov_b32_e32 v131, v128
	s_nop 1
	v_permlane32_swap_b32_e32 v128, v131
	s_waitcnt lgkmcnt(1)
	v_add_f32_e32 v142, v143, v142
	v_add_f32_e32 v131, v128, v131
	ds_swizzle_b32 v128, v146 offset:swizzle(SWAP,1)
	ds_swizzle_b32 v143, v142 offset:swizzle(SWAP,2)
	s_waitcnt lgkmcnt(2)
	v_add_f32_e32 v129, v129, v130
	ds_swizzle_b32 v130, v129 offset:swizzle(SWAP,4)
	v_fmamk_f32 v151, v165, 0xba800000, v107
	s_waitcnt lgkmcnt(2)
	v_add_f32_e32 v128, v146, v128
	s_waitcnt lgkmcnt(1)
	v_add_f32_e32 v142, v142, v143
	ds_swizzle_b32 v144, v128 offset:swizzle(SWAP,2)
	ds_swizzle_b32 v143, v142 offset:swizzle(SWAP,4)
	s_waitcnt lgkmcnt(2)
	v_add_f32_e32 v129, v129, v130
	ds_swizzle_b32 v130, v129 offset:swizzle(SWAP,8)
	v_fmamk_f32 v105, v165, 0xba800000, v105
	s_waitcnt lgkmcnt(2)
	v_add_f32_e32 v128, v128, v144
	s_waitcnt lgkmcnt(1)
	v_add_f32_e32 v142, v142, v143
	ds_swizzle_b32 v144, v128 offset:swizzle(SWAP,4)
	ds_swizzle_b32 v143, v142 offset:swizzle(SWAP,8)
	s_waitcnt lgkmcnt(2)
	v_add_f32_e32 v129, v129, v130
	ds_swizzle_b32 v130, v129 offset:swizzle(SWAP,16)
	v_fmamk_f32 v150, v165, 0xba800000, v106
	s_waitcnt lgkmcnt(2)
	v_add_f32_e32 v128, v128, v144
	s_waitcnt lgkmcnt(1)
	v_add_f32_e32 v142, v142, v143
	ds_swizzle_b32 v144, v128 offset:swizzle(SWAP,8)
	ds_swizzle_b32 v143, v142 offset:swizzle(SWAP,16)
	s_waitcnt lgkmcnt(2)
	v_add_f32_e32 v129, v129, v130
	v_mov_b32_e32 v130, v129
	s_nop 1
	v_permlane32_swap_b32_e32 v129, v130
	s_waitcnt lgkmcnt(1)
	v_add_f32_e32 v128, v128, v144
	v_add_f32_e32 v130, v129, v130
	s_waitcnt lgkmcnt(0)
	v_add_f32_e32 v129, v142, v143
	ds_swizzle_b32 v142, v128 offset:swizzle(SWAP,16)
	v_fmac_f32_e32 v104, 0xba800000, v165
	v_mul_f32_e32 v106, v105, v105
	v_mul_f32_e32 v107, v151, v151
	v_fmac_f32_e32 v106, v104, v104
	s_waitcnt lgkmcnt(0)
	v_add_f32_e32 v128, v128, v142
	v_mov_b32_e32 v142, v128
	s_nop 1
	v_permlane32_swap_b32_e32 v128, v142
	v_fmac_f32_e32 v107, v150, v150
	v_fmamk_f32 v67, v165, 0xba800000, v67
	v_fmamk_f32 v65, v165, 0xba800000, v65
	v_add_f32_e32 v128, v128, v142
	v_add_f32_e32 v106, v106, v107
	v_fmamk_f32 v66, v165, 0xba800000, v66
	v_fmac_f32_e32 v64, 0xba800000, v165
	v_mul_f32_e32 v107, v65, v65
	v_mul_f32_e32 v142, v67, v67
	v_fmac_f32_e32 v107, v64, v64
	v_fmac_f32_e32 v142, v66, v66
	v_add_f32_e32 v107, v107, v142
	v_fmamk_f32 v35, v165, 0xba800000, v35
	v_fmamk_f32 v33, v165, 0xba800000, v33
	v_add_f32_e32 v106, v106, v107
	v_fmamk_f32 v34, v165, 0xba800000, v34
	v_fmac_f32_e32 v32, 0xba800000, v165
	v_mul_f32_e32 v107, v33, v33
	v_mul_f32_e32 v142, v35, v35
	v_fmac_f32_e32 v107, v32, v32
	v_fmac_f32_e32 v142, v34, v34
	v_add_f32_e32 v107, v107, v142
	v_fmamk_f32 v3, v165, 0xba800000, v3
	v_fmamk_f32 v1, v165, 0xba800000, v1
	v_add_f32_e32 v106, v107, v106
	v_fmamk_f32 v2, v165, 0xba800000, v2
	v_fmac_f32_e32 v0, 0xba800000, v165
	v_mul_f32_e32 v107, v1, v1
	v_mul_f32_e32 v142, v3, v3
	v_fmac_f32_e32 v107, v0, v0
	v_fmac_f32_e32 v142, v2, v2
	v_add_f32_e32 v107, v107, v142
	v_fmamk_f32 v99, v164, 0xba800000, v99
	v_fmamk_f32 v97, v164, 0xba800000, v97
	v_add_f32_e32 v166, v107, v106
	v_fmamk_f32 v98, v164, 0xba800000, v98
	v_fmac_f32_e32 v96, 0xba800000, v164
	v_mul_f32_e32 v106, v97, v97
	v_mul_f32_e32 v107, v99, v99
	v_fmac_f32_e32 v106, v96, v96
	v_fmac_f32_e32 v107, v98, v98
	v_add_f32_e32 v142, v106, v107
	v_fmamk_f32 v107, v164, 0xba800000, v71
	v_fmamk_f32 v69, v164, 0xba800000, v69
	v_fmamk_f32 v106, v164, 0xba800000, v70
	v_fmac_f32_e32 v68, 0xba800000, v164
	v_mul_f32_e32 v70, v69, v69
	v_mul_f32_e32 v71, v107, v107
	v_fmac_f32_e32 v70, v68, v68
	v_fmac_f32_e32 v71, v106, v106
	v_add_f32_e32 v70, v70, v71
	v_fmamk_f32 v39, v164, 0xba800000, v39
	v_fmamk_f32 v37, v164, 0xba800000, v37
	v_add_f32_e32 v70, v142, v70
	v_fmamk_f32 v38, v164, 0xba800000, v38
	v_fmac_f32_e32 v36, 0xba800000, v164
	v_mul_f32_e32 v71, v37, v37
	v_mul_f32_e32 v142, v39, v39
	v_fmac_f32_e32 v71, v36, v36
	v_fmac_f32_e32 v142, v38, v38
	v_add_f32_e32 v71, v71, v142
	v_fmamk_f32 v7, v164, 0xba800000, v7
	v_fmamk_f32 v5, v164, 0xba800000, v5
	v_add_f32_e32 v70, v71, v70
	v_fmamk_f32 v6, v164, 0xba800000, v6
	v_fmac_f32_e32 v4, 0xba800000, v164
	v_mul_f32_e32 v71, v5, v5
	v_mul_f32_e32 v142, v7, v7
	v_fmac_f32_e32 v71, v4, v4
	v_fmac_f32_e32 v142, v6, v6
	v_add_f32_e32 v71, v71, v142
	v_fmamk_f32 v153, v133, 0xba800000, v111
	v_fmamk_f32 v109, v133, 0xba800000, v109
	v_add_f32_e32 v167, v71, v70
	v_fmamk_f32 v152, v133, 0xba800000, v110
	v_fmac_f32_e32 v108, 0xba800000, v133
	v_mul_f32_e32 v70, v109, v109
	v_mul_f32_e32 v71, v153, v153
	v_fmac_f32_e32 v70, v108, v108
	v_fmac_f32_e32 v71, v152, v152
	v_fmamk_f32 v111, v133, 0xba800000, v75
	v_fmamk_f32 v73, v133, 0xba800000, v73
	v_add_f32_e32 v70, v70, v71
	v_fmamk_f32 v110, v133, 0xba800000, v74
	v_fmac_f32_e32 v72, 0xba800000, v133
	v_mul_f32_e32 v71, v73, v73
	v_mul_f32_e32 v74, v111, v111
	v_fmac_f32_e32 v71, v72, v72
	v_fmac_f32_e32 v74, v110, v110
	v_add_f32_e32 v71, v71, v74
	v_fmamk_f32 v43, v133, 0xba800000, v43
	v_fmamk_f32 v41, v133, 0xba800000, v41
	v_add_f32_e32 v70, v70, v71
	v_fmamk_f32 v42, v133, 0xba800000, v42
	v_fmac_f32_e32 v40, 0xba800000, v133
	v_mul_f32_e32 v71, v41, v41
	v_mul_f32_e32 v74, v43, v43
	v_fmac_f32_e32 v71, v40, v40
	v_fmac_f32_e32 v74, v42, v42
	v_add_f32_e32 v71, v71, v74
	v_fmamk_f32 v11, v133, 0xba800000, v11
	v_fmamk_f32 v9, v133, 0xba800000, v9
	v_add_f32_e32 v70, v71, v70
	v_fmamk_f32 v10, v133, 0xba800000, v10
	v_fmac_f32_e32 v8, 0xba800000, v133
	v_mul_f32_e32 v71, v9, v9
	v_mul_f32_e32 v74, v11, v11
	v_fmac_f32_e32 v71, v8, v8
	v_fmac_f32_e32 v74, v10, v10
	v_mov_b32_e32 v143, v129
	v_add_f32_e32 v71, v71, v74
	v_fmamk_f32 v155, v132, 0xba800000, v103
	v_fmamk_f32 v101, v132, 0xba800000, v101
	v_permlane32_swap_b32_e32 v129, v143
	v_add_f32_e32 v74, v71, v70
	v_fmamk_f32 v154, v132, 0xba800000, v102
	v_fmac_f32_e32 v100, 0xba800000, v132
	v_mul_f32_e32 v70, v101, v101
	v_mul_f32_e32 v71, v155, v155
	v_add_f32_e32 v129, v129, v143
	v_fmac_f32_e32 v70, v100, v100
	v_fmac_f32_e32 v71, v154, v154
	v_fmamk_f32 v143, v132, 0xba800000, v79
	v_fmamk_f32 v77, v132, 0xba800000, v77
	v_add_f32_e32 v70, v70, v71
	v_fmamk_f32 v142, v132, 0xba800000, v78
	v_fmac_f32_e32 v76, 0xba800000, v132
	v_mul_f32_e32 v71, v77, v77
	v_mul_f32_e32 v75, v143, v143
	v_fmac_f32_e32 v71, v76, v76
	v_fmac_f32_e32 v75, v142, v142
	v_add_f32_e32 v71, v71, v75
	v_fmamk_f32 v47, v132, 0xba800000, v47
	v_fmamk_f32 v45, v132, 0xba800000, v45
	v_add_f32_e32 v70, v70, v71
	v_fmamk_f32 v46, v132, 0xba800000, v46
	v_fmac_f32_e32 v44, 0xba800000, v132
	v_mul_f32_e32 v71, v45, v45
	v_mul_f32_e32 v75, v47, v47
	v_fmac_f32_e32 v71, v44, v44
	v_fmac_f32_e32 v75, v46, v46
	v_add_f32_e32 v71, v71, v75
	v_fmamk_f32 v15, v132, 0xba800000, v15
	v_fmamk_f32 v13, v132, 0xba800000, v13
	v_add_f32_e32 v70, v71, v70
	v_fmamk_f32 v14, v132, 0xba800000, v14
	v_fmac_f32_e32 v12, 0xba800000, v132
	v_mul_f32_e32 v71, v13, v13
	v_mul_f32_e32 v75, v15, v15
	v_fmac_f32_e32 v71, v12, v12
	v_fmac_f32_e32 v75, v14, v14
	v_add_f32_e32 v71, v71, v75
	v_fmamk_f32 v157, v131, 0xba800000, v119
	v_fmamk_f32 v117, v131, 0xba800000, v117
	v_add_f32_e32 v75, v71, v70
	v_fmamk_f32 v156, v131, 0xba800000, v118
	v_fmac_f32_e32 v116, 0xba800000, v131
	v_mul_f32_e32 v70, v117, v117
	v_mul_f32_e32 v71, v157, v157
	v_fmac_f32_e32 v70, v116, v116
	v_fmac_f32_e32 v71, v156, v156
	v_fmamk_f32 v145, v131, 0xba800000, v83
	v_fmamk_f32 v81, v131, 0xba800000, v81
	v_add_f32_e32 v70, v70, v71
	v_fmamk_f32 v144, v131, 0xba800000, v82
	v_fmac_f32_e32 v80, 0xba800000, v131
	v_mul_f32_e32 v71, v81, v81
	v_mul_f32_e32 v78, v145, v145
	v_fmac_f32_e32 v71, v80, v80
	v_fmac_f32_e32 v78, v144, v144
	v_add_f32_e32 v71, v71, v78
	v_fmamk_f32 v51, v131, 0xba800000, v51
	v_fmamk_f32 v49, v131, 0xba800000, v49
	v_add_f32_e32 v70, v70, v71
	v_fmamk_f32 v50, v131, 0xba800000, v50
	v_fmac_f32_e32 v48, 0xba800000, v131
	v_mul_f32_e32 v71, v49, v49
	v_mul_f32_e32 v78, v51, v51
	v_fmac_f32_e32 v71, v48, v48
	v_fmac_f32_e32 v78, v50, v50
	v_add_f32_e32 v71, v71, v78
	v_fmamk_f32 v19, v131, 0xba800000, v19
	v_fmamk_f32 v17, v131, 0xba800000, v17
	v_add_f32_e32 v70, v71, v70
	v_fmamk_f32 v18, v131, 0xba800000, v18
	v_fmac_f32_e32 v16, 0xba800000, v131
	v_mul_f32_e32 v71, v17, v17
	v_mul_f32_e32 v78, v19, v19
	v_fmac_f32_e32 v71, v16, v16
	v_fmac_f32_e32 v78, v18, v18
	v_add_f32_e32 v71, v71, v78
	v_fmamk_f32 v159, v130, 0xba800000, v115
	v_fmamk_f32 v113, v130, 0xba800000, v113
	v_add_f32_e32 v79, v71, v70
	v_fmamk_f32 v158, v130, 0xba800000, v114
	v_fmac_f32_e32 v112, 0xba800000, v130
	v_mul_f32_e32 v70, v113, v113
	v_mul_f32_e32 v71, v159, v159
	v_fmac_f32_e32 v70, v112, v112
	v_fmac_f32_e32 v71, v158, v158
	v_fmamk_f32 v147, v130, 0xba800000, v87
	v_fmamk_f32 v85, v130, 0xba800000, v85
	v_add_f32_e32 v70, v70, v71
	v_fmamk_f32 v146, v130, 0xba800000, v86
	v_fmac_f32_e32 v84, 0xba800000, v130
	v_mul_f32_e32 v71, v85, v85
	v_mul_f32_e32 v78, v147, v147
	v_fmac_f32_e32 v71, v84, v84
	v_fmac_f32_e32 v78, v146, v146
	v_add_f32_e32 v71, v71, v78
	v_fmamk_f32 v55, v130, 0xba800000, v55
	v_fmamk_f32 v53, v130, 0xba800000, v53
	v_add_f32_e32 v70, v70, v71
	v_fmamk_f32 v54, v130, 0xba800000, v54
	v_fmac_f32_e32 v52, 0xba800000, v130
	v_mul_f32_e32 v71, v53, v53
	v_mul_f32_e32 v78, v55, v55
	v_fmac_f32_e32 v71, v52, v52
	v_fmac_f32_e32 v78, v54, v54
	v_add_f32_e32 v71, v71, v78
	v_fmamk_f32 v23, v130, 0xba800000, v23
	v_fmamk_f32 v21, v130, 0xba800000, v21
	v_add_f32_e32 v70, v71, v70
	v_fmamk_f32 v22, v130, 0xba800000, v22
	v_fmac_f32_e32 v20, 0xba800000, v130
	v_mul_f32_e32 v71, v21, v21
	v_mul_f32_e32 v78, v23, v23
	v_fmac_f32_e32 v71, v20, v20
	v_fmac_f32_e32 v78, v22, v22
	v_add_f32_e32 v71, v71, v78
	v_fmamk_f32 v161, v129, 0xba800000, v127
	v_fmamk_f32 v125, v129, 0xba800000, v125
	v_add_f32_e32 v83, v71, v70
	v_fmamk_f32 v160, v129, 0xba800000, v126
	v_fmac_f32_e32 v124, 0xba800000, v129
	v_mul_f32_e32 v70, v125, v125
	v_mul_f32_e32 v71, v161, v161
	v_fmac_f32_e32 v70, v124, v124
	v_fmac_f32_e32 v71, v160, v160
	v_fmamk_f32 v149, v129, 0xba800000, v91
	v_fmamk_f32 v89, v129, 0xba800000, v89
	v_add_f32_e32 v70, v70, v71
	v_fmamk_f32 v148, v129, 0xba800000, v90
	v_fmac_f32_e32 v88, 0xba800000, v129
	v_mul_f32_e32 v71, v89, v89
	v_mul_f32_e32 v78, v149, v149
	v_fmac_f32_e32 v71, v88, v88
	v_fmac_f32_e32 v78, v148, v148
	v_add_f32_e32 v71, v71, v78
	v_fmamk_f32 v59, v129, 0xba800000, v59
	v_fmamk_f32 v57, v129, 0xba800000, v57
	v_add_f32_e32 v70, v70, v71
	v_fmamk_f32 v58, v129, 0xba800000, v58
	v_fmac_f32_e32 v56, 0xba800000, v129
	v_mul_f32_e32 v71, v57, v57
	v_mul_f32_e32 v78, v59, v59
	v_fmac_f32_e32 v71, v56, v56
	v_fmac_f32_e32 v78, v58, v58
	v_add_f32_e32 v71, v71, v78
	v_fmamk_f32 v27, v129, 0xba800000, v27
	v_fmamk_f32 v25, v129, 0xba800000, v25
	v_add_f32_e32 v70, v71, v70
	v_fmamk_f32 v26, v129, 0xba800000, v26
	v_fmac_f32_e32 v24, 0xba800000, v129
	v_mul_f32_e32 v71, v25, v25
	v_mul_f32_e32 v78, v27, v27
	v_fmac_f32_e32 v71, v24, v24
	v_fmac_f32_e32 v78, v26, v26
	v_add_f32_e32 v71, v71, v78
	v_fmamk_f32 v163, v128, 0xba800000, v123
	v_fmamk_f32 v121, v128, 0xba800000, v121
	v_add_f32_e32 v87, v71, v70
	v_fmamk_f32 v162, v128, 0xba800000, v122
	v_fmac_f32_e32 v120, 0xba800000, v128
	v_mul_f32_e32 v70, v121, v121
	v_mul_f32_e32 v71, v163, v163
	v_fmac_f32_e32 v70, v120, v120
	v_fmac_f32_e32 v71, v162, v162
	v_fmamk_f32 v123, v128, 0xba800000, v95
	v_fmamk_f32 v93, v128, 0xba800000, v93
	v_add_f32_e32 v70, v70, v71
	v_fmamk_f32 v122, v128, 0xba800000, v94
	v_fmac_f32_e32 v92, 0xba800000, v128
	v_mul_f32_e32 v71, v93, v93
	v_mul_f32_e32 v78, v123, v123
	v_fmac_f32_e32 v71, v92, v92
	v_fmac_f32_e32 v78, v122, v122
	v_add_f32_e32 v71, v71, v78
	v_add_f32_e32 v78, v70, v71
	v_fmamk_f32 v70, v128, 0xba800000, v62
	ds_swizzle_b32 v62, v166 offset:swizzle(SWAP,1)
	v_fmamk_f32 v71, v128, 0xba800000, v63
	v_fmamk_f32 v61, v128, 0xba800000, v61
	v_fmac_f32_e32 v60, 0xba800000, v128
	v_mul_f32_e32 v63, v61, v61
	s_waitcnt lgkmcnt(0)
	v_add_f32_e32 v62, v166, v62
	ds_swizzle_b32 v86, v62 offset:swizzle(SWAP,2)
	v_mul_f32_e32 v82, v71, v71
	v_fmac_f32_e32 v63, v60, v60
	v_fmac_f32_e32 v82, v70, v70
	v_add_f32_e32 v63, v63, v82
	s_waitcnt lgkmcnt(0)
	v_add_f32_e32 v62, v62, v86
	v_add_f32_e32 v63, v63, v78
	ds_swizzle_b32 v78, v62 offset:swizzle(SWAP,4)
	ds_swizzle_b32 v82, v167 offset:swizzle(SWAP,1)
	v_fmamk_f32 v31, v128, 0xba800000, v31
	v_fmamk_f32 v29, v128, 0xba800000, v29
	v_fmamk_f32 v30, v128, 0xba800000, v30
	s_waitcnt lgkmcnt(1)
	v_add_f32_e32 v62, v62, v78
	s_waitcnt lgkmcnt(0)
	v_add_f32_e32 v82, v167, v82
	ds_swizzle_b32 v78, v62 offset:swizzle(SWAP,8)
	ds_swizzle_b32 v90, v82 offset:swizzle(SWAP,2)
	v_fmac_f32_e32 v28, 0xba800000, v128
	v_mul_f32_e32 v86, v29, v29
	v_mul_f32_e32 v91, v31, v31
	s_waitcnt lgkmcnt(1)
	v_add_f32_e32 v62, v62, v78
	s_waitcnt lgkmcnt(0)
	v_add_f32_e32 v82, v82, v90
	ds_swizzle_b32 v78, v62 offset:swizzle(SWAP,16)
	ds_swizzle_b32 v90, v82 offset:swizzle(SWAP,4)
	v_fmac_f32_e32 v86, v28, v28
	v_fmac_f32_e32 v91, v30, v30
	v_add_f32_e32 v86, v86, v91
	s_waitcnt lgkmcnt(1)
	v_add_f32_e32 v62, v62, v78
	s_waitcnt lgkmcnt(0)
	v_add_f32_e32 v78, v82, v90
	ds_swizzle_b32 v90, v74 offset:swizzle(SWAP,1)
	ds_swizzle_b32 v82, v78 offset:swizzle(SWAP,8)
	v_add_f32_e32 v63, v86, v63
	v_mov_b32_e32 v86, v62
	s_nop 1
	v_permlane32_swap_b32_e32 v62, v86
	s_waitcnt lgkmcnt(1)
	v_add_f32_e32 v74, v74, v90
	s_waitcnt lgkmcnt(0)
	v_add_f32_e32 v78, v78, v82
	ds_swizzle_b32 v90, v74 offset:swizzle(SWAP,2)
	v_add_f32_e32 v62, v62, v86
	ds_swizzle_b32 v86, v75 offset:swizzle(SWAP,1)
	ds_swizzle_b32 v82, v78 offset:swizzle(SWAP,16)
	ds_swizzle_b32 v91, v83 offset:swizzle(SWAP,1)
	s_waitcnt lgkmcnt(3)
	v_add_f32_e32 v74, v74, v90
	ds_swizzle_b32 v90, v79 offset:swizzle(SWAP,1)
	s_waitcnt lgkmcnt(3)
	v_add_f32_e32 v75, v75, v86
	s_waitcnt lgkmcnt(2)
	v_add_f32_e32 v78, v78, v82
	ds_swizzle_b32 v82, v74 offset:swizzle(SWAP,4)
	ds_swizzle_b32 v86, v75 offset:swizzle(SWAP,2)
	s_waitcnt lgkmcnt(2)
	v_add_f32_e32 v79, v79, v90
	ds_swizzle_b32 v90, v79 offset:swizzle(SWAP,2)
	ds_swizzle_b32 v103, v87 offset:swizzle(SWAP,1)
	s_waitcnt lgkmcnt(3)
	v_add_f32_e32 v74, v74, v82
	s_waitcnt lgkmcnt(2)
	v_add_f32_e32 v75, v75, v86
	ds_swizzle_b32 v82, v74 offset:swizzle(SWAP,8)
	ds_swizzle_b32 v86, v75 offset:swizzle(SWAP,4)
	s_waitcnt lgkmcnt(3)
	v_add_f32_e32 v79, v79, v90
	ds_swizzle_b32 v90, v79 offset:swizzle(SWAP,4)
	v_fmamk_f32 v62, v62, 0x3a800000, v243
	s_waitcnt lgkmcnt(2)
	v_add_f32_e32 v74, v74, v82
	s_waitcnt lgkmcnt(1)
	v_add_f32_e32 v75, v75, v86
	ds_swizzle_b32 v82, v74 offset:swizzle(SWAP,16)
	ds_swizzle_b32 v86, v75 offset:swizzle(SWAP,8)
	s_waitcnt lgkmcnt(2)
	v_add_f32_e32 v79, v79, v90
	ds_swizzle_b32 v90, v79 offset:swizzle(SWAP,8)
	v_cmp_gt_f32_e32 vcc, s84, v62
	s_waitcnt lgkmcnt(2)
	v_add_f32_e32 v82, v74, v82
	s_waitcnt lgkmcnt(1)
	v_add_f32_e32 v74, v75, v86
	ds_swizzle_b32 v75, v74 offset:swizzle(SWAP,16)
	v_mov_b32_e32 v102, v78
	v_mov_b32_e32 v95, v82
	s_nop 0
	v_permlane32_swap_b32_e32 v78, v102
	s_waitcnt lgkmcnt(0)
	v_add_f32_e32 v86, v74, v75
	v_add_f32_e32 v74, v79, v90
	v_add_f32_e32 v79, v83, v91
	ds_swizzle_b32 v75, v74 offset:swizzle(SWAP,16)
	ds_swizzle_b32 v83, v79 offset:swizzle(SWAP,2)
	v_mov_b32_e32 v94, v86
	v_permlane32_swap_b32_e32 v82, v95
	s_waitcnt lgkmcnt(1)
	v_add_f32_e32 v90, v74, v75
	s_waitcnt lgkmcnt(0)
	v_add_f32_e32 v74, v79, v83
	v_add_f32_e32 v79, v87, v103
	ds_swizzle_b32 v87, v63 offset:swizzle(SWAP,1)
	ds_swizzle_b32 v75, v74 offset:swizzle(SWAP,4)
	ds_swizzle_b32 v83, v79 offset:swizzle(SWAP,2)
	v_mov_b32_e32 v91, v90
	v_permlane32_swap_b32_e32 v86, v94
	s_waitcnt lgkmcnt(2)
	v_add_f32_e32 v63, v63, v87
	s_waitcnt lgkmcnt(1)
	v_add_f32_e32 v74, v74, v75
	s_waitcnt lgkmcnt(0)
	v_add_f32_e32 v79, v79, v83
	ds_swizzle_b32 v87, v63 offset:swizzle(SWAP,2)
	ds_swizzle_b32 v75, v74 offset:swizzle(SWAP,8)
	ds_swizzle_b32 v83, v79 offset:swizzle(SWAP,4)
	v_permlane32_swap_b32_e32 v90, v91
	s_waitcnt lgkmcnt(2)
	v_add_f32_e32 v63, v63, v87
	s_waitcnt lgkmcnt(1)
	v_add_f32_e32 v74, v74, v75
	s_waitcnt lgkmcnt(0)
	v_add_f32_e32 v79, v79, v83
	ds_swizzle_b32 v114, v63 offset:swizzle(SWAP,4)
	ds_swizzle_b32 v75, v74 offset:swizzle(SWAP,16)
	ds_swizzle_b32 v103, v79 offset:swizzle(SWAP,8)
	s_waitcnt lgkmcnt(2)
	v_add_f32_e32 v63, v63, v114
	s_waitcnt lgkmcnt(1)
	v_add_f32_e32 v83, v74, v75
	s_waitcnt lgkmcnt(0)
	v_add_f32_e32 v74, v79, v103
	ds_swizzle_b32 v103, v63 offset:swizzle(SWAP,8)
	ds_swizzle_b32 v75, v74 offset:swizzle(SWAP,16)
	v_mov_b32_e32 v87, v83
	s_nop 1
	v_permlane32_swap_b32_e32 v83, v87
	s_waitcnt lgkmcnt(1)
	v_add_f32_e32 v63, v63, v103
	v_mul_f32_e32 v103, 0x4f800000, v62
	s_waitcnt lgkmcnt(0)
	v_add_f32_e32 v75, v74, v75
	ds_swizzle_b32 v74, v63 offset:swizzle(SWAP,16)
	v_cndmask_b32_e32 v103, v62, v103, vcc
	v_sqrt_f32_e32 v114, v103
	v_mov_b32_e32 v79, v75
	s_nop 1
	v_permlane32_swap_b32_e32 v75, v79
	s_waitcnt lgkmcnt(0)
	v_add_f32_e32 v62, v63, v74
	v_add_u32_e32 v63, -1, v114
	v_fma_f32 v74, -v63, v114, v103
	v_cmp_ge_f32_e64 s[6:7], 0, v74
	v_add_u32_e32 v74, 1, v114
	s_nop 0
	v_cndmask_b32_e64 v63, v114, v63, s[6:7]
	v_fma_f32 v114, -v74, v114, v103
	v_cmp_lt_f32_e64 s[6:7], 0, v114
	s_nop 1
	v_cndmask_b32_e64 v63, v63, v74, s[6:7]
	v_mul_f32_e32 v74, 0x37800000, v63
	v_cndmask_b32_e32 v63, v63, v74, vcc
	v_cmp_class_f32_e32 vcc, v103, v248
	s_nop 1
	v_cndmask_b32_e32 v74, v63, v103, vcc
	v_div_scale_f32 v103, s[6:7], v74, v74, 1.0
	v_rcp_f32_e32 v114, v103
	v_mov_b32_e32 v63, v62
	s_nop 1
	v_permlane32_swap_b32_e32 v62, v63
	v_fma_f32 v115, -v103, v114, 1.0
	v_fmac_f32_e32 v114, v115, v114
	v_div_scale_f32 v115, vcc, 1.0, v74, 1.0
	v_mul_f32_e32 v118, v115, v114
	v_fma_f32 v119, -v103, v118, v115
	v_fmac_f32_e32 v118, v119, v114
	v_fma_f32 v103, -v103, v118, v115
	v_div_fmas_f32 v103, v103, v114, v118
	v_div_fixup_f32 v74, v103, v74, 1.0
	s_and_saveexec_b64 s[6:7], s[4:5]
	s_cbranch_execz .LBB0_1225
	v_mov_b32_e32 v103, s13
	v_add_co_u32_e32 v118, vcc, 0x1fa00000, v103
	v_mov_b32_e32 v103, s11
	v_mul_f32_e32 v114, 0x3a800000, v165
	v_addc_co_u32_e32 v119, vcc, 0, v103, vcc
	v_mov_b32_e32 v115, v74
	global_store_dwordx2 v[118:119], v[114:115], off

.LBB0_1552:
	v_add_co_u32_e32 v0, vcc, 0xffff8400, v138
	s_nop 1
	v_addc_co_u32_e32 v1, vcc, -1, v139, vcc
	v_add_co_u32_e32 v2, vcc, 0xffff8800, v138
	s_nop 1
	v_addc_co_u32_e32 v3, vcc, -1, v139, vcc
	s_waitcnt vmcnt(0)
	global_load_dwordx4 v[84:87], v[0:1], off nt
	global_load_dwordx4 v[48:51], v[2:3], off nt
	v_add_co_u32_e32 v0, vcc, 0xffff8c00, v138
	s_waitcnt vmcnt(0) lgkmcnt(0)
	v_add_f32_e32 v128, v84, v85
	v_addc_co_u32_e32 v1, vcc, -1, v139, vcc
	v_add_co_u32_e32 v2, vcc, 0xffff9000, v138
	v_add_f32_e32 v129, v86, v87
	s_nop 0
	v_addc_co_u32_e32 v3, vcc, -1, v139, vcc
	v_add_co_u32_e32 v4, vcc, 0xffff9400, v138
	global_load_dwordx4 v[20:23], v[0:1], off nt
	s_nop 0
	global_load_dwordx4 v[0:3], v[2:3], off nt
	v_addc_co_u32_e32 v5, vcc, -1, v139, vcc
	v_add_co_u32_e32 v6, vcc, 0xffff9800, v138
	v_add_f32_e32 v128, v128, v129
	s_nop 0
	v_addc_co_u32_e32 v7, vcc, -1, v139, vcc
	global_load_dwordx4 v[92:95], v[4:5], off nt
	global_load_dwordx4 v[56:59], v[6:7], off nt
	v_add_co_u32_e32 v4, vcc, 0xffff9c00, v138
	v_add_f32_e32 v129, v48, v49
	s_nop 0
	v_addc_co_u32_e32 v5, vcc, -1, v139, vcc
	v_add_co_u32_e32 v6, vcc, 0xffffa000, v138
	v_add_f32_e32 v130, v50, v51
	s_nop 0
	v_addc_co_u32_e32 v7, vcc, -1, v139, vcc
	v_add_co_u32_e32 v8, vcc, 0xffffa400, v138
	global_load_dwordx4 v[28:31], v[4:5], off nt
	s_nop 0
	global_load_dwordx4 v[4:7], v[6:7], off nt
	v_addc_co_u32_e32 v9, vcc, -1, v139, vcc
	v_add_co_u32_e32 v10, vcc, 0xffffa800, v138
	v_add_f32_e32 v128, 0, v128
	s_nop 0
	v_addc_co_u32_e32 v11, vcc, -1, v139, vcc
	global_load_dwordx4 v[100:103], v[8:9], off nt
	global_load_dwordx4 v[64:67], v[10:11], off nt
	v_add_co_u32_e32 v8, vcc, 0xffffac00, v138
	v_add_f32_e32 v129, v129, v130
	s_nop 0
	v_addc_co_u32_e32 v9, vcc, -1, v139, vcc
	v_add_co_u32_e32 v10, vcc, 0xffffb000, v138
	v_add_f32_e32 v128, v128, v129
	s_nop 0
	v_addc_co_u32_e32 v11, vcc, -1, v139, vcc
	v_add_co_u32_e32 v12, vcc, 0xffffb400, v138
	global_load_dwordx4 v[36:39], v[8:9], off nt
	s_nop 0
	global_load_dwordx4 v[8:11], v[10:11], off nt
	v_addc_co_u32_e32 v13, vcc, -1, v139, vcc
	v_add_co_u32_e32 v14, vcc, 0xffffb800, v138
	s_waitcnt vmcnt(0) lgkmcnt(0)
	v_add_f32_e32 v129, v20, v21
	v_addc_co_u32_e32 v15, vcc, -1, v139, vcc
	global_load_dwordx4 v[108:111], v[12:13], off nt
	global_load_dwordx4 v[76:79], v[14:15], off nt
	v_add_co_u32_e32 v12, vcc, 0xffffbc00, v138
	v_add_f32_e32 v130, v22, v23
	s_nop 0
	v_addc_co_u32_e32 v13, vcc, -1, v139, vcc
	v_add_co_u32_e32 v14, vcc, 0xffffc000, v138
	v_add_f32_e32 v129, v129, v130
	s_nop 0
	v_addc_co_u32_e32 v15, vcc, -1, v139, vcc
	v_add_co_u32_e32 v16, vcc, 0xffffc400, v138
	global_load_dwordx4 v[44:47], v[12:13], off nt
	s_nop 0
	global_load_dwordx4 v[12:15], v[14:15], off nt
	v_addc_co_u32_e32 v17, vcc, -1, v139, vcc
	v_add_co_u32_e32 v18, vcc, 0xffffc800, v138
	v_add_f32_e32 v128, v128, v129
	s_nop 0
	v_addc_co_u32_e32 v19, vcc, -1, v139, vcc
	global_load_dwordx4 v[112:115], v[16:17], off nt
	global_load_dwordx4 v[80:83], v[18:19], off nt
	v_add_co_u32_e32 v16, vcc, 0xffffcc00, v138
	v_add_f32_e32 v129, v0, v1
	s_nop 0
	v_addc_co_u32_e32 v17, vcc, -1, v139, vcc
	v_add_co_u32_e32 v18, vcc, 0xffffd000, v138
	v_add_f32_e32 v130, v2, v3
	s_nop 0
	v_addc_co_u32_e32 v19, vcc, -1, v139, vcc
	v_add_co_u32_e32 v24, vcc, 0xffffd400, v138
	global_load_dwordx4 v[52:55], v[16:17], off nt
	s_nop 0
	global_load_dwordx4 v[16:19], v[18:19], off nt
	v_addc_co_u32_e32 v25, vcc, -1, v139, vcc
	v_add_co_u32_e32 v26, vcc, 0xffffd800, v138
	v_add_f32_e32 v129, v129, v130
	s_nop 0
	v_addc_co_u32_e32 v27, vcc, -1, v139, vcc
	global_load_dwordx4 v[116:119], v[24:25], off nt
	global_load_dwordx4 v[88:91], v[26:27], off nt
	v_add_co_u32_e32 v24, vcc, 0xffffdc00, v138
	v_add_f32_e32 v128, v128, v129
	s_nop 0
	v_addc_co_u32_e32 v25, vcc, -1, v139, vcc
	v_add_co_u32_e32 v26, vcc, 0xffffe000, v138
	v_add_f32_e32 v129, v92, v93
	s_nop 0
	v_addc_co_u32_e32 v27, vcc, -1, v139, vcc
	v_add_co_u32_e32 v32, vcc, 0xffffe400, v138
	global_load_dwordx4 v[60:63], v[24:25], off nt
	s_nop 0
	global_load_dwordx4 v[24:27], v[26:27], off nt
	v_addc_co_u32_e32 v33, vcc, -1, v139, vcc
	v_add_co_u32_e32 v34, vcc, s46, v138
	v_add_f32_e32 v130, v94, v95
	s_nop 0
	v_addc_co_u32_e32 v35, vcc, -1, v139, vcc
	global_load_dwordx4 v[120:123], v[32:33], off nt
	global_load_dwordx4 v[96:99], v[34:35], off nt
	v_add_co_u32_e32 v32, vcc, 0xffffec00, v138
	v_add_f32_e32 v129, v129, v130
	s_nop 0
	v_addc_co_u32_e32 v33, vcc, -1, v139, vcc
	v_add_co_u32_e32 v34, vcc, 0xfffff000, v138
	v_add_f32_e32 v130, v56, v57
	s_nop 0
	v_addc_co_u32_e32 v35, vcc, -1, v139, vcc
	global_load_dwordx4 v[68:71], v[32:33], off nt
	s_nop 0
	global_load_dwordx4 v[32:35], v[34:35], off nt
	v_add_co_u32_e32 v40, vcc, 0xfffff400, v138
	v_add_f32_e32 v131, v58, v59
	s_nop 0
	v_addc_co_u32_e32 v41, vcc, -1, v139, vcc
	v_add_co_u32_e32 v42, vcc, 0xfffff800, v138
	v_add_f32_e32 v129, 0, v129
	s_nop 0
	v_addc_co_u32_e32 v43, vcc, -1, v139, vcc
	global_load_dwordx4 v[124:127], v[40:41], off nt
	global_load_dwordx4 v[104:107], v[42:43], off nt
	v_add_co_u32_e32 v40, vcc, s76, v138
	v_add_f32_e32 v130, v130, v131
	s_nop 0
	v_addc_co_u32_e32 v41, vcc, -1, v139, vcc
	global_load_dwordx4 v[72:75], v[40:41], off nt
	s_nop 0
	global_load_dwordx4 v[40:43], v[138:139], off nt
	v_add_f32_e32 v129, v129, v130
	v_add_f32_e32 v130, v28, v29
	v_add_f32_e32 v131, v30, v31
	v_add_f32_e32 v130, v130, v131
	v_add_f32_e32 v129, v129, v130
	v_add_f32_e32 v130, v4, v5
	v_add_f32_e32 v131, v6, v7
	v_add_f32_e32 v130, v130, v131
	v_add_f32_e32 v129, v129, v130
	v_add_f32_e32 v130, v100, v101
	v_add_f32_e32 v131, v102, v103
	v_add_f32_e32 v130, v130, v131
	v_add_f32_e32 v131, v64, v65
	v_add_f32_e32 v132, v66, v67
	v_add_f32_e32 v130, 0, v130
	v_add_f32_e32 v131, v131, v132
	v_add_f32_e32 v130, v130, v131
	v_add_f32_e32 v131, v36, v37
	v_add_f32_e32 v132, v38, v39
	v_add_f32_e32 v131, v131, v132
	v_add_f32_e32 v130, v130, v131
	v_add_f32_e32 v131, v8, v9
	v_add_f32_e32 v132, v10, v11
	v_add_f32_e32 v131, v131, v132
	v_add_f32_e32 v130, v130, v131
	s_waitcnt vmcnt(0) lgkmcnt(0)
	v_add_f32_e32 v131, v108, v109
	v_add_f32_e32 v132, v110, v111
	v_add_f32_e32 v131, v131, v132
	v_add_f32_e32 v132, v76, v77
	v_add_f32_e32 v133, v78, v79
	v_add_f32_e32 v131, 0, v131
	v_add_f32_e32 v132, v132, v133
	v_add_f32_e32 v131, v131, v132
	v_add_f32_e32 v132, v44, v45
	v_add_f32_e32 v133, v46, v47
	v_add_f32_e32 v132, v132, v133
	v_add_f32_e32 v131, v131, v132
	v_add_f32_e32 v132, v12, v13
	v_add_f32_e32 v133, v14, v15
	v_add_f32_e32 v132, v132, v133
	v_add_f32_e32 v131, v131, v132
	v_add_f32_e32 v132, v112, v113
	v_add_f32_e32 v133, v114, v115
	v_add_f32_e32 v132, v132, v133
	v_add_f32_e32 v133, v80, v81
	v_add_f32_e32 v140, v82, v83
	v_add_f32_e32 v132, 0, v132
	v_add_f32_e32 v133, v133, v140
	v_add_f32_e32 v132, v132, v133
	v_add_f32_e32 v133, v52, v53
	v_add_f32_e32 v140, v54, v55
	v_add_f32_e32 v133, v133, v140
	v_add_f32_e32 v132, v132, v133
	v_add_f32_e32 v133, v16, v17
	v_add_f32_e32 v140, v18, v19
	v_add_f32_e32 v133, v133, v140
	v_add_f32_e32 v132, v132, v133
	v_add_f32_e32 v133, v116, v117
	v_add_f32_e32 v140, v118, v119
	v_add_f32_e32 v133, v133, v140
	v_add_f32_e32 v140, v88, v89
	v_add_f32_e32 v141, v90, v91
	v_add_f32_e32 v133, 0, v133
	v_add_f32_e32 v140, v140, v141
	v_add_f32_e32 v133, v133, v140
	v_add_f32_e32 v140, v60, v61
	v_add_f32_e32 v141, v62, v63
	v_add_f32_e32 v140, v140, v141
	v_add_f32_e32 v133, v133, v140
	v_add_f32_e32 v140, v24, v25
	v_add_f32_e32 v141, v26, v27
	v_add_f32_e32 v140, v140, v141
	v_add_f32_e32 v133, v133, v140
	v_add_f32_e32 v140, v120, v121
	v_add_f32_e32 v141, v122, v123
	v_add_f32_e32 v140, v140, v141
	v_add_f32_e32 v141, v96, v97
	v_add_f32_e32 v142, v98, v99
	v_add_f32_e32 v140, 0, v140
	v_add_f32_e32 v141, v141, v142
	v_add_f32_e32 v140, v140, v141
	v_add_f32_e32 v141, v68, v69
	v_add_f32_e32 v142, v70, v71
	v_add_f32_e32 v141, v141, v142
	v_add_f32_e32 v140, v140, v141
	v_add_f32_e32 v141, v32, v33
	v_add_f32_e32 v142, v34, v35
	v_add_f32_e32 v141, v141, v142
	v_add_f32_e32 v140, v140, v141
	v_add_f32_e32 v141, v124, v125
	v_add_f32_e32 v142, v126, v127
	v_add_f32_e32 v141, v141, v142
	v_add_f32_e32 v143, v104, v105
	v_add_f32_e32 v144, v106, v107
	v_add_f32_e32 v141, 0, v141
	v_add_f32_e32 v143, v143, v144
	v_add_f32_e32 v141, v141, v143
	ds_swizzle_b32 v143, v129 offset:swizzle(SWAP,1)
	ds_swizzle_b32 v142, v128 offset:swizzle(SWAP,1)
	v_add_f32_e32 v144, v72, v73
	v_add_f32_e32 v145, v74, v75
	v_add_f32_e32 v144, v144, v145
	s_waitcnt lgkmcnt(1)
	v_add_f32_e32 v129, v129, v143
	ds_swizzle_b32 v143, v129 offset:swizzle(SWAP,2)
	s_waitcnt lgkmcnt(1)
	v_add_f32_e32 v128, v128, v142
	ds_swizzle_b32 v142, v128 offset:swizzle(SWAP,2)
	v_add_f32_e32 v141, v141, v144
	v_add_f32_e32 v144, v40, v41
	s_waitcnt lgkmcnt(1)
	v_add_f32_e32 v129, v129, v143
	ds_swizzle_b32 v143, v129 offset:swizzle(SWAP,4)
	s_waitcnt lgkmcnt(1)
	v_add_f32_e32 v128, v128, v142
	ds_swizzle_b32 v142, v128 offset:swizzle(SWAP,4)
	v_add_f32_e32 v145, v42, v43
	v_add_f32_e32 v144, v144, v145
	s_waitcnt lgkmcnt(1)
	v_add_f32_e32 v129, v129, v143
	ds_swizzle_b32 v143, v129 offset:swizzle(SWAP,8)
	s_waitcnt lgkmcnt(1)
	v_add_f32_e32 v128, v128, v142
	ds_swizzle_b32 v142, v128 offset:swizzle(SWAP,8)
	v_add_f32_e32 v141, v141, v144
	ds_swizzle_b32 v144, v130 offset:swizzle(SWAP,1)
	s_waitcnt lgkmcnt(2)
	v_add_f32_e32 v129, v129, v143
	ds_swizzle_b32 v143, v129 offset:swizzle(SWAP,16)
	s_waitcnt lgkmcnt(2)
	v_add_f32_e32 v128, v128, v142
	ds_swizzle_b32 v142, v128 offset:swizzle(SWAP,16)
	s_waitcnt lgkmcnt(2)
	v_add_f32_e32 v130, v130, v144
	ds_swizzle_b32 v144, v131 offset:swizzle(SWAP,1)
	s_waitcnt lgkmcnt(2)
	v_add_f32_e32 v129, v129, v143
	v_mov_b32_e32 v143, v129
	s_waitcnt lgkmcnt(1)
	v_add_f32_e32 v128, v128, v142
	v_permlane32_swap_b32_e32 v129, v143
	v_mov_b32_e32 v142, v128
	s_waitcnt lgkmcnt(0)
	v_add_f32_e32 v131, v131, v144
	v_add_f32_e32 v129, v129, v143
	ds_swizzle_b32 v143, v132 offset:swizzle(SWAP,1)
	v_permlane32_swap_b32_e32 v128, v142
	ds_swizzle_b32 v144, v131 offset:swizzle(SWAP,2)
	v_add_f32_e32 v128, v128, v142
	ds_swizzle_b32 v142, v130 offset:swizzle(SWAP,2)
	s_waitcnt lgkmcnt(2)
	v_add_f32_e32 v132, v132, v143
	ds_swizzle_b32 v143, v132 offset:swizzle(SWAP,2)
	s_waitcnt lgkmcnt(2)
	v_add_f32_e32 v131, v131, v144
	ds_swizzle_b32 v144, v131 offset:swizzle(SWAP,4)
	s_waitcnt lgkmcnt(2)
	v_add_f32_e32 v130, v130, v142
	ds_swizzle_b32 v142, v130 offset:swizzle(SWAP,4)
	s_waitcnt lgkmcnt(2)
	v_add_f32_e32 v132, v132, v143
	ds_swizzle_b32 v143, v132 offset:swizzle(SWAP,4)
	s_waitcnt lgkmcnt(2)
	v_add_f32_e32 v131, v131, v144
	ds_swizzle_b32 v144, v131 offset:swizzle(SWAP,8)
	s_waitcnt lgkmcnt(2)
	v_add_f32_e32 v130, v130, v142
	ds_swizzle_b32 v142, v130 offset:swizzle(SWAP,8)
	s_waitcnt lgkmcnt(2)
	v_add_f32_e32 v132, v132, v143
	ds_swizzle_b32 v143, v132 offset:swizzle(SWAP,8)
	s_waitcnt lgkmcnt(2)
	v_add_f32_e32 v131, v131, v144
	ds_swizzle_b32 v144, v131 offset:swizzle(SWAP,16)
	s_waitcnt lgkmcnt(2)
	v_add_f32_e32 v130, v130, v142
	ds_swizzle_b32 v142, v130 offset:swizzle(SWAP,16)
	s_waitcnt lgkmcnt(2)
	v_add_f32_e32 v132, v132, v143
	ds_swizzle_b32 v143, v132 offset:swizzle(SWAP,16)
	s_waitcnt lgkmcnt(2)
	v_add_f32_e32 v131, v131, v144
	ds_swizzle_b32 v144, v133 offset:swizzle(SWAP,1)
	s_waitcnt lgkmcnt(2)
	v_add_f32_e32 v130, v130, v142
	v_mov_b32_e32 v142, v130
	s_nop 1
	v_permlane32_swap_b32_e32 v130, v142
	v_add_f32_e32 v130, v130, v142
	v_mov_b32_e32 v142, v131
	s_nop 1
	v_permlane32_swap_b32_e32 v131, v142
	s_waitcnt lgkmcnt(1)
	v_add_f32_e32 v132, v132, v143
	s_waitcnt lgkmcnt(0)
	v_add_f32_e32 v133, v133, v144
	ds_swizzle_b32 v144, v140 offset:swizzle(SWAP,1)
	v_add_f32_e32 v131, v131, v142
	ds_swizzle_b32 v142, v133 offset:swizzle(SWAP,2)
	v_mov_b32_e32 v143, v132
	s_nop 1
	v_permlane32_swap_b32_e32 v132, v143
	v_add_f32_e32 v132, v132, v143
	ds_swizzle_b32 v143, v141 offset:swizzle(SWAP,1)
	s_waitcnt lgkmcnt(2)
	v_add_f32_e32 v140, v140, v144
	s_waitcnt lgkmcnt(1)
	v_add_f32_e32 v133, v133, v142
	ds_swizzle_b32 v144, v140 offset:swizzle(SWAP,2)
	ds_swizzle_b32 v142, v133 offset:swizzle(SWAP,4)
	s_waitcnt lgkmcnt(2)
	v_add_f32_e32 v141, v141, v143
	ds_swizzle_b32 v143, v141 offset:swizzle(SWAP,2)
	v_fmamk_f32 v87, v128, 0xba800000, v87
	s_waitcnt lgkmcnt(2)
	v_add_f32_e32 v140, v140, v144
	s_waitcnt lgkmcnt(1)
	v_add_f32_e32 v133, v133, v142
	ds_swizzle_b32 v144, v140 offset:swizzle(SWAP,4)
	ds_swizzle_b32 v142, v133 offset:swizzle(SWAP,8)
	s_waitcnt lgkmcnt(2)
	v_add_f32_e32 v141, v141, v143
	ds_swizzle_b32 v143, v141 offset:swizzle(SWAP,4)
	v_fmamk_f32 v85, v128, 0xba800000, v85
	s_waitcnt lgkmcnt(2)
	v_add_f32_e32 v140, v140, v144
	s_waitcnt lgkmcnt(1)
	v_add_f32_e32 v133, v133, v142
	ds_swizzle_b32 v144, v140 offset:swizzle(SWAP,8)
	ds_swizzle_b32 v142, v133 offset:swizzle(SWAP,16)
	s_waitcnt lgkmcnt(2)
	v_add_f32_e32 v141, v141, v143
	ds_swizzle_b32 v143, v141 offset:swizzle(SWAP,8)
	v_fmamk_f32 v86, v128, 0xba800000, v86
	s_waitcnt lgkmcnt(2)
	v_add_f32_e32 v140, v140, v144
	s_waitcnt lgkmcnt(1)
	v_add_f32_e32 v133, v133, v142
	ds_swizzle_b32 v144, v140 offset:swizzle(SWAP,16)
	v_mov_b32_e32 v142, v133
	s_nop 1
	v_permlane32_swap_b32_e32 v133, v142
	s_waitcnt lgkmcnt(1)
	v_add_f32_e32 v141, v141, v143
	v_add_f32_e32 v133, v133, v142
	ds_swizzle_b32 v142, v141 offset:swizzle(SWAP,16)
	s_waitcnt lgkmcnt(1)
	v_add_f32_e32 v140, v140, v144
	v_mov_b32_e32 v143, v140
	s_nop 1
	v_permlane32_swap_b32_e32 v140, v143
	v_add_f32_e32 v143, v140, v143
	s_waitcnt lgkmcnt(0)
	v_add_f32_e32 v140, v141, v142
	v_mov_b32_e32 v141, v140
	s_nop 1
	v_permlane32_swap_b32_e32 v140, v141
	v_add_f32_e32 v142, v140, v141
	v_fmac_f32_e32 v84, 0xba800000, v128
	v_mul_f32_e32 v140, v85, v85
	v_mul_f32_e32 v141, v87, v87
	v_fmac_f32_e32 v140, v84, v84
	v_fmac_f32_e32 v141, v86, v86
	v_fmamk_f32 v51, v128, 0xba800000, v51
	v_fmamk_f32 v49, v128, 0xba800000, v49
	v_add_f32_e32 v140, v140, v141
	v_fmamk_f32 v50, v128, 0xba800000, v50
	v_fmac_f32_e32 v48, 0xba800000, v128
	v_mul_f32_e32 v141, v49, v49
	v_mul_f32_e32 v144, v51, v51
	v_fmac_f32_e32 v141, v48, v48
	v_fmac_f32_e32 v144, v50, v50
	v_add_f32_e32 v141, v141, v144
	v_fmamk_f32 v23, v128, 0xba800000, v23
	v_fmamk_f32 v21, v128, 0xba800000, v21
	v_add_f32_e32 v140, v140, v141
	v_fmamk_f32 v22, v128, 0xba800000, v22
	v_fmac_f32_e32 v20, 0xba800000, v128
	v_mul_f32_e32 v141, v21, v21
	v_mul_f32_e32 v144, v23, v23
	v_fmac_f32_e32 v141, v20, v20
	v_fmac_f32_e32 v144, v22, v22
	v_add_f32_e32 v141, v141, v144
	v_fmamk_f32 v3, v128, 0xba800000, v3
	v_fmamk_f32 v1, v128, 0xba800000, v1
	v_add_f32_e32 v140, v141, v140
	v_fmamk_f32 v2, v128, 0xba800000, v2
	v_fmac_f32_e32 v0, 0xba800000, v128
	v_mul_f32_e32 v128, v1, v1
	v_mul_f32_e32 v141, v3, v3
	v_fmac_f32_e32 v128, v0, v0
	v_fmac_f32_e32 v141, v2, v2
	v_add_f32_e32 v128, v128, v141
	v_fmamk_f32 v95, v129, 0xba800000, v95
	v_fmamk_f32 v93, v129, 0xba800000, v93
	v_add_f32_e32 v128, v128, v140
	v_fmamk_f32 v94, v129, 0xba800000, v94
	v_fmac_f32_e32 v92, 0xba800000, v129
	v_mul_f32_e32 v140, v93, v93
	v_mul_f32_e32 v141, v95, v95
	v_fmac_f32_e32 v140, v92, v92
	v_fmac_f32_e32 v141, v94, v94
	v_fmamk_f32 v59, v129, 0xba800000, v59
	v_fmamk_f32 v57, v129, 0xba800000, v57
	v_add_f32_e32 v140, v140, v141
	v_fmamk_f32 v58, v129, 0xba800000, v58
	v_fmac_f32_e32 v56, 0xba800000, v129
	v_mul_f32_e32 v141, v57, v57
	v_mul_f32_e32 v144, v59, v59
	v_fmac_f32_e32 v141, v56, v56
	v_fmac_f32_e32 v144, v58, v58
	v_add_f32_e32 v141, v141, v144
	v_fmamk_f32 v31, v129, 0xba800000, v31
	v_fmamk_f32 v29, v129, 0xba800000, v29
	v_add_f32_e32 v140, v140, v141
	v_fmamk_f32 v30, v129, 0xba800000, v30
	v_fmac_f32_e32 v28, 0xba800000, v129
	v_mul_f32_e32 v141, v29, v29
	v_mul_f32_e32 v144, v31, v31
	v_fmac_f32_e32 v141, v28, v28
	v_fmac_f32_e32 v144, v30, v30
	v_add_f32_e32 v141, v141, v144
	v_fmamk_f32 v7, v129, 0xba800000, v7
	v_fmamk_f32 v5, v129, 0xba800000, v5
	v_add_f32_e32 v140, v141, v140
	v_fmamk_f32 v6, v129, 0xba800000, v6
	v_fmac_f32_e32 v4, 0xba800000, v129
	v_mul_f32_e32 v129, v5, v5
	v_mul_f32_e32 v141, v7, v7
	v_fmac_f32_e32 v129, v4, v4
	v_fmac_f32_e32 v141, v6, v6
	v_add_f32_e32 v129, v129, v141
	v_fmamk_f32 v103, v130, 0xba800000, v103
	v_fmamk_f32 v101, v130, 0xba800000, v101
	v_add_f32_e32 v129, v129, v140
	v_fmamk_f32 v102, v130, 0xba800000, v102
	v_fmac_f32_e32 v100, 0xba800000, v130
	v_mul_f32_e32 v140, v101, v101
	v_mul_f32_e32 v141, v103, v103
	v_fmac_f32_e32 v140, v100, v100
	v_fmac_f32_e32 v141, v102, v102
	v_fmamk_f32 v67, v130, 0xba800000, v67
	v_fmamk_f32 v65, v130, 0xba800000, v65
	v_add_f32_e32 v140, v140, v141
	v_fmamk_f32 v66, v130, 0xba800000, v66
	v_fmac_f32_e32 v64, 0xba800000, v130
	v_mul_f32_e32 v141, v65, v65
	v_mul_f32_e32 v144, v67, v67
	v_fmac_f32_e32 v141, v64, v64
	v_fmac_f32_e32 v144, v66, v66
	v_add_f32_e32 v141, v141, v144
	v_fmamk_f32 v39, v130, 0xba800000, v39
	v_fmamk_f32 v37, v130, 0xba800000, v37
	v_add_f32_e32 v140, v140, v141
	v_fmamk_f32 v38, v130, 0xba800000, v38
	v_fmac_f32_e32 v36, 0xba800000, v130
	v_mul_f32_e32 v141, v37, v37
	v_mul_f32_e32 v144, v39, v39
	v_fmac_f32_e32 v141, v36, v36
	v_fmac_f32_e32 v144, v38, v38
	v_add_f32_e32 v141, v141, v144
	v_fmamk_f32 v11, v130, 0xba800000, v11
	v_fmamk_f32 v9, v130, 0xba800000, v9
	v_add_f32_e32 v140, v141, v140
	v_fmamk_f32 v10, v130, 0xba800000, v10
	v_fmac_f32_e32 v8, 0xba800000, v130
	v_mul_f32_e32 v130, v9, v9
	v_mul_f32_e32 v141, v11, v11
	v_fmac_f32_e32 v130, v8, v8
	v_fmac_f32_e32 v141, v10, v10
	v_add_f32_e32 v130, v130, v141
	v_fmamk_f32 v111, v131, 0xba800000, v111
	v_fmamk_f32 v109, v131, 0xba800000, v109
	v_add_f32_e32 v130, v130, v140
	v_fmamk_f32 v110, v131, 0xba800000, v110
	v_fmac_f32_e32 v108, 0xba800000, v131
	v_mul_f32_e32 v140, v109, v109
	v_mul_f32_e32 v141, v111, v111
	v_fmac_f32_e32 v140, v108, v108
	v_fmac_f32_e32 v141, v110, v110
	v_fmamk_f32 v79, v131, 0xba800000, v79
	v_fmamk_f32 v77, v131, 0xba800000, v77
	v_add_f32_e32 v140, v140, v141
	v_fmamk_f32 v78, v131, 0xba800000, v78
	v_fmac_f32_e32 v76, 0xba800000, v131
	v_mul_f32_e32 v141, v77, v77
	v_mul_f32_e32 v144, v79, v79
	v_fmac_f32_e32 v141, v76, v76
	v_fmac_f32_e32 v144, v78, v78
	v_add_f32_e32 v141, v141, v144
	v_fmamk_f32 v47, v131, 0xba800000, v47
	v_fmamk_f32 v45, v131, 0xba800000, v45
	v_add_f32_e32 v140, v140, v141
	v_fmamk_f32 v46, v131, 0xba800000, v46
	v_fmac_f32_e32 v44, 0xba800000, v131
	v_mul_f32_e32 v141, v45, v45
	v_mul_f32_e32 v144, v47, v47
	v_fmac_f32_e32 v141, v44, v44
	v_fmac_f32_e32 v144, v46, v46
	v_add_f32_e32 v141, v141, v144
	v_fmamk_f32 v15, v131, 0xba800000, v15
	v_fmamk_f32 v13, v131, 0xba800000, v13
	v_add_f32_e32 v140, v141, v140
	v_fmamk_f32 v14, v131, 0xba800000, v14
	v_fmac_f32_e32 v12, 0xba800000, v131
	v_mul_f32_e32 v131, v13, v13
	v_mul_f32_e32 v141, v15, v15
	v_fmac_f32_e32 v131, v12, v12
	v_fmac_f32_e32 v141, v14, v14
	v_add_f32_e32 v131, v131, v141
	v_fmamk_f32 v115, v132, 0xba800000, v115
	v_fmamk_f32 v113, v132, 0xba800000, v113
	v_add_f32_e32 v131, v131, v140
	v_fmamk_f32 v114, v132, 0xba800000, v114
	v_fmac_f32_e32 v112, 0xba800000, v132
	v_mul_f32_e32 v140, v113, v113
	v_mul_f32_e32 v141, v115, v115
	v_fmac_f32_e32 v140, v112, v112
	v_fmac_f32_e32 v141, v114, v114
	v_fmamk_f32 v83, v132, 0xba800000, v83
	v_fmamk_f32 v81, v132, 0xba800000, v81
	v_add_f32_e32 v140, v140, v141
	v_fmamk_f32 v82, v132, 0xba800000, v82
	v_fmac_f32_e32 v80, 0xba800000, v132
	v_mul_f32_e32 v141, v81, v81
	v_mul_f32_e32 v144, v83, v83
	v_fmac_f32_e32 v141, v80, v80
	v_fmac_f32_e32 v144, v82, v82
	v_add_f32_e32 v141, v141, v144
	v_fmamk_f32 v55, v132, 0xba800000, v55
	v_fmamk_f32 v53, v132, 0xba800000, v53
	v_add_f32_e32 v140, v140, v141
	v_fmamk_f32 v54, v132, 0xba800000, v54
	v_fmac_f32_e32 v52, 0xba800000, v132
	v_mul_f32_e32 v141, v53, v53
	v_mul_f32_e32 v144, v55, v55
	v_fmac_f32_e32 v141, v52, v52
	v_fmac_f32_e32 v144, v54, v54
	v_add_f32_e32 v141, v141, v144
	v_fmamk_f32 v19, v132, 0xba800000, v19
	v_fmamk_f32 v17, v132, 0xba800000, v17
	v_add_f32_e32 v140, v141, v140
	v_fmamk_f32 v18, v132, 0xba800000, v18
	v_fmac_f32_e32 v16, 0xba800000, v132
	v_mul_f32_e32 v132, v17, v17
	v_mul_f32_e32 v141, v19, v19
	v_fmac_f32_e32 v132, v16, v16
	v_fmac_f32_e32 v141, v18, v18
	v_add_f32_e32 v132, v132, v141
	v_fmamk_f32 v141, v133, 0xba800000, v119
	v_fmamk_f32 v117, v133, 0xba800000, v117
	v_add_f32_e32 v132, v132, v140
	v_fmamk_f32 v140, v133, 0xba800000, v118
	v_fmac_f32_e32 v116, 0xba800000, v133
	v_mul_f32_e32 v118, v117, v117
	v_mul_f32_e32 v119, v141, v141
	v_fmac_f32_e32 v118, v116, v116
	v_fmac_f32_e32 v119, v140, v140
	v_fmamk_f32 v91, v133, 0xba800000, v91
	v_fmamk_f32 v89, v133, 0xba800000, v89
	v_add_f32_e32 v118, v118, v119
	v_fmamk_f32 v90, v133, 0xba800000, v90
	v_fmac_f32_e32 v88, 0xba800000, v133
	v_mul_f32_e32 v119, v89, v89
	v_mul_f32_e32 v144, v91, v91
	v_fmac_f32_e32 v119, v88, v88
	v_fmac_f32_e32 v144, v90, v90
	v_add_f32_e32 v119, v119, v144
	v_fmamk_f32 v63, v133, 0xba800000, v63
	v_fmamk_f32 v61, v133, 0xba800000, v61
	v_add_f32_e32 v118, v118, v119
	v_fmamk_f32 v62, v133, 0xba800000, v62
	v_fmac_f32_e32 v60, 0xba800000, v133
	v_mul_f32_e32 v119, v61, v61
	v_mul_f32_e32 v144, v63, v63
	v_fmac_f32_e32 v119, v60, v60
	v_fmac_f32_e32 v144, v62, v62
	v_add_f32_e32 v119, v119, v144
	v_fmamk_f32 v27, v133, 0xba800000, v27
	v_fmamk_f32 v25, v133, 0xba800000, v25
	v_add_f32_e32 v118, v119, v118
	v_fmamk_f32 v26, v133, 0xba800000, v26
	v_fmac_f32_e32 v24, 0xba800000, v133
	v_mul_f32_e32 v119, v25, v25
	v_mul_f32_e32 v133, v27, v27
	v_fmac_f32_e32 v119, v24, v24
	v_fmac_f32_e32 v133, v26, v26
	v_add_f32_e32 v119, v119, v133
	v_fmamk_f32 v153, v143, 0xba800000, v123
	v_fmamk_f32 v121, v143, 0xba800000, v121
	v_add_f32_e32 v118, v119, v118
	v_fmamk_f32 v152, v143, 0xba800000, v122
	v_fmac_f32_e32 v120, 0xba800000, v143
	v_mul_f32_e32 v119, v121, v121
	v_mul_f32_e32 v122, v153, v153
	v_fmac_f32_e32 v119, v120, v120
	v_fmac_f32_e32 v122, v152, v152
	v_fmamk_f32 v99, v143, 0xba800000, v99
	v_fmamk_f32 v97, v143, 0xba800000, v97
	v_add_f32_e32 v119, v119, v122
	v_fmamk_f32 v98, v143, 0xba800000, v98
	v_fmac_f32_e32 v96, 0xba800000, v143
	v_mul_f32_e32 v122, v97, v97
	v_mul_f32_e32 v123, v99, v99
	v_fmac_f32_e32 v122, v96, v96
	v_fmac_f32_e32 v123, v98, v98
	v_add_f32_e32 v122, v122, v123
	v_fmamk_f32 v71, v143, 0xba800000, v71
	v_fmamk_f32 v69, v143, 0xba800000, v69
	v_add_f32_e32 v119, v119, v122
	v_fmamk_f32 v70, v143, 0xba800000, v70
	v_fmac_f32_e32 v68, 0xba800000, v143
	v_mul_f32_e32 v122, v69, v69
	v_mul_f32_e32 v123, v71, v71
	v_fmac_f32_e32 v122, v68, v68
	v_fmac_f32_e32 v123, v70, v70
	v_add_f32_e32 v122, v122, v123
	v_fmamk_f32 v35, v143, 0xba800000, v35
	v_fmamk_f32 v33, v143, 0xba800000, v33
	v_add_f32_e32 v119, v122, v119
	v_fmamk_f32 v34, v143, 0xba800000, v34
	v_fmac_f32_e32 v32, 0xba800000, v143
	v_mul_f32_e32 v122, v33, v33
	v_mul_f32_e32 v123, v35, v35
	v_fmac_f32_e32 v122, v32, v32
	v_fmac_f32_e32 v123, v34, v34
	v_add_f32_e32 v122, v122, v123
	v_fmamk_f32 v155, v142, 0xba800000, v127
	v_fmamk_f32 v125, v142, 0xba800000, v125
	v_add_f32_e32 v119, v122, v119
	v_fmamk_f32 v154, v142, 0xba800000, v126
	v_fmac_f32_e32 v124, 0xba800000, v142
	v_mul_f32_e32 v122, v125, v125
	v_mul_f32_e32 v123, v155, v155
	v_fmac_f32_e32 v122, v124, v124
	v_fmac_f32_e32 v123, v154, v154
	v_fmamk_f32 v107, v142, 0xba800000, v107
	v_fmamk_f32 v105, v142, 0xba800000, v105
	v_add_f32_e32 v122, v122, v123
	v_fmamk_f32 v106, v142, 0xba800000, v106
	v_fmac_f32_e32 v104, 0xba800000, v142
	v_mul_f32_e32 v123, v105, v105
	v_mul_f32_e32 v126, v107, v107
	v_fmac_f32_e32 v123, v104, v104
	v_fmac_f32_e32 v126, v106, v106
	ds_swizzle_b32 v127, v128 offset:swizzle(SWAP,1)
	v_add_f32_e32 v123, v123, v126
	v_fmamk_f32 v75, v142, 0xba800000, v75
	v_fmamk_f32 v73, v142, 0xba800000, v73
	v_add_f32_e32 v122, v122, v123
	v_fmamk_f32 v74, v142, 0xba800000, v74
	v_fmac_f32_e32 v72, 0xba800000, v142
	v_mul_f32_e32 v123, v73, v73
	v_mul_f32_e32 v126, v75, v75
	v_fmac_f32_e32 v123, v72, v72
	v_fmac_f32_e32 v126, v74, v74
	v_add_f32_e32 v123, v123, v126
	v_add_f32_e32 v122, v123, v122
	s_waitcnt lgkmcnt(0)
	v_add_f32_e32 v123, v128, v127
	ds_swizzle_b32 v126, v123 offset:swizzle(SWAP,2)
	ds_swizzle_b32 v127, v129 offset:swizzle(SWAP,1)
	v_fmamk_f32 v43, v142, 0xba800000, v43
	v_fmamk_f32 v41, v142, 0xba800000, v41
	v_fmamk_f32 v42, v142, 0xba800000, v42
	s_waitcnt lgkmcnt(1)
	v_add_f32_e32 v123, v123, v126
	s_waitcnt lgkmcnt(0)
	v_add_f32_e32 v127, v129, v127
	ds_swizzle_b32 v126, v123 offset:swizzle(SWAP,4)
	ds_swizzle_b32 v129, v127 offset:swizzle(SWAP,2)
	v_fmac_f32_e32 v40, 0xba800000, v142
	v_mul_f32_e32 v128, v41, v41
	v_mul_f32_e32 v133, v43, v43
	s_waitcnt lgkmcnt(1)
	v_add_f32_e32 v123, v123, v126
	s_waitcnt lgkmcnt(0)
	v_add_f32_e32 v127, v127, v129
	ds_swizzle_b32 v126, v123 offset:swizzle(SWAP,8)
	ds_swizzle_b32 v129, v127 offset:swizzle(SWAP,4)
	v_fmac_f32_e32 v128, v40, v40
	v_fmac_f32_e32 v133, v42, v42
	v_add_f32_e32 v128, v128, v133
	s_waitcnt lgkmcnt(1)
	v_add_f32_e32 v123, v123, v126
	s_waitcnt lgkmcnt(0)
	v_add_f32_e32 v129, v127, v129
	ds_swizzle_b32 v126, v123 offset:swizzle(SWAP,16)
	ds_swizzle_b32 v133, v129 offset:swizzle(SWAP,8)
	v_add_f32_e32 v122, v128, v122
	ds_swizzle_b32 v128, v130 offset:swizzle(SWAP,1)
	s_andn2_b64 vcc, exec, s[16:17]
	s_waitcnt lgkmcnt(2)
	v_add_f32_e32 v126, v123, v126
	s_waitcnt lgkmcnt(1)
	v_add_f32_e32 v123, v129, v133
	ds_swizzle_b32 v129, v123 offset:swizzle(SWAP,16)
	s_waitcnt lgkmcnt(1)
	v_add_f32_e32 v128, v130, v128
	ds_swizzle_b32 v130, v128 offset:swizzle(SWAP,2)
	ds_swizzle_b32 v133, v131 offset:swizzle(SWAP,1)
	v_mov_b32_e32 v127, v126
	s_waitcnt lgkmcnt(2)
	v_add_f32_e32 v209, v123, v129
	v_mov_b32_e32 v211, v209
	s_waitcnt lgkmcnt(1)
	v_add_f32_e32 v123, v128, v130
	s_waitcnt lgkmcnt(0)
	v_add_f32_e32 v129, v131, v133
	ds_swizzle_b32 v128, v123 offset:swizzle(SWAP,4)
	ds_swizzle_b32 v130, v129 offset:swizzle(SWAP,2)
	ds_swizzle_b32 v131, v132 offset:swizzle(SWAP,1)
	v_permlane32_swap_b32_e32 v126, v127
	s_waitcnt lgkmcnt(2)
	v_add_f32_e32 v123, v123, v128
	s_waitcnt lgkmcnt(1)
	v_add_f32_e32 v129, v129, v130
	s_waitcnt lgkmcnt(0)
	v_add_f32_e32 v131, v132, v131
	ds_swizzle_b32 v128, v123 offset:swizzle(SWAP,8)
	ds_swizzle_b32 v130, v129 offset:swizzle(SWAP,4)
	ds_swizzle_b32 v132, v131 offset:swizzle(SWAP,2)
	v_permlane32_swap_b32_e32 v209, v211
	s_waitcnt lgkmcnt(2)
	v_add_f32_e32 v123, v123, v128
	s_waitcnt lgkmcnt(1)
	v_add_f32_e32 v129, v129, v130
	s_waitcnt lgkmcnt(0)
	v_add_f32_e32 v131, v131, v132
	ds_swizzle_b32 v128, v123 offset:swizzle(SWAP,16)
	ds_swizzle_b32 v130, v129 offset:swizzle(SWAP,8)
	ds_swizzle_b32 v132, v131 offset:swizzle(SWAP,4)
	s_waitcnt lgkmcnt(2)
	v_add_f32_e32 v213, v123, v128
	s_waitcnt lgkmcnt(1)
	v_add_f32_e32 v123, v129, v130
	s_waitcnt lgkmcnt(0)
	v_add_f32_e32 v129, v131, v132
	ds_swizzle_b32 v131, v118 offset:swizzle(SWAP,1)
	ds_swizzle_b32 v128, v123 offset:swizzle(SWAP,16)
	ds_swizzle_b32 v130, v129 offset:swizzle(SWAP,8)
	v_mov_b32_e32 v215, v213
	s_nop 1
	v_permlane32_swap_b32_e32 v213, v215
	s_waitcnt lgkmcnt(2)
	v_add_f32_e32 v118, v118, v131
	s_waitcnt lgkmcnt(1)
	v_add_f32_e32 v214, v123, v128
	s_waitcnt lgkmcnt(0)
	v_add_f32_e32 v123, v129, v130
	ds_swizzle_b32 v129, v118 offset:swizzle(SWAP,2)
	ds_swizzle_b32 v128, v123 offset:swizzle(SWAP,16)
	v_mov_b32_e32 v216, v214
	s_nop 1
	v_permlane32_swap_b32_e32 v214, v216
	s_waitcnt lgkmcnt(1)
	v_add_f32_e32 v118, v118, v129
	s_waitcnt lgkmcnt(0)
	v_add_f32_e32 v212, v123, v128
	ds_swizzle_b32 v123, v119 offset:swizzle(SWAP,1)
	ds_swizzle_b32 v128, v118 offset:swizzle(SWAP,4)
	ds_swizzle_b32 v129, v122 offset:swizzle(SWAP,1)
	v_mov_b32_e32 v217, v212
	s_nop 1
	v_permlane32_swap_b32_e32 v212, v217
	s_waitcnt lgkmcnt(2)
	v_add_f32_e32 v119, v119, v123
	s_waitcnt lgkmcnt(1)
	v_add_f32_e32 v118, v118, v128
	s_waitcnt lgkmcnt(0)
	v_add_f32_e32 v122, v122, v129
	ds_swizzle_b32 v123, v119 offset:swizzle(SWAP,2)
	ds_swizzle_b32 v128, v118 offset:swizzle(SWAP,8)
	ds_swizzle_b32 v129, v122 offset:swizzle(SWAP,2)
	s_waitcnt lgkmcnt(2)
	v_add_f32_e32 v119, v119, v123
	s_waitcnt lgkmcnt(1)
	v_add_f32_e32 v118, v118, v128
	s_waitcnt lgkmcnt(0)
	v_add_f32_e32 v122, v122, v129
	ds_swizzle_b32 v123, v119 offset:swizzle(SWAP,4)
	ds_swizzle_b32 v128, v118 offset:swizzle(SWAP,16)
	ds_swizzle_b32 v129, v122 offset:swizzle(SWAP,4)
	s_waitcnt lgkmcnt(2)
	v_add_f32_e32 v119, v119, v123
	s_waitcnt lgkmcnt(1)
	v_add_f32_e32 v210, v118, v128
	s_waitcnt lgkmcnt(0)
	v_add_f32_e32 v118, v122, v129
	ds_swizzle_b32 v123, v119 offset:swizzle(SWAP,8)
	ds_swizzle_b32 v122, v118 offset:swizzle(SWAP,8)
	v_mov_b32_e32 v218, v210
	s_nop 1
	v_permlane32_swap_b32_e32 v210, v218
	s_waitcnt lgkmcnt(1)
	v_add_f32_e32 v119, v119, v123
	s_waitcnt lgkmcnt(0)
	v_add_f32_e32 v118, v118, v122
	ds_swizzle_b32 v123, v119 offset:swizzle(SWAP,16)
	ds_swizzle_b32 v122, v118 offset:swizzle(SWAP,16)
	s_waitcnt lgkmcnt(1)
	v_add_f32_e32 v208, v119, v123
	s_waitcnt lgkmcnt(0)
	v_add_f32_e32 v190, v118, v122
	v_mov_b32_e32 v219, v208
	v_mov_b32_e32 v220, v190
	s_nop 0
	v_permlane32_swap_b32_e32 v208, v219
	v_permlane32_swap_b32_e32 v190, v220
	s_cbranch_vccnz .LBB0_1551
	s_movk_i32 s6, 0x8400
	s_mov_b32 s7, -1
	v_lshl_add_u64 v[192:193], v[138:139], 0, s[6:7]
	s_movk_i32 s6, 0x8800
	s_mov_b32 s7, -1
	v_lshl_add_u64 v[172:173], v[138:139], 0, s[6:7]
	s_movk_i32 s6, 0x8c00
	s_mov_b32 s7, -1
	v_lshl_add_u64 v[156:157], v[138:139], 0, s[6:7]
	s_movk_i32 s6, 0x9000
	s_mov_b32 s7, -1
	v_lshl_add_u64 v[118:119], v[138:139], 0, s[6:7]
	s_movk_i32 s6, 0x9400
	s_mov_b32 s7, -1
	v_lshl_add_u64 v[194:195], v[138:139], 0, s[6:7]
	s_movk_i32 s6, 0x9800
	s_mov_b32 s7, -1
	v_lshl_add_u64 v[174:175], v[138:139], 0, s[6:7]
	s_movk_i32 s6, 0x9c00
	s_mov_b32 s7, -1
	v_lshl_add_u64 v[158:159], v[138:139], 0, s[6:7]
	s_movk_i32 s6, 0xa000
	s_mov_b32 s7, -1
	v_lshl_add_u64 v[122:123], v[138:139], 0, s[6:7]
	s_movk_i32 s6, 0xa400
	s_mov_b32 s7, -1
	v_lshl_add_u64 v[198:199], v[138:139], 0, s[6:7]
	s_movk_i32 s6, 0xa800
	s_mov_b32 s7, -1
	v_lshl_add_u64 v[176:177], v[138:139], 0, s[6:7]
	s_movk_i32 s6, 0xac00
	s_mov_b32 s7, -1
	v_lshl_add_u64 v[160:161], v[138:139], 0, s[6:7]
	s_movk_i32 s6, 0xb000
	s_mov_b32 s7, -1
	v_lshl_add_u64 v[142:143], v[138:139], 0, s[6:7]
	s_movk_i32 s6, 0xb400
	s_mov_b32 s7, -1
	v_lshl_add_u64 v[200:201], v[138:139], 0, s[6:7]
	s_movk_i32 s6, 0xb800
	s_mov_b32 s7, -1
	v_lshl_add_u64 v[178:179], v[138:139], 0, s[6:7]
	s_movk_i32 s6, 0xbc00
	s_mov_b32 s7, -1
	v_lshl_add_u64 v[162:163], v[138:139], 0, s[6:7]
	s_movk_i32 s6, 0xc000
	s_mov_b32 s7, -1
	v_lshl_add_u64 v[144:145], v[138:139], 0, s[6:7]
	s_movk_i32 s6, 0xc400
	s_mov_b32 s7, -1
	v_lshl_add_u64 v[204:205], v[138:139], 0, s[6:7]
	s_movk_i32 s6, 0xc800
	s_mov_b32 s7, -1
	v_lshl_add_u64 v[182:183], v[138:139], 0, s[6:7]
	s_movk_i32 s6, 0xcc00
	s_mov_b32 s7, -1
	v_lshl_add_u64 v[166:167], v[138:139], 0, s[6:7]
	s_movk_i32 s6, 0xd000
	s_mov_b32 s7, -1
	v_lshl_add_u64 v[146:147], v[138:139], 0, s[6:7]
	s_movk_i32 s6, 0xd400
	s_mov_b32 s7, -1
	v_lshl_add_u64 v[206:207], v[138:139], 0, s[6:7]
	s_movk_i32 s6, 0xd800
	s_mov_b32 s7, -1
	v_lshl_add_u64 v[186:187], v[138:139], 0, s[6:7]
	s_movk_i32 s6, 0xdc00
	s_mov_b32 s7, -1
	v_lshl_add_u64 v[170:171], v[138:139], 0, s[6:7]
	s_movk_i32 s6, 0xe000
	s_mov_b32 s7, -1
	v_lshl_add_u64 v[150:151], v[138:139], 0, s[6:7]
	s_movk_i32 s6, 0xe400
	s_mov_b32 s7, -1
	v_lshl_add_u64 v[202:203], v[138:139], 0, s[6:7]
	s_movk_i32 s6, 0xe800
	s_mov_b32 s7, -1
	v_lshl_add_u64 v[184:185], v[138:139], 0, s[6:7]
	s_movk_i32 s6, 0xec00
	v_add_f32_e32 v126, v126, v127
	s_mov_b32 s7, -1
	v_fmamk_f32 v126, v126, 0x3a800000, v243
	v_lshl_add_u64 v[168:169], v[138:139], 0, s[6:7]
	s_movk_i32 s6, 0xf000
	v_cmp_gt_f32_e32 vcc, s84, v126
	v_mul_f32_e32 v127, 0x4f800000, v126
	s_mov_b32 s7, -1
	v_cndmask_b32_e32 v126, v126, v127, vcc
	v_lshl_add_u64 v[148:149], v[138:139], 0, s[6:7]
	s_movk_i32 s6, 0xf400
	v_sqrt_f32_e32 v127, v126
	s_mov_b32 s7, -1
	v_lshl_add_u64 v[196:197], v[138:139], 0, s[6:7]
	s_movk_i32 s6, 0xf800
	s_mov_b32 s7, -1
	v_lshl_add_u64 v[180:181], v[138:139], 0, s[6:7]
	s_movk_i32 s6, 0xfc00
	v_add_u32_e32 v128, -1, v127
	s_mov_b32 s7, -1
	v_fma_f32 v129, -v128, v127, v126
	v_lshl_add_u64 v[164:165], v[138:139], 0, s[6:7]
	v_cmp_ge_f32_e64 s[6:7], 0, v129
	v_add_u32_e32 v129, 1, v127
	v_add_f32_e32 v190, v190, v220
	v_cndmask_b32_e64 v128, v127, v128, s[6:7]
	v_fma_f32 v127, -v129, v127, v126
	v_cmp_lt_f32_e64 s[6:7], 0, v127
	v_fmamk_f32 v190, v190, 0x3a800000, v243
	v_mul_f32_e32 v220, 0x4f800000, v190
	v_cndmask_b32_e64 v127, v128, v129, s[6:7]
	v_mul_f32_e32 v128, 0x37800000, v127
	v_cndmask_b32_e32 v127, v127, v128, vcc
	v_cmp_class_f32_e32 vcc, v126, v248
	v_add_f32_e32 v208, v208, v219
	v_fmamk_f32 v208, v208, 0x3a800000, v243
	v_cndmask_b32_e32 v126, v127, v126, vcc
	v_div_scale_f32 v127, s[6:7], v126, v126, 1.0
	v_rcp_f32_e32 v128, v127
	v_mul_f32_e32 v219, 0x4f800000, v208
	v_add_f32_e32 v210, v210, v218
	v_fmamk_f32 v210, v210, 0x3a800000, v243
	v_fma_f32 v129, -v127, v128, 1.0
	v_fmac_f32_e32 v128, v129, v128
	v_div_scale_f32 v129, vcc, 1.0, v126, 1.0
	v_mul_f32_e32 v130, v129, v128
	v_fma_f32 v131, -v127, v130, v129
	v_fmac_f32_e32 v130, v131, v128
	v_fma_f32 v127, -v127, v130, v129
	v_div_fmas_f32 v127, v127, v128, v130
	v_cmp_gt_f32_e32 vcc, s84, v190
	v_mul_f32_e32 v218, 0x4f800000, v210
	v_add_f32_e32 v212, v212, v217
	v_cndmask_b32_e32 v190, v190, v220, vcc
	v_sqrt_f32_e32 v220, v190
	v_fmamk_f32 v212, v212, 0x3a800000, v243
	v_mul_f32_e32 v217, 0x4f800000, v212
	v_add_f32_e32 v214, v214, v216
	v_add_u32_e32 v221, -1, v220
	v_fma_f32 v222, -v221, v220, v190
	v_cmp_ge_f32_e64 s[6:7], 0, v222
	v_add_u32_e32 v222, 1, v220
	v_div_fixup_f32 v188, v127, v126, 1.0
	v_cndmask_b32_e64 v221, v220, v221, s[6:7]
	v_fma_f32 v220, -v222, v220, v190
	v_cmp_lt_f32_e64 s[6:7], 0, v220
	global_load_dwordx4 v[126:129], v[136:137], off nt
	global_load_dwordx4 v[130:133], v[134:135], off nt
	v_cndmask_b32_e64 v220, v221, v222, s[6:7]
	v_mul_f32_e32 v221, 0x37800000, v220
	v_cndmask_b32_e32 v220, v220, v221, vcc
	v_cmp_class_f32_e32 vcc, v190, v248
	v_fmamk_f32 v214, v214, 0x3a800000, v243
	v_mul_f32_e32 v216, 0x4f800000, v214
	v_cndmask_b32_e32 v190, v220, v190, vcc
	v_div_scale_f32 v220, s[6:7], v190, v190, 1.0
	v_rcp_f32_e32 v221, v220
	v_add_f32_e32 v213, v213, v215
	v_fmamk_f32 v213, v213, 0x3a800000, v243
	v_mul_f32_e32 v215, 0x4f800000, v213
	v_fma_f32 v222, -v220, v221, 1.0
	v_fmac_f32_e32 v221, v222, v221
	v_div_scale_f32 v222, vcc, 1.0, v190, 1.0
	v_mul_f32_e32 v223, v222, v221
	v_fma_f32 v224, -v220, v223, v222
	v_fmac_f32_e32 v223, v224, v221
	v_fma_f32 v220, -v220, v223, v222
	v_div_fmas_f32 v220, v220, v221, v223
	v_cmp_gt_f32_e32 vcc, s84, v208
	v_div_fixup_f32 v190, v220, v190, 1.0
	v_add_f32_e32 v209, v209, v211
	v_cndmask_b32_e32 v208, v208, v219, vcc
	v_sqrt_f32_e32 v219, v208
	v_fmamk_f32 v209, v209, 0x3a800000, v243
	v_mul_f32_e32 v211, 0x4f800000, v209
	v_pk_mul_f32 v[84:85], v[84:85], v[188:189] op_sel_hi:[1,0]
	v_add_u32_e32 v220, -1, v219
	v_fma_f32 v221, -v220, v219, v208
	v_cmp_ge_f32_e64 s[6:7], 0, v221
	v_add_u32_e32 v221, 1, v219
	v_pk_mul_f32 v[86:87], v[86:87], v[188:189] op_sel_hi:[1,0]
	v_cndmask_b32_e64 v220, v219, v220, s[6:7]
	v_fma_f32 v219, -v221, v219, v208
	v_cmp_lt_f32_e64 s[6:7], 0, v219
	v_pk_mul_f32 v[50:51], v[50:51], v[188:189] op_sel_hi:[1,0]
	v_pk_mul_f32 v[48:49], v[48:49], v[188:189] op_sel_hi:[1,0]
	v_cndmask_b32_e64 v219, v220, v221, s[6:7]
	v_mul_f32_e32 v220, 0x37800000, v219
	v_cndmask_b32_e32 v219, v219, v220, vcc
	v_cmp_class_f32_e32 vcc, v208, v248
	v_pk_mul_f32 v[22:23], v[22:23], v[188:189] op_sel_hi:[1,0]
	v_pk_mul_f32 v[20:21], v[20:21], v[188:189] op_sel_hi:[1,0]
	v_cndmask_b32_e32 v208, v219, v208, vcc
	v_div_scale_f32 v219, s[6:7], v208, v208, 1.0
	v_rcp_f32_e32 v220, v219
	v_pk_mul_f32 v[2:3], v[2:3], v[188:189] op_sel_hi:[1,0]
	v_pk_mul_f32 v[0:1], v[0:1], v[188:189] op_sel_hi:[1,0]
	v_fma_f32 v221, -v219, v220, 1.0
	v_fmac_f32_e32 v220, v221, v220
	v_div_scale_f32 v221, vcc, 1.0, v208, 1.0
	v_mul_f32_e32 v222, v221, v220
	v_fma_f32 v223, -v219, v222, v221
	v_fmac_f32_e32 v222, v223, v220
	v_fma_f32 v219, -v219, v222, v221
	v_div_fmas_f32 v219, v219, v220, v222
	v_cmp_gt_f32_e32 vcc, s84, v210
	v_div_fixup_f32 v208, v219, v208, 1.0
	s_waitcnt vmcnt(0) lgkmcnt(0)
	v_pk_fma_f32 v[86:87], v[86:87], v[132:133], v[128:129]
	v_cndmask_b32_e32 v210, v210, v218, vcc
	v_sqrt_f32_e32 v218, v210
	v_pk_fma_f32 v[84:85], v[84:85], v[130:131], v[126:127]
	global_store_dwordx4 v[192:193], v[84:87], off
	v_add_u32_e32 v219, -1, v218
	v_fma_f32 v220, -v219, v218, v210
	v_cmp_ge_f32_e64 s[6:7], 0, v220
	v_add_u32_e32 v220, 1, v218
	s_nop 0
	v_cndmask_b32_e64 v219, v218, v219, s[6:7]
	v_fma_f32 v218, -v220, v218, v210
	v_cmp_lt_f32_e64 s[6:7], 0, v218
	s_nop 1
	v_cndmask_b32_e64 v218, v219, v220, s[6:7]
	v_mul_f32_e32 v219, 0x37800000, v218
	v_cndmask_b32_e32 v218, v218, v219, vcc
	v_cmp_class_f32_e32 vcc, v210, v248
	s_nop 1
	v_cndmask_b32_e32 v210, v218, v210, vcc
	v_div_scale_f32 v218, s[6:7], v210, v210, 1.0
	v_rcp_f32_e32 v219, v218
	s_nop 0
	v_fma_f32 v220, -v218, v219, 1.0
	v_fmac_f32_e32 v219, v220, v219
	v_div_scale_f32 v220, vcc, 1.0, v210, 1.0
	v_mul_f32_e32 v221, v220, v219
	v_fma_f32 v222, -v218, v221, v220
	v_fmac_f32_e32 v221, v222, v219
	v_fma_f32 v218, -v218, v221, v220
	v_div_fmas_f32 v218, v218, v219, v221
	v_cmp_gt_f32_e32 vcc, s84, v212
	v_div_fixup_f32 v210, v218, v210, 1.0
	s_nop 0
	v_cndmask_b32_e32 v212, v212, v217, vcc
	v_sqrt_f32_e32 v217, v212
	s_nop 0
	v_add_u32_e32 v218, -1, v217
	v_fma_f32 v219, -v218, v217, v212
	v_cmp_ge_f32_e64 s[6:7], 0, v219
	v_add_u32_e32 v219, 1, v217
	s_nop 0
	v_cndmask_b32_e64 v218, v217, v218, s[6:7]
	v_fma_f32 v217, -v219, v217, v212
	v_cmp_lt_f32_e64 s[6:7], 0, v217
	s_nop 1
	v_cndmask_b32_e64 v217, v218, v219, s[6:7]
	v_mul_f32_e32 v218, 0x37800000, v217
	v_cndmask_b32_e32 v217, v217, v218, vcc
	v_cmp_class_f32_e32 vcc, v212, v248
	s_nop 1
	v_cndmask_b32_e32 v212, v217, v212, vcc
	v_div_scale_f32 v217, s[6:7], v212, v212, 1.0
	v_rcp_f32_e32 v218, v217
	s_nop 0
	v_fma_f32 v219, -v217, v218, 1.0
	v_fmac_f32_e32 v218, v219, v218
	v_div_scale_f32 v219, vcc, 1.0, v212, 1.0
	v_mul_f32_e32 v220, v219, v218
	v_fma_f32 v221, -v217, v220, v219
	v_fmac_f32_e32 v220, v221, v218
	v_fma_f32 v217, -v217, v220, v219
	v_div_fmas_f32 v217, v217, v218, v220
	v_cmp_gt_f32_e32 vcc, s84, v214
	v_div_fixup_f32 v212, v217, v212, 1.0
	s_nop 0
	v_cndmask_b32_e32 v214, v214, v216, vcc
	v_sqrt_f32_e32 v216, v214
	s_nop 0
	v_add_u32_e32 v217, -1, v216
	v_fma_f32 v218, -v217, v216, v214
	v_cmp_ge_f32_e64 s[6:7], 0, v218
	v_add_u32_e32 v218, 1, v216
	s_nop 0
	v_cndmask_b32_e64 v217, v216, v217, s[6:7]
	v_fma_f32 v216, -v218, v216, v214
	v_cmp_lt_f32_e64 s[6:7], 0, v216
	s_nop 1
	v_cndmask_b32_e64 v216, v217, v218, s[6:7]
	v_mul_f32_e32 v217, 0x37800000, v216
	v_cndmask_b32_e32 v216, v216, v217, vcc
	v_cmp_class_f32_e32 vcc, v214, v248
	s_nop 1
	v_cndmask_b32_e32 v214, v216, v214, vcc
	v_div_scale_f32 v216, s[6:7], v214, v214, 1.0
	v_rcp_f32_e32 v217, v216
	s_nop 0
	v_fma_f32 v218, -v216, v217, 1.0
	v_fmac_f32_e32 v217, v218, v217
	v_div_scale_f32 v218, vcc, 1.0, v214, 1.0
	v_mul_f32_e32 v219, v218, v217
	v_fma_f32 v220, -v216, v219, v218
	v_fmac_f32_e32 v219, v220, v217
	v_fma_f32 v216, -v216, v219, v218
	v_div_fmas_f32 v216, v216, v217, v219
	v_cmp_gt_f32_e32 vcc, s84, v213
	v_div_fixup_f32 v214, v216, v214, 1.0
	s_nop 0
	v_cndmask_b32_e32 v213, v213, v215, vcc
	v_sqrt_f32_e32 v215, v213
	s_nop 0
	v_add_u32_e32 v216, -1, v215
	v_fma_f32 v217, -v216, v215, v213
	v_cmp_ge_f32_e64 s[6:7], 0, v217
	v_add_u32_e32 v217, 1, v215
	s_nop 0
	v_cndmask_b32_e64 v216, v215, v216, s[6:7]
	v_fma_f32 v215, -v217, v215, v213
	v_cmp_lt_f32_e64 s[6:7], 0, v215
	s_nop 1
	v_cndmask_b32_e64 v215, v216, v217, s[6:7]
	v_mul_f32_e32 v216, 0x37800000, v215
	v_cndmask_b32_e32 v215, v215, v216, vcc
	v_cmp_class_f32_e32 vcc, v213, v248
	s_nop 1
	v_cndmask_b32_e32 v213, v215, v213, vcc
	v_div_scale_f32 v215, s[6:7], v213, v213, 1.0
	v_rcp_f32_e32 v216, v215
	s_nop 0
	v_fma_f32 v217, -v215, v216, 1.0
	v_fmac_f32_e32 v216, v217, v216
	v_div_scale_f32 v217, vcc, 1.0, v213, 1.0
	v_mul_f32_e32 v218, v217, v216
	v_fma_f32 v219, -v215, v218, v217
	v_fmac_f32_e32 v218, v219, v216
	v_fma_f32 v215, -v215, v218, v217
	v_div_fmas_f32 v215, v215, v216, v218
	v_cmp_gt_f32_e32 vcc, s84, v209
	v_div_fixup_f32 v216, v215, v213, 1.0
	s_nop 0
	v_cndmask_b32_e32 v209, v209, v211, vcc
	v_sqrt_f32_e32 v211, v209
	s_nop 0
	v_add_u32_e32 v213, -1, v211
	v_fma_f32 v215, -v213, v211, v209
	v_cmp_ge_f32_e64 s[6:7], 0, v215
	v_add_u32_e32 v215, 1, v211
	s_nop 0
	v_cndmask_b32_e64 v213, v211, v213, s[6:7]
	v_fma_f32 v211, -v215, v211, v209
	v_cmp_lt_f32_e64 s[6:7], 0, v211
	s_nop 1
	v_cndmask_b32_e64 v211, v213, v215, s[6:7]
	v_mul_f32_e32 v213, 0x37800000, v211
	v_cndmask_b32_e32 v211, v211, v213, vcc
	v_cmp_class_f32_e32 vcc, v209, v248
	s_nop 1
	v_cndmask_b32_e32 v209, v211, v209, vcc
	v_div_scale_f32 v211, s[6:7], v209, v209, 1.0
	v_rcp_f32_e32 v213, v211
	s_nop 0
	v_fma_f32 v215, -v211, v213, 1.0
	v_fmac_f32_e32 v213, v215, v213
	v_div_scale_f32 v215, vcc, 1.0, v209, 1.0
	v_mul_f32_e32 v217, v215, v213
	v_fma_f32 v218, -v211, v217, v215
	v_fmac_f32_e32 v217, v218, v213
	v_fma_f32 v211, -v211, v217, v215
	v_div_fmas_f32 v211, v211, v213, v217
	v_div_fixup_f32 v218, v211, v209, 1.0
	v_pk_mul_f32 v[84:85], v[92:93], v[218:219] op_sel_hi:[1,0]
	v_pk_mul_f32 v[86:87], v[94:95], v[218:219] op_sel_hi:[1,0]
	v_pk_fma_f32 v[84:85], v[84:85], v[130:131], v[126:127]
	v_pk_fma_f32 v[86:87], v[86:87], v[132:133], v[128:129]
	global_store_dwordx4 v[194:195], v[84:87], off
	s_nop 1
	v_pk_mul_f32 v[84:85], v[100:101], v[216:217] op_sel_hi:[1,0]
	v_pk_mul_f32 v[86:87], v[102:103], v[216:217] op_sel_hi:[1,0]
	v_pk_fma_f32 v[84:85], v[84:85], v[130:131], v[126:127]
	v_pk_fma_f32 v[86:87], v[86:87], v[132:133], v[128:129]
	global_store_dwordx4 v[198:199], v[84:87], off
	s_nop 1
	v_pk_mul_f32 v[84:85], v[108:109], v[214:215] op_sel_hi:[1,0]
	v_pk_mul_f32 v[86:87], v[110:111], v[214:215] op_sel_hi:[1,0]
	v_pk_fma_f32 v[84:85], v[84:85], v[130:131], v[126:127]
	v_pk_fma_f32 v[86:87], v[86:87], v[132:133], v[128:129]
	global_store_dwordx4 v[200:201], v[84:87], off
	s_nop 1
	v_pk_mul_f32 v[84:85], v[112:113], v[212:213] op_sel_hi:[1,0]
	v_pk_mul_f32 v[86:87], v[114:115], v[212:213] op_sel_hi:[1,0]
	v_pk_fma_f32 v[84:85], v[84:85], v[130:131], v[126:127]
	v_pk_fma_f32 v[86:87], v[86:87], v[132:133], v[128:129]
	global_store_dwordx4 v[204:205], v[84:87], off
	s_nop 1
	v_pk_mul_f32 v[84:85], v[116:117], v[210:211] op_sel_hi:[1,0]
	v_pk_mul_f32 v[86:87], v[140:141], v[210:211] op_sel_hi:[1,0]
	v_pk_fma_f32 v[84:85], v[84:85], v[130:131], v[126:127]
	v_pk_fma_f32 v[86:87], v[86:87], v[132:133], v[128:129]
	global_store_dwordx4 v[206:207], v[84:87], off
	s_nop 1
	v_pk_mul_f32 v[84:85], v[120:121], v[208:209] op_sel_hi:[1,0]
	v_pk_mul_f32 v[86:87], v[152:153], v[208:209] op_sel_hi:[1,0]
	v_pk_fma_f32 v[84:85], v[130:131], v[84:85], v[126:127]
	v_pk_fma_f32 v[86:87], v[132:133], v[86:87], v[128:129]
	global_store_dwordx4 v[202:203], v[84:87], off
	s_nop 1
	v_pk_mul_f32 v[84:85], v[124:125], v[190:191] op_sel_hi:[1,0]
	v_pk_mul_f32 v[86:87], v[154:155], v[190:191] op_sel_hi:[1,0]
	v_pk_fma_f32 v[84:85], v[130:131], v[84:85], v[126:127]
	v_pk_fma_f32 v[86:87], v[132:133], v[86:87], v[128:129]
	global_store_dwordx4 v[196:197], v[84:87], off
	global_load_dwordx4 v[84:87], v[134:135], off offset:1024 nt
	s_nop 0
	global_load_dwordx4 v[92:95], v[136:137], off offset:1024 nt
	s_waitcnt vmcnt(0) lgkmcnt(0)
	v_pk_fma_f32 v[48:49], v[48:49], v[84:85], v[92:93]
	v_pk_fma_f32 v[50:51], v[50:51], v[86:87], v[94:95]
	global_store_dwordx4 v[172:173], v[48:51], off
	s_nop 1
	v_pk_mul_f32 v[50:51], v[58:59], v[218:219] op_sel_hi:[1,0]
	v_pk_mul_f32 v[48:49], v[56:57], v[218:219] op_sel_hi:[1,0]
	v_pk_fma_f32 v[50:51], v[50:51], v[86:87], v[94:95]
	v_pk_fma_f32 v[48:49], v[48:49], v[84:85], v[92:93]
	global_store_dwordx4 v[174:175], v[48:51], off
	s_nop 1
	v_pk_mul_f32 v[50:51], v[66:67], v[216:217] op_sel_hi:[1,0]
	v_pk_mul_f32 v[48:49], v[64:65], v[216:217] op_sel_hi:[1,0]
	v_pk_fma_f32 v[50:51], v[50:51], v[86:87], v[94:95]
	v_pk_fma_f32 v[48:49], v[48:49], v[84:85], v[92:93]
	global_store_dwordx4 v[176:177], v[48:51], off
	s_nop 1
	v_pk_mul_f32 v[50:51], v[78:79], v[214:215] op_sel_hi:[1,0]
	v_pk_mul_f32 v[48:49], v[76:77], v[214:215] op_sel_hi:[1,0]
	v_pk_fma_f32 v[50:51], v[50:51], v[86:87], v[94:95]
	v_pk_fma_f32 v[48:49], v[48:49], v[84:85], v[92:93]
	global_store_dwordx4 v[178:179], v[48:51], off
	s_nop 1
	v_pk_mul_f32 v[50:51], v[82:83], v[212:213] op_sel_hi:[1,0]
	v_pk_mul_f32 v[48:49], v[80:81], v[212:213] op_sel_hi:[1,0]
	v_pk_fma_f32 v[50:51], v[50:51], v[86:87], v[94:95]
	v_pk_fma_f32 v[48:49], v[48:49], v[84:85], v[92:93]
	global_store_dwordx4 v[182:183], v[48:51], off
	s_nop 1
	v_pk_mul_f32 v[50:51], v[90:91], v[210:211] op_sel_hi:[1,0]
	v_pk_mul_f32 v[48:49], v[88:89], v[210:211] op_sel_hi:[1,0]
	v_pk_fma_f32 v[50:51], v[50:51], v[86:87], v[94:95]
	v_pk_fma_f32 v[48:49], v[48:49], v[84:85], v[92:93]
	global_store_dwordx4 v[186:187], v[48:51], off
	s_nop 1
	v_pk_mul_f32 v[50:51], v[98:99], v[208:209] op_sel_hi:[1,0]
	v_pk_mul_f32 v[48:49], v[96:97], v[208:209] op_sel_hi:[1,0]
	v_pk_fma_f32 v[50:51], v[50:51], v[86:87], v[94:95]
	v_pk_fma_f32 v[48:49], v[48:49], v[84:85], v[92:93]
	global_store_dwordx4 v[184:185], v[48:51], off
	s_nop 1
	v_pk_mul_f32 v[50:51], v[106:107], v[190:191] op_sel_hi:[1,0]
	v_pk_mul_f32 v[48:49], v[104:105], v[190:191] op_sel_hi:[1,0]
	v_pk_fma_f32 v[50:51], v[50:51], v[86:87], v[94:95]
	v_pk_fma_f32 v[48:49], v[48:49], v[84:85], v[92:93]
	global_store_dwordx4 v[180:181], v[48:51], off
	global_load_dwordx4 v[48:51], v[134:135], off offset:2048 nt
	s_nop 0
	global_load_dwordx4 v[56:59], v[136:137], off offset:2048 nt
	s_waitcnt vmcnt(0) lgkmcnt(0)
	v_pk_fma_f32 v[20:21], v[20:21], v[48:49], v[56:57]
	v_pk_fma_f32 v[22:23], v[22:23], v[50:51], v[58:59]
	global_store_dwordx4 v[156:157], v[20:23], off
	s_nop 1
	v_pk_mul_f32 v[22:23], v[30:31], v[218:219] op_sel_hi:[1,0]
	v_pk_mul_f32 v[20:21], v[28:29], v[218:219] op_sel_hi:[1,0]
	v_pk_fma_f32 v[22:23], v[22:23], v[50:51], v[58:59]
	v_pk_fma_f32 v[20:21], v[20:21], v[48:49], v[56:57]
	global_store_dwordx4 v[158:159], v[20:23], off
	s_nop 1
	v_pk_mul_f32 v[22:23], v[38:39], v[216:217] op_sel_hi:[1,0]
	v_pk_mul_f32 v[20:21], v[36:37], v[216:217] op_sel_hi:[1,0]
	v_pk_fma_f32 v[22:23], v[22:23], v[50:51], v[58:59]
	v_pk_fma_f32 v[20:21], v[20:21], v[48:49], v[56:57]
	global_store_dwordx4 v[160:161], v[20:23], off
	s_nop 1
	v_pk_mul_f32 v[22:23], v[46:47], v[214:215] op_sel_hi:[1,0]
	v_pk_mul_f32 v[20:21], v[44:45], v[214:215] op_sel_hi:[1,0]
	v_pk_fma_f32 v[22:23], v[22:23], v[50:51], v[58:59]
	v_pk_fma_f32 v[20:21], v[20:21], v[48:49], v[56:57]
	global_store_dwordx4 v[162:163], v[20:23], off
	s_nop 1
	v_pk_mul_f32 v[22:23], v[54:55], v[212:213] op_sel_hi:[1,0]
	v_pk_mul_f32 v[20:21], v[52:53], v[212:213] op_sel_hi:[1,0]
	v_pk_fma_f32 v[22:23], v[22:23], v[50:51], v[58:59]
	v_pk_fma_f32 v[20:21], v[20:21], v[48:49], v[56:57]
	global_store_dwordx4 v[166:167], v[20:23], off
	s_nop 1
	v_pk_mul_f32 v[22:23], v[62:63], v[210:211] op_sel_hi:[1,0]
	v_pk_mul_f32 v[20:21], v[60:61], v[210:211] op_sel_hi:[1,0]
	v_pk_fma_f32 v[22:23], v[22:23], v[50:51], v[58:59]
	v_pk_fma_f32 v[20:21], v[20:21], v[48:49], v[56:57]
	global_store_dwordx4 v[170:171], v[20:23], off
	s_nop 1
	v_pk_mul_f32 v[22:23], v[70:71], v[208:209] op_sel_hi:[1,0]
	v_pk_mul_f32 v[20:21], v[68:69], v[208:209] op_sel_hi:[1,0]
	v_pk_fma_f32 v[22:23], v[22:23], v[50:51], v[58:59]
	v_pk_fma_f32 v[20:21], v[20:21], v[48:49], v[56:57]
	global_store_dwordx4 v[168:169], v[20:23], off
	s_nop 1
	v_pk_mul_f32 v[22:23], v[74:75], v[190:191] op_sel_hi:[1,0]
	v_pk_mul_f32 v[20:21], v[72:73], v[190:191] op_sel_hi:[1,0]
	v_pk_fma_f32 v[22:23], v[22:23], v[50:51], v[58:59]
	v_pk_fma_f32 v[20:21], v[20:21], v[48:49], v[56:57]
	global_store_dwordx4 v[164:165], v[20:23], off
	global_load_dwordx4 v[20:23], v[134:135], off offset:3072 nt
	s_nop 0
	global_load_dwordx4 v[28:31], v[136:137], off offset:3072 nt
	s_waitcnt vmcnt(0) lgkmcnt(0)
	v_pk_fma_f32 v[0:1], v[0:1], v[20:21], v[28:29]
	v_pk_fma_f32 v[2:3], v[2:3], v[22:23], v[30:31]
	global_store_dwordx4 v[118:119], v[0:3], off
	s_nop 1
	v_pk_mul_f32 v[2:3], v[6:7], v[218:219] op_sel_hi:[1,0]
	v_pk_mul_f32 v[0:1], v[4:5], v[218:219] op_sel_hi:[1,0]
	v_pk_fma_f32 v[2:3], v[2:3], v[22:23], v[30:31]
	v_pk_fma_f32 v[0:1], v[0:1], v[20:21], v[28:29]
	global_store_dwordx4 v[122:123], v[0:3], off
	s_nop 1
	v_pk_mul_f32 v[2:3], v[10:11], v[216:217] op_sel_hi:[1,0]
	v_pk_mul_f32 v[0:1], v[8:9], v[216:217] op_sel_hi:[1,0]
	v_pk_fma_f32 v[2:3], v[2:3], v[22:23], v[30:31]
	v_pk_fma_f32 v[0:1], v[0:1], v[20:21], v[28:29]
	global_store_dwordx4 v[142:143], v[0:3], off
	s_nop 1
	v_pk_mul_f32 v[2:3], v[14:15], v[214:215] op_sel_hi:[1,0]
	v_pk_mul_f32 v[0:1], v[12:13], v[214:215] op_sel_hi:[1,0]
	v_pk_fma_f32 v[2:3], v[2:3], v[22:23], v[30:31]
	v_pk_fma_f32 v[0:1], v[0:1], v[20:21], v[28:29]
	global_store_dwordx4 v[144:145], v[0:3], off
	s_nop 1
	v_pk_mul_f32 v[2:3], v[18:19], v[212:213] op_sel_hi:[1,0]
	v_pk_mul_f32 v[0:1], v[16:17], v[212:213] op_sel_hi:[1,0]
	v_pk_fma_f32 v[2:3], v[2:3], v[22:23], v[30:31]
	v_pk_fma_f32 v[0:1], v[0:1], v[20:21], v[28:29]
	global_store_dwordx4 v[146:147], v[0:3], off
	s_nop 1
	v_pk_mul_f32 v[2:3], v[26:27], v[210:211] op_sel_hi:[1,0]
	v_pk_mul_f32 v[0:1], v[24:25], v[210:211] op_sel_hi:[1,0]
	v_pk_fma_f32 v[2:3], v[2:3], v[22:23], v[30:31]
	v_pk_fma_f32 v[0:1], v[0:1], v[20:21], v[28:29]
	global_store_dwordx4 v[150:151], v[0:3], off
	s_nop 1
	v_pk_mul_f32 v[2:3], v[34:35], v[208:209] op_sel_hi:[1,0]
	v_pk_mul_f32 v[0:1], v[32:33], v[208:209] op_sel_hi:[1,0]
	v_pk_fma_f32 v[2:3], v[2:3], v[22:23], v[30:31]
	v_pk_fma_f32 v[0:1], v[0:1], v[20:21], v[28:29]
	global_store_dwordx4 v[148:149], v[0:3], off
	s_nop 1
	v_pk_mul_f32 v[2:3], v[42:43], v[190:191] op_sel_hi:[1,0]
	v_pk_mul_f32 v[0:1], v[40:41], v[190:191] op_sel_hi:[1,0]
	v_pk_fma_f32 v[2:3], v[2:3], v[22:23], v[30:31]
	v_pk_fma_f32 v[0:1], v[0:1], v[20:21], v[28:29]
	global_store_dwordx4 v[138:139], v[0:3], off
	s_branch .LBB0_1551

.LBB0_1558:
	s_or_b64 exec, exec, s[6:7]
	global_load_dwordx4 v[126:129], v[134:135], off nt
	global_load_dwordx4 v[130:133], v[136:137], off nt
	v_pk_mul_f32 v[94:95], v[150:151], v[74:75] op_sel_hi:[1,0]
	v_pk_mul_f32 v[104:105], v[104:105], v[74:75] op_sel_hi:[1,0]
	v_lshl_add_u64 v[62:63], s[0:1], 0, v[138:139]
	s_mov_b32 s6, 0x3a00000
	v_pk_mul_f32 v[96:97], v[96:97], v[78:79] op_sel_hi:[1,0]
	v_pk_mul_f32 v[64:65], v[64:65], v[74:75] op_sel_hi:[1,0]
	v_pk_mul_f32 v[34:35], v[34:35], v[74:75] op_sel_hi:[1,0]
	v_pk_mul_f32 v[32:33], v[32:33], v[74:75] op_sel_hi:[1,0]
	v_pk_mul_f32 v[2:3], v[2:3], v[74:75] op_sel_hi:[1,0]
	v_pk_mul_f32 v[0:1], v[0:1], v[74:75] op_sel_hi:[1,0]
	s_add_i32 s10, s10, s12
	s_add_u32 s14, s14, s16
	s_addc_u32 s15, s15, s17
	v_lshl_add_u64 v[138:139], v[138:139], 0, s[18:19]
	v_lshl_add_u64 v[140:141], v[140:141], 0, s[20:21]
	s_cmpk_gt_i32 s10, 0x7fff
	s_waitcnt vmcnt(0) lgkmcnt(0)
	v_pk_fma_f32 v[94:95], v[94:95], v[128:129], v[132:133]
	v_pk_fma_f32 v[104:105], v[104:105], v[126:127], v[130:131]
	v_cvt_pk_bf16_f32 v151, v94, v95
	v_pk_mul_f32 v[94:95], v[98:99], v[78:79] op_sel_hi:[1,0]
	v_cvt_pk_bf16_f32 v150, v104, v105
	v_add_co_u32_e32 v104, vcc, s6, v62
	v_pk_fma_f32 v[94:95], v[94:95], v[128:129], v[132:133]
	v_pk_fma_f32 v[96:97], v[96:97], v[126:127], v[130:131]
	v_addc_co_u32_e32 v105, vcc, 0, v63, vcc
	v_cvt_pk_bf16_f32 v96, v96, v97
	v_cvt_pk_bf16_f32 v97, v94, v95
	global_store_dwordx2 v[104:105], v[96:97], off offset:2048
	v_pk_mul_f32 v[94:95], v[152:153], v[82:83] op_sel_hi:[1,0]
	v_pk_mul_f32 v[96:97], v[108:109], v[82:83] op_sel_hi:[1,0]
	s_mov_b32 s6, 0x3a01000
	v_pk_fma_f32 v[94:95], v[94:95], v[128:129], v[132:133]
	v_pk_fma_f32 v[96:97], v[96:97], v[126:127], v[130:131]
	v_add_co_u32_e32 v108, vcc, s6, v62
	v_cvt_pk_bf16_f32 v96, v96, v97
	v_cvt_pk_bf16_f32 v97, v94, v95
	v_addc_co_u32_e32 v109, vcc, 0, v63, vcc
	global_store_dwordx2 v[108:109], v[96:97], off
	v_pk_mul_f32 v[94:95], v[154:155], v[86:87] op_sel_hi:[1,0]
	v_pk_mul_f32 v[96:97], v[100:101], v[86:87] op_sel_hi:[1,0]
	v_pk_fma_f32 v[94:95], v[94:95], v[128:129], v[132:133]
	v_pk_fma_f32 v[96:97], v[96:97], v[126:127], v[130:131]
	s_mov_b32 s6, 0x3a02000
	v_cvt_pk_bf16_f32 v96, v96, v97
	v_cvt_pk_bf16_f32 v97, v94, v95
	global_store_dwordx2 v[108:109], v[96:97], off offset:2048
	v_pk_mul_f32 v[94:95], v[156:157], v[90:91] op_sel_hi:[1,0]
	v_pk_mul_f32 v[96:97], v[116:117], v[90:91] op_sel_hi:[1,0]
	v_pk_fma_f32 v[94:95], v[94:95], v[128:129], v[132:133]
	v_pk_fma_f32 v[96:97], v[96:97], v[126:127], v[130:131]
	v_add_co_u32_e32 v116, vcc, s6, v62
	v_cvt_pk_bf16_f32 v96, v96, v97
	v_cvt_pk_bf16_f32 v97, v94, v95
	v_addc_co_u32_e32 v117, vcc, 0, v63, vcc
	global_store_dwordx2 v[116:117], v[96:97], off
	v_pk_mul_f32 v[94:95], v[158:159], v[102:103] op_sel_hi:[1,0]
	v_pk_mul_f32 v[96:97], v[112:113], v[102:103] op_sel_hi:[1,0]
	v_pk_fma_f32 v[94:95], v[94:95], v[128:129], v[132:133]
	v_pk_fma_f32 v[96:97], v[96:97], v[126:127], v[130:131]
	s_mov_b32 s6, 0x3a03000
	v_cvt_pk_bf16_f32 v96, v96, v97
	v_cvt_pk_bf16_f32 v97, v94, v95
	global_store_dwordx2 v[116:117], v[96:97], off offset:2048
	v_pk_mul_f32 v[94:95], v[160:161], v[114:115] op_sel_hi:[1,0]
	v_pk_mul_f32 v[96:97], v[124:125], v[114:115] op_sel_hi:[1,0]
	v_pk_fma_f32 v[94:95], v[94:95], v[128:129], v[132:133]
	v_pk_fma_f32 v[96:97], v[96:97], v[126:127], v[130:131]
	v_add_co_u32_e32 v112, vcc, s6, v62
	v_cvt_pk_bf16_f32 v96, v96, v97
	v_cvt_pk_bf16_f32 v97, v94, v95
	v_addc_co_u32_e32 v113, vcc, 0, v63, vcc
	v_pk_mul_f32 v[62:63], v[162:163], v[118:119] op_sel_hi:[1,0]
	v_pk_mul_f32 v[94:95], v[120:121], v[118:119] op_sel_hi:[1,0]
	v_pk_fma_f32 v[62:63], v[62:63], v[128:129], v[132:133]
	v_pk_fma_f32 v[94:95], v[94:95], v[126:127], v[130:131]
	global_store_dwordx2 v[104:105], v[150:151], off
	v_cvt_pk_bf16_f32 v94, v94, v95
	v_cvt_pk_bf16_f32 v95, v62, v63
	global_store_dwordx2 v[112:113], v[96:97], off
	global_store_dwordx2 v[112:113], v[94:95], off offset:2048
	global_load_dwordx4 v[94:97], v[134:135], off offset:1024 nt
	s_nop 0
	global_load_dwordx4 v[98:101], v[136:137], off offset:1024 nt
	v_pk_mul_f32 v[62:63], v[66:67], v[74:75] op_sel_hi:[1,0]
	s_waitcnt vmcnt(0) lgkmcnt(0)
	v_pk_fma_f32 v[64:65], v[64:65], v[94:95], v[98:99]
	v_pk_fma_f32 v[62:63], v[62:63], v[96:97], v[100:101]
	v_cvt_pk_bf16_f32 v64, v64, v65
	v_cvt_pk_bf16_f32 v65, v62, v63
	global_store_dwordx2 v[104:105], v[64:65], off offset:512
	v_pk_mul_f32 v[62:63], v[106:107], v[78:79] op_sel_hi:[1,0]
	v_pk_mul_f32 v[64:65], v[68:69], v[78:79] op_sel_hi:[1,0]
	v_pk_fma_f32 v[62:63], v[62:63], v[96:97], v[100:101]
	v_pk_fma_f32 v[64:65], v[64:65], v[94:95], v[98:99]
	s_nop 0
	v_cvt_pk_bf16_f32 v64, v64, v65
	v_cvt_pk_bf16_f32 v65, v62, v63
	global_store_dwordx2 v[104:105], v[64:65], off offset:2560
	v_pk_mul_f32 v[62:63], v[110:111], v[82:83] op_sel_hi:[1,0]
	v_pk_mul_f32 v[64:65], v[72:73], v[82:83] op_sel_hi:[1,0]
	v_pk_fma_f32 v[62:63], v[62:63], v[96:97], v[100:101]
	v_pk_fma_f32 v[64:65], v[64:65], v[94:95], v[98:99]
	s_nop 0
	v_cvt_pk_bf16_f32 v64, v64, v65
	v_cvt_pk_bf16_f32 v65, v62, v63
	global_store_dwordx2 v[108:109], v[64:65], off offset:512
	v_pk_mul_f32 v[62:63], v[142:143], v[86:87] op_sel_hi:[1,0]
	v_pk_mul_f32 v[64:65], v[76:77], v[86:87] op_sel_hi:[1,0]
	v_pk_fma_f32 v[62:63], v[62:63], v[96:97], v[100:101]
	v_pk_fma_f32 v[64:65], v[64:65], v[94:95], v[98:99]
	s_nop 0
	v_cvt_pk_bf16_f32 v64, v64, v65
	v_cvt_pk_bf16_f32 v65, v62, v63
	global_store_dwordx2 v[108:109], v[64:65], off offset:2560
	v_pk_mul_f32 v[62:63], v[144:145], v[90:91] op_sel_hi:[1,0]
	v_pk_mul_f32 v[64:65], v[80:81], v[90:91] op_sel_hi:[1,0]
	v_pk_fma_f32 v[62:63], v[62:63], v[96:97], v[100:101]
	v_pk_fma_f32 v[64:65], v[64:65], v[94:95], v[98:99]
	s_nop 0
	v_cvt_pk_bf16_f32 v64, v64, v65
	v_cvt_pk_bf16_f32 v65, v62, v63
	global_store_dwordx2 v[116:117], v[64:65], off offset:512
	v_pk_mul_f32 v[62:63], v[146:147], v[102:103] op_sel_hi:[1,0]
	v_pk_mul_f32 v[64:65], v[84:85], v[102:103] op_sel_hi:[1,0]
	v_pk_fma_f32 v[62:63], v[62:63], v[96:97], v[100:101]
	v_pk_fma_f32 v[64:65], v[64:65], v[94:95], v[98:99]
	s_nop 0
	v_cvt_pk_bf16_f32 v64, v64, v65
	v_cvt_pk_bf16_f32 v65, v62, v63
	global_store_dwordx2 v[116:117], v[64:65], off offset:2560
	v_pk_mul_f32 v[62:63], v[148:149], v[114:115] op_sel_hi:[1,0]
	v_pk_mul_f32 v[64:65], v[88:89], v[114:115] op_sel_hi:[1,0]
	v_pk_fma_f32 v[62:63], v[62:63], v[96:97], v[100:101]
	v_pk_fma_f32 v[64:65], v[64:65], v[94:95], v[98:99]
	s_nop 0
	v_cvt_pk_bf16_f32 v64, v64, v65
	v_cvt_pk_bf16_f32 v65, v62, v63
	global_store_dwordx2 v[112:113], v[64:65], off offset:512
	v_pk_mul_f32 v[62:63], v[122:123], v[118:119] op_sel_hi:[1,0]
	v_pk_mul_f32 v[64:65], v[92:93], v[118:119] op_sel_hi:[1,0]
	v_pk_fma_f32 v[62:63], v[62:63], v[96:97], v[100:101]
	v_pk_fma_f32 v[64:65], v[64:65], v[94:95], v[98:99]
	s_nop 0
	v_cvt_pk_bf16_f32 v64, v64, v65
	v_cvt_pk_bf16_f32 v65, v62, v63
	global_store_dwordx2 v[112:113], v[64:65], off offset:2560
	global_load_dwordx4 v[62:65], v[134:135], off offset:2048 nt
	s_nop 0
	global_load_dwordx4 v[66:69], v[136:137], off offset:2048 nt
	s_waitcnt vmcnt(0) lgkmcnt(0)
	v_pk_fma_f32 v[34:35], v[34:35], v[64:65], v[68:69]
	v_pk_fma_f32 v[32:33], v[32:33], v[62:63], v[66:67]
	s_nop 0
	v_cvt_pk_bf16_f32 v32, v32, v33
	v_cvt_pk_bf16_f32 v33, v34, v35
	global_store_dwordx2 v[104:105], v[32:33], off offset:1024
	v_pk_mul_f32 v[32:33], v[38:39], v[78:79] op_sel_hi:[1,0]
	v_pk_mul_f32 v[34:35], v[36:37], v[78:79] op_sel_hi:[1,0]
	v_pk_fma_f32 v[32:33], v[32:33], v[64:65], v[68:69]
	v_pk_fma_f32 v[34:35], v[34:35], v[62:63], v[66:67]
	s_nop 0
	v_cvt_pk_bf16_f32 v34, v34, v35
	v_cvt_pk_bf16_f32 v35, v32, v33
	global_store_dwordx2 v[104:105], v[34:35], off offset:3072
	v_pk_mul_f32 v[32:33], v[42:43], v[82:83] op_sel_hi:[1,0]
	v_pk_mul_f32 v[34:35], v[40:41], v[82:83] op_sel_hi:[1,0]
	v_pk_fma_f32 v[32:33], v[32:33], v[64:65], v[68:69]
	v_pk_fma_f32 v[34:35], v[34:35], v[62:63], v[66:67]
	s_nop 0
	v_cvt_pk_bf16_f32 v34, v34, v35
	v_cvt_pk_bf16_f32 v35, v32, v33
	global_store_dwordx2 v[108:109], v[34:35], off offset:1024
	v_pk_mul_f32 v[32:33], v[46:47], v[86:87] op_sel_hi:[1,0]
	v_pk_mul_f32 v[34:35], v[44:45], v[86:87] op_sel_hi:[1,0]
	v_pk_fma_f32 v[32:33], v[32:33], v[64:65], v[68:69]
	v_pk_fma_f32 v[34:35], v[34:35], v[62:63], v[66:67]
	s_nop 0
	v_cvt_pk_bf16_f32 v34, v34, v35
	v_cvt_pk_bf16_f32 v35, v32, v33
	global_store_dwordx2 v[108:109], v[34:35], off offset:3072
	v_pk_mul_f32 v[32:33], v[50:51], v[90:91] op_sel_hi:[1,0]
	v_pk_mul_f32 v[34:35], v[48:49], v[90:91] op_sel_hi:[1,0]
	v_pk_fma_f32 v[32:33], v[32:33], v[64:65], v[68:69]
	v_pk_fma_f32 v[34:35], v[34:35], v[62:63], v[66:67]
	s_nop 0
	v_cvt_pk_bf16_f32 v34, v34, v35
	v_cvt_pk_bf16_f32 v35, v32, v33
	global_store_dwordx2 v[116:117], v[34:35], off offset:1024
	v_pk_mul_f32 v[32:33], v[54:55], v[102:103] op_sel_hi:[1,0]
	v_pk_mul_f32 v[34:35], v[52:53], v[102:103] op_sel_hi:[1,0]
	v_pk_fma_f32 v[32:33], v[32:33], v[64:65], v[68:69]
	v_pk_fma_f32 v[34:35], v[34:35], v[62:63], v[66:67]
	s_nop 0
	v_cvt_pk_bf16_f32 v34, v34, v35
	v_cvt_pk_bf16_f32 v35, v32, v33
	global_store_dwordx2 v[116:117], v[34:35], off offset:3072
	v_pk_mul_f32 v[32:33], v[58:59], v[114:115] op_sel_hi:[1,0]
	v_pk_mul_f32 v[34:35], v[56:57], v[114:115] op_sel_hi:[1,0]
	v_pk_fma_f32 v[32:33], v[32:33], v[64:65], v[68:69]
	v_pk_fma_f32 v[34:35], v[34:35], v[62:63], v[66:67]
	s_nop 0
	v_cvt_pk_bf16_f32 v34, v34, v35
	v_cvt_pk_bf16_f32 v35, v32, v33
	global_store_dwordx2 v[112:113], v[34:35], off offset:1024
	v_pk_mul_f32 v[32:33], v[70:71], v[118:119] op_sel_hi:[1,0]
	v_pk_mul_f32 v[34:35], v[60:61], v[118:119] op_sel_hi:[1,0]
	v_pk_fma_f32 v[32:33], v[32:33], v[64:65], v[68:69]
	v_pk_fma_f32 v[34:35], v[34:35], v[62:63], v[66:67]
	s_nop 0
	v_cvt_pk_bf16_f32 v34, v34, v35
	v_cvt_pk_bf16_f32 v35, v32, v33
	global_store_dwordx2 v[112:113], v[34:35], off offset:3072
	global_load_dwordx4 v[32:35], v[134:135], off offset:3072 nt
	s_nop 0
	global_load_dwordx4 v[36:39], v[136:137], off offset:3072 nt
	s_waitcnt vmcnt(0) lgkmcnt(0)
	v_pk_fma_f32 v[2:3], v[2:3], v[34:35], v[38:39]
	v_pk_fma_f32 v[0:1], v[0:1], v[32:33], v[36:37]
	s_nop 0
	v_cvt_pk_bf16_f32 v0, v0, v1
	v_cvt_pk_bf16_f32 v1, v2, v3
	global_store_dwordx2 v[104:105], v[0:1], off offset:1536
	v_pk_mul_f32 v[0:1], v[6:7], v[78:79] op_sel_hi:[1,0]
	v_pk_mul_f32 v[2:3], v[4:5], v[78:79] op_sel_hi:[1,0]
	v_pk_fma_f32 v[0:1], v[0:1], v[34:35], v[38:39]
	v_pk_fma_f32 v[2:3], v[2:3], v[32:33], v[36:37]
	s_nop 0
	v_cvt_pk_bf16_f32 v2, v2, v3
	v_cvt_pk_bf16_f32 v3, v0, v1
	global_store_dwordx2 v[104:105], v[2:3], off offset:3584
	v_pk_mul_f32 v[0:1], v[10:11], v[82:83] op_sel_hi:[1,0]
	v_pk_mul_f32 v[2:3], v[8:9], v[82:83] op_sel_hi:[1,0]
	v_pk_fma_f32 v[0:1], v[0:1], v[34:35], v[38:39]
	v_pk_fma_f32 v[2:3], v[2:3], v[32:33], v[36:37]
	s_nop 0
	v_cvt_pk_bf16_f32 v2, v2, v3
	v_cvt_pk_bf16_f32 v3, v0, v1
	global_store_dwordx2 v[108:109], v[2:3], off offset:1536
	v_pk_mul_f32 v[0:1], v[14:15], v[86:87] op_sel_hi:[1,0]
	v_pk_mul_f32 v[2:3], v[12:13], v[86:87] op_sel_hi:[1,0]
	v_pk_fma_f32 v[0:1], v[0:1], v[34:35], v[38:39]
	v_pk_fma_f32 v[2:3], v[2:3], v[32:33], v[36:37]
	s_nop 0
	v_cvt_pk_bf16_f32 v2, v2, v3
	v_cvt_pk_bf16_f32 v3, v0, v1
	global_store_dwordx2 v[108:109], v[2:3], off offset:3584
	v_pk_mul_f32 v[0:1], v[18:19], v[90:91] op_sel_hi:[1,0]
	v_pk_mul_f32 v[2:3], v[16:17], v[90:91] op_sel_hi:[1,0]
	v_pk_fma_f32 v[0:1], v[0:1], v[34:35], v[38:39]
	v_pk_fma_f32 v[2:3], v[2:3], v[32:33], v[36:37]
	s_nop 0
	v_cvt_pk_bf16_f32 v2, v2, v3
	v_cvt_pk_bf16_f32 v3, v0, v1
	global_store_dwordx2 v[116:117], v[2:3], off offset:1536
	v_pk_mul_f32 v[0:1], v[22:23], v[102:103] op_sel_hi:[1,0]
	v_pk_mul_f32 v[2:3], v[20:21], v[102:103] op_sel_hi:[1,0]
	v_pk_fma_f32 v[0:1], v[0:1], v[34:35], v[38:39]
	v_pk_fma_f32 v[2:3], v[2:3], v[32:33], v[36:37]
	s_nop 0
	v_cvt_pk_bf16_f32 v2, v2, v3
	v_cvt_pk_bf16_f32 v3, v0, v1
	global_store_dwordx2 v[116:117], v[2:3], off offset:3584
	v_pk_mul_f32 v[0:1], v[26:27], v[114:115] op_sel_hi:[1,0]
	v_pk_mul_f32 v[2:3], v[24:25], v[114:115] op_sel_hi:[1,0]
	v_pk_fma_f32 v[0:1], v[0:1], v[34:35], v[38:39]
	v_pk_fma_f32 v[2:3], v[2:3], v[32:33], v[36:37]
	s_nop 0
	v_cvt_pk_bf16_f32 v2, v2, v3
	v_cvt_pk_bf16_f32 v3, v0, v1
	global_store_dwordx2 v[112:113], v[2:3], off offset:1536
	v_pk_mul_f32 v[0:1], v[30:31], v[118:119] op_sel_hi:[1,0]
	v_pk_mul_f32 v[2:3], v[28:29], v[118:119] op_sel_hi:[1,0]
	v_pk_fma_f32 v[0:1], v[0:1], v[34:35], v[38:39]
	v_pk_fma_f32 v[2:3], v[2:3], v[32:33], v[36:37]
	s_nop 0
	v_cvt_pk_bf16_f32 v2, v2, v3
	v_cvt_pk_bf16_f32 v3, v0, v1
	global_store_dwordx2 v[112:113], v[2:3], off offset:3584
	s_cbranch_scc1 .LBB0_1575
.LBB0_1559:
	v_add_co_u32_e32 v0, vcc, 0xffff8400, v140
	s_add_u32 s13, s0, s14
	s_nop 0
	v_addc_co_u32_e32 v1, vcc, -1, v141, vcc
	v_add_co_u32_e32 v2, vcc, 0xffff8800, v140
	s_addc_u32 s11, s1, s15
	s_nop 0
	v_addc_co_u32_e32 v3, vcc, -1, v141, vcc
	global_load_dwordx4 v[104:107], v[0:1], off nt
	s_waitcnt vmcnt(0)
	global_load_dwordx4 v[64:67], v[2:3], off nt
	v_add_co_u32_e32 v0, vcc, 0xffff8c00, v140
	s_waitcnt lgkmcnt(0)
	v_add_f32_e32 v128, v104, v105
	v_addc_co_u32_e32 v1, vcc, -1, v141, vcc
	v_add_co_u32_e32 v2, vcc, 0xffff9000, v140
	v_add_f32_e32 v129, v106, v107
	s_nop 0
	v_addc_co_u32_e32 v3, vcc, -1, v141, vcc
	v_add_co_u32_e32 v4, vcc, 0xffff9400, v140
	global_load_dwordx4 v[32:35], v[0:1], off nt
	s_nop 0
	global_load_dwordx4 v[0:3], v[2:3], off nt
	v_addc_co_u32_e32 v5, vcc, -1, v141, vcc
	v_add_co_u32_e32 v6, vcc, 0xffff9800, v140
	v_add_f32_e32 v128, v128, v129
	s_nop 0
	v_addc_co_u32_e32 v7, vcc, -1, v141, vcc
	global_load_dwordx4 v[96:99], v[4:5], off nt
	global_load_dwordx4 v[68:71], v[6:7], off nt
	v_add_co_u32_e32 v4, vcc, 0xffff9c00, v140
	s_waitcnt vmcnt(0)
	v_add_f32_e32 v129, v64, v65
	v_addc_co_u32_e32 v5, vcc, -1, v141, vcc
	v_add_co_u32_e32 v6, vcc, 0xffffa000, v140
	v_add_f32_e32 v130, v66, v67
	s_nop 0
	v_addc_co_u32_e32 v7, vcc, -1, v141, vcc
	v_add_co_u32_e32 v8, vcc, 0xffffa400, v140
	global_load_dwordx4 v[36:39], v[4:5], off nt
	s_nop 0
	global_load_dwordx4 v[4:7], v[6:7], off nt
	v_addc_co_u32_e32 v9, vcc, -1, v141, vcc
	v_add_co_u32_e32 v10, vcc, 0xffffa800, v140
	v_add_f32_e32 v128, 0, v128
	s_nop 0
	v_addc_co_u32_e32 v11, vcc, -1, v141, vcc
	global_load_dwordx4 v[108:111], v[8:9], off nt
	global_load_dwordx4 v[72:75], v[10:11], off nt
	v_add_co_u32_e32 v8, vcc, 0xffffac00, v140
	v_add_f32_e32 v129, v129, v130
	s_nop 0
	v_addc_co_u32_e32 v9, vcc, -1, v141, vcc
	v_add_co_u32_e32 v10, vcc, 0xffffb000, v140
	v_add_f32_e32 v128, v128, v129
	s_nop 0
	v_addc_co_u32_e32 v11, vcc, -1, v141, vcc
	v_add_co_u32_e32 v12, vcc, 0xffffb400, v140
	global_load_dwordx4 v[40:43], v[8:9], off nt
	s_nop 0
	global_load_dwordx4 v[8:11], v[10:11], off nt
	v_addc_co_u32_e32 v13, vcc, -1, v141, vcc
	v_add_co_u32_e32 v14, vcc, 0xffffb800, v140
	s_waitcnt lgkmcnt(0)
	v_add_f32_e32 v129, v32, v33
	v_addc_co_u32_e32 v15, vcc, -1, v141, vcc
	global_load_dwordx4 v[100:103], v[12:13], off nt
	global_load_dwordx4 v[76:79], v[14:15], off nt
	v_add_co_u32_e32 v12, vcc, 0xffffbc00, v140
	v_add_f32_e32 v130, v34, v35
	s_nop 0
	v_addc_co_u32_e32 v13, vcc, -1, v141, vcc
	v_add_co_u32_e32 v14, vcc, 0xffffc000, v140
	v_add_f32_e32 v129, v129, v130
	s_nop 0
	v_addc_co_u32_e32 v15, vcc, -1, v141, vcc
	v_add_co_u32_e32 v16, vcc, 0xffffc400, v140
	global_load_dwordx4 v[44:47], v[12:13], off nt
	s_nop 0
	global_load_dwordx4 v[12:15], v[14:15], off nt
	v_addc_co_u32_e32 v17, vcc, -1, v141, vcc
	v_add_co_u32_e32 v18, vcc, 0xffffc800, v140
	v_add_f32_e32 v128, v128, v129
	s_nop 0
	v_addc_co_u32_e32 v19, vcc, -1, v141, vcc
	global_load_dwordx4 v[116:119], v[16:17], off nt
	global_load_dwordx4 v[80:83], v[18:19], off nt
	v_add_co_u32_e32 v16, vcc, 0xffffcc00, v140
	v_add_f32_e32 v129, v0, v1
	s_nop 0
	v_addc_co_u32_e32 v17, vcc, -1, v141, vcc
	v_add_co_u32_e32 v18, vcc, 0xffffd000, v140
	v_add_f32_e32 v130, v2, v3
	s_nop 0
	v_addc_co_u32_e32 v19, vcc, -1, v141, vcc
	v_add_co_u32_e32 v20, vcc, 0xffffd400, v140
	global_load_dwordx4 v[48:51], v[16:17], off nt
	s_nop 0
	global_load_dwordx4 v[16:19], v[18:19], off nt
	v_addc_co_u32_e32 v21, vcc, -1, v141, vcc
	v_add_co_u32_e32 v22, vcc, 0xffffd800, v140
	v_add_f32_e32 v129, v129, v130
	s_nop 0
	v_addc_co_u32_e32 v23, vcc, -1, v141, vcc
	global_load_dwordx4 v[112:115], v[20:21], off nt
	global_load_dwordx4 v[84:87], v[22:23], off nt
	v_add_co_u32_e32 v20, vcc, 0xffffdc00, v140
	v_add_f32_e32 v128, v128, v129
	s_nop 0
	v_addc_co_u32_e32 v21, vcc, -1, v141, vcc
	v_add_co_u32_e32 v22, vcc, 0xffffe000, v140
	v_add_f32_e32 v129, v96, v97
	s_nop 0
	v_addc_co_u32_e32 v23, vcc, -1, v141, vcc
	v_add_co_u32_e32 v24, vcc, 0xffffe400, v140
	global_load_dwordx4 v[52:55], v[20:21], off nt
	s_nop 0
	global_load_dwordx4 v[20:23], v[22:23], off nt
	v_addc_co_u32_e32 v25, vcc, -1, v141, vcc
	v_add_co_u32_e32 v26, vcc, s46, v140
	v_add_f32_e32 v130, v98, v99
	s_nop 0
	v_addc_co_u32_e32 v27, vcc, -1, v141, vcc
	global_load_dwordx4 v[124:127], v[24:25], off nt
	global_load_dwordx4 v[88:91], v[26:27], off nt
	v_add_co_u32_e32 v24, vcc, 0xffffec00, v140
	v_add_f32_e32 v129, v129, v130
	s_nop 0
	v_addc_co_u32_e32 v25, vcc, -1, v141, vcc
	v_add_co_u32_e32 v26, vcc, 0xfffff000, v140
	v_add_f32_e32 v130, v68, v69
	s_nop 0
	v_addc_co_u32_e32 v27, vcc, -1, v141, vcc
	global_load_dwordx4 v[56:59], v[24:25], off nt
	s_nop 0
	global_load_dwordx4 v[24:27], v[26:27], off nt
	v_add_co_u32_e32 v28, vcc, 0xfffff400, v140
	v_add_f32_e32 v131, v70, v71
	s_nop 0
	v_addc_co_u32_e32 v29, vcc, -1, v141, vcc
	v_add_co_u32_e32 v30, vcc, 0xfffff800, v140
	v_add_f32_e32 v129, 0, v129
	s_nop 0
	v_addc_co_u32_e32 v31, vcc, -1, v141, vcc
	global_load_dwordx4 v[120:123], v[28:29], off nt
	global_load_dwordx4 v[92:95], v[30:31], off nt
	v_add_co_u32_e32 v28, vcc, s76, v140
	v_add_f32_e32 v130, v130, v131
	s_nop 0
	v_addc_co_u32_e32 v29, vcc, -1, v141, vcc
	global_load_dwordx4 v[60:63], v[28:29], off nt
	s_nop 0
	global_load_dwordx4 v[28:31], v[140:141], off nt
	v_add_f32_e32 v129, v129, v130
	s_waitcnt vmcnt(0)
	v_add_f32_e32 v130, v36, v37
	v_add_f32_e32 v131, v38, v39
	v_add_f32_e32 v130, v130, v131
	v_add_f32_e32 v129, v129, v130
	v_add_f32_e32 v130, v4, v5
	v_add_f32_e32 v131, v6, v7
	v_add_f32_e32 v130, v130, v131
	v_add_f32_e32 v129, v129, v130
	v_add_f32_e32 v130, v108, v109
	v_add_f32_e32 v131, v110, v111
	v_add_f32_e32 v130, v130, v131
	v_add_f32_e32 v131, v72, v73
	v_add_f32_e32 v132, v74, v75
	v_add_f32_e32 v130, 0, v130
	v_add_f32_e32 v131, v131, v132
	v_add_f32_e32 v130, v130, v131
	v_add_f32_e32 v131, v40, v41
	v_add_f32_e32 v132, v42, v43
	v_add_f32_e32 v131, v131, v132
	v_add_f32_e32 v130, v130, v131
	v_add_f32_e32 v131, v8, v9
	v_add_f32_e32 v132, v10, v11
	v_add_f32_e32 v131, v131, v132
	v_add_f32_e32 v130, v130, v131
	s_waitcnt lgkmcnt(0)
	v_add_f32_e32 v131, v100, v101
	v_add_f32_e32 v132, v102, v103
	v_add_f32_e32 v131, v131, v132
	v_add_f32_e32 v132, v76, v77
	v_add_f32_e32 v133, v78, v79
	v_add_f32_e32 v131, 0, v131
	v_add_f32_e32 v132, v132, v133
	v_add_f32_e32 v131, v131, v132
	v_add_f32_e32 v132, v44, v45
	v_add_f32_e32 v133, v46, v47
	v_add_f32_e32 v132, v132, v133
	v_add_f32_e32 v131, v131, v132
	v_add_f32_e32 v132, v12, v13
	v_add_f32_e32 v133, v14, v15
	v_add_f32_e32 v132, v132, v133
	v_add_f32_e32 v131, v131, v132
	v_add_f32_e32 v132, v116, v117
	v_add_f32_e32 v133, v118, v119
	v_add_f32_e32 v132, v132, v133
	v_add_f32_e32 v133, v80, v81
	v_add_f32_e32 v142, v82, v83
	v_add_f32_e32 v132, 0, v132
	v_add_f32_e32 v133, v133, v142
	v_add_f32_e32 v132, v132, v133
	v_add_f32_e32 v133, v48, v49
	v_add_f32_e32 v142, v50, v51
	v_add_f32_e32 v133, v133, v142
	v_add_f32_e32 v132, v132, v133
	v_add_f32_e32 v133, v16, v17
	v_add_f32_e32 v142, v18, v19
	v_add_f32_e32 v133, v133, v142
	v_add_f32_e32 v132, v132, v133
	v_add_f32_e32 v133, v112, v113
	v_add_f32_e32 v142, v114, v115
	v_add_f32_e32 v133, v133, v142
	v_add_f32_e32 v142, v84, v85
	v_add_f32_e32 v143, v86, v87
	v_add_f32_e32 v133, 0, v133
	v_add_f32_e32 v142, v142, v143
	v_add_f32_e32 v133, v133, v142
	v_add_f32_e32 v142, v52, v53
	v_add_f32_e32 v143, v54, v55
	v_add_f32_e32 v142, v142, v143
	v_add_f32_e32 v133, v133, v142
	v_add_f32_e32 v142, v20, v21
	v_add_f32_e32 v143, v22, v23
	v_add_f32_e32 v142, v142, v143
	v_add_f32_e32 v142, v133, v142
	v_add_f32_e32 v133, v124, v125
	v_add_f32_e32 v143, v126, v127
	v_add_f32_e32 v133, v133, v143
	v_add_f32_e32 v143, v88, v89
	v_add_f32_e32 v144, v90, v91
	v_add_f32_e32 v133, 0, v133
	v_add_f32_e32 v143, v143, v144
	v_add_f32_e32 v133, v133, v143
	v_add_f32_e32 v143, v56, v57
	v_add_f32_e32 v144, v58, v59
	v_add_f32_e32 v143, v143, v144
	v_add_f32_e32 v133, v133, v143
	v_add_f32_e32 v143, v24, v25
	v_add_f32_e32 v144, v26, v27
	v_add_f32_e32 v143, v143, v144
	v_add_f32_e32 v143, v133, v143
	v_add_f32_e32 v133, v120, v121
	v_add_f32_e32 v144, v122, v123
	v_add_f32_e32 v133, v133, v144
	ds_swizzle_b32 v144, v128 offset:swizzle(SWAP,1)
	v_add_f32_e32 v145, v92, v93
	v_add_f32_e32 v146, v94, v95
	v_add_f32_e32 v133, 0, v133
	v_add_f32_e32 v145, v145, v146
	s_waitcnt lgkmcnt(0)
	v_add_f32_e32 v128, v128, v144
	v_add_f32_e32 v133, v133, v145
	ds_swizzle_b32 v145, v129 offset:swizzle(SWAP,1)
	ds_swizzle_b32 v144, v128 offset:swizzle(SWAP,2)
	v_add_f32_e32 v146, v60, v61
	v_add_f32_e32 v147, v62, v63
	v_add_f32_e32 v146, v146, v147
	s_waitcnt lgkmcnt(1)
	v_add_f32_e32 v129, v129, v145
	s_waitcnt lgkmcnt(0)
	v_add_f32_e32 v128, v128, v144
	ds_swizzle_b32 v145, v129 offset:swizzle(SWAP,2)
	ds_swizzle_b32 v144, v128 offset:swizzle(SWAP,4)
	v_add_f32_e32 v133, v133, v146
	v_add_f32_e32 v146, v28, v29
	v_add_f32_e32 v147, v30, v31
	s_waitcnt lgkmcnt(1)
	v_add_f32_e32 v129, v129, v145
	s_waitcnt lgkmcnt(0)
	v_add_f32_e32 v128, v128, v144
	ds_swizzle_b32 v145, v129 offset:swizzle(SWAP,4)
	ds_swizzle_b32 v144, v128 offset:swizzle(SWAP,8)
	v_add_f32_e32 v146, v146, v147
	v_add_f32_e32 v146, v133, v146
	s_waitcnt lgkmcnt(1)
	v_add_f32_e32 v129, v129, v145
	s_waitcnt lgkmcnt(0)
	v_add_f32_e32 v128, v128, v144
	ds_swizzle_b32 v145, v129 offset:swizzle(SWAP,8)
	ds_swizzle_b32 v144, v128 offset:swizzle(SWAP,16)
	s_waitcnt lgkmcnt(1)
	v_add_f32_e32 v129, v129, v145
	s_waitcnt lgkmcnt(0)
	v_add_f32_e32 v128, v128, v144
	ds_swizzle_b32 v144, v129 offset:swizzle(SWAP,16)
	ds_swizzle_b32 v145, v130 offset:swizzle(SWAP,1)
	v_mov_b32_e32 v133, v128
	s_nop 1
	v_permlane32_swap_b32_e32 v128, v133
	v_add_f32_e32 v165, v128, v133
	s_waitcnt lgkmcnt(1)
	v_add_f32_e32 v128, v129, v144
	ds_swizzle_b32 v144, v131 offset:swizzle(SWAP,1)
	s_waitcnt lgkmcnt(1)
	v_add_f32_e32 v129, v130, v145
	ds_swizzle_b32 v130, v129 offset:swizzle(SWAP,2)
	v_mov_b32_e32 v133, v128
	s_nop 1
	v_permlane32_swap_b32_e32 v128, v133
	s_waitcnt lgkmcnt(1)
	v_add_f32_e32 v131, v131, v144
	ds_swizzle_b32 v144, v131 offset:swizzle(SWAP,2)
	v_add_f32_e32 v164, v128, v133
	ds_swizzle_b32 v128, v132 offset:swizzle(SWAP,1)
	s_waitcnt lgkmcnt(2)
	v_add_f32_e32 v129, v129, v130
	ds_swizzle_b32 v130, v129 offset:swizzle(SWAP,4)
	s_waitcnt lgkmcnt(2)
	v_add_f32_e32 v131, v131, v144
	ds_swizzle_b32 v133, v131 offset:swizzle(SWAP,4)
	s_waitcnt lgkmcnt(2)
	v_add_f32_e32 v128, v132, v128
	ds_swizzle_b32 v132, v128 offset:swizzle(SWAP,2)
	s_waitcnt lgkmcnt(2)
	v_add_f32_e32 v129, v129, v130
	ds_swizzle_b32 v130, v129 offset:swizzle(SWAP,8)
	s_waitcnt lgkmcnt(2)
	v_add_f32_e32 v131, v131, v133
	ds_swizzle_b32 v133, v131 offset:swizzle(SWAP,8)
	s_waitcnt lgkmcnt(2)
	v_add_f32_e32 v128, v128, v132
	ds_swizzle_b32 v132, v128 offset:swizzle(SWAP,4)
	s_waitcnt lgkmcnt(2)
	v_add_f32_e32 v129, v129, v130
	ds_swizzle_b32 v130, v129 offset:swizzle(SWAP,16)
	s_waitcnt lgkmcnt(2)
	v_add_f32_e32 v131, v131, v133
	ds_swizzle_b32 v144, v131 offset:swizzle(SWAP,16)
	s_waitcnt lgkmcnt(2)
	v_add_f32_e32 v128, v128, v132
	ds_swizzle_b32 v132, v128 offset:swizzle(SWAP,8)
	s_waitcnt lgkmcnt(2)
	v_add_f32_e32 v129, v129, v130
	v_mov_b32_e32 v130, v129
	s_nop 1
	v_permlane32_swap_b32_e32 v129, v130
	v_add_f32_e32 v133, v129, v130
	s_waitcnt lgkmcnt(1)
	v_add_f32_e32 v129, v131, v144
	ds_swizzle_b32 v144, v142 offset:swizzle(SWAP,1)
	s_waitcnt lgkmcnt(1)
	v_add_f32_e32 v128, v128, v132
	ds_swizzle_b32 v131, v128 offset:swizzle(SWAP,16)
	v_mov_b32_e32 v130, v129
	s_nop 1
	v_permlane32_swap_b32_e32 v129, v130
	v_add_f32_e32 v132, v129, v130
	s_waitcnt lgkmcnt(1)
	v_add_f32_e32 v129, v142, v144
	ds_swizzle_b32 v142, v143 offset:swizzle(SWAP,1)
	s_waitcnt lgkmcnt(1)
	v_add_f32_e32 v128, v128, v131
	ds_swizzle_b32 v130, v129 offset:swizzle(SWAP,2)
	v_mov_b32_e32 v131, v128
	s_nop 1
	v_permlane32_swap_b32_e32 v128, v131
	s_waitcnt lgkmcnt(1)
	v_add_f32_e32 v142, v143, v142
	v_add_f32_e32 v131, v128, v131
	ds_swizzle_b32 v128, v146 offset:swizzle(SWAP,1)
	ds_swizzle_b32 v143, v142 offset:swizzle(SWAP,2)
	s_waitcnt lgkmcnt(2)
	v_add_f32_e32 v129, v129, v130
	ds_swizzle_b32 v130, v129 offset:swizzle(SWAP,4)
	v_fmamk_f32 v151, v165, 0xba800000, v107
	s_waitcnt lgkmcnt(2)
	v_add_f32_e32 v128, v146, v128
	s_waitcnt lgkmcnt(1)
	v_add_f32_e32 v142, v142, v143
	ds_swizzle_b32 v144, v128 offset:swizzle(SWAP,2)
	ds_swizzle_b32 v143, v142 offset:swizzle(SWAP,4)
	s_waitcnt lgkmcnt(2)
	v_add_f32_e32 v129, v129, v130
	ds_swizzle_b32 v130, v129 offset:swizzle(SWAP,8)
	v_fmamk_f32 v105, v165, 0xba800000, v105
	s_waitcnt lgkmcnt(2)
	v_add_f32_e32 v128, v128, v144
	s_waitcnt lgkmcnt(1)
	v_add_f32_e32 v142, v142, v143
	ds_swizzle_b32 v144, v128 offset:swizzle(SWAP,4)
	ds_swizzle_b32 v143, v142 offset:swizzle(SWAP,8)
	s_waitcnt lgkmcnt(2)
	v_add_f32_e32 v129, v129, v130
	ds_swizzle_b32 v130, v129 offset:swizzle(SWAP,16)
	v_fmamk_f32 v150, v165, 0xba800000, v106
	s_waitcnt lgkmcnt(2)
	v_add_f32_e32 v128, v128, v144
	s_waitcnt lgkmcnt(1)
	v_add_f32_e32 v142, v142, v143
	ds_swizzle_b32 v144, v128 offset:swizzle(SWAP,8)
	ds_swizzle_b32 v143, v142 offset:swizzle(SWAP,16)
	s_waitcnt lgkmcnt(2)
	v_add_f32_e32 v129, v129, v130
	v_mov_b32_e32 v130, v129
	s_nop 1
	v_permlane32_swap_b32_e32 v129, v130
	s_waitcnt lgkmcnt(1)
	v_add_f32_e32 v128, v128, v144
	v_add_f32_e32 v130, v129, v130
	s_waitcnt lgkmcnt(0)
	v_add_f32_e32 v129, v142, v143
	ds_swizzle_b32 v142, v128 offset:swizzle(SWAP,16)
	v_fmac_f32_e32 v104, 0xba800000, v165
	v_mul_f32_e32 v106, v105, v105
	v_mul_f32_e32 v107, v151, v151
	v_fmac_f32_e32 v106, v104, v104
	s_waitcnt lgkmcnt(0)
	v_add_f32_e32 v128, v128, v142
	v_mov_b32_e32 v142, v128
	s_nop 1
	v_permlane32_swap_b32_e32 v128, v142
	v_fmac_f32_e32 v107, v150, v150
	v_fmamk_f32 v67, v165, 0xba800000, v67
	v_fmamk_f32 v65, v165, 0xba800000, v65
	v_add_f32_e32 v128, v128, v142
	v_add_f32_e32 v106, v106, v107
	v_fmamk_f32 v66, v165, 0xba800000, v66
	v_fmac_f32_e32 v64, 0xba800000, v165
	v_mul_f32_e32 v107, v65, v65
	v_mul_f32_e32 v142, v67, v67
	v_fmac_f32_e32 v107, v64, v64
	v_fmac_f32_e32 v142, v66, v66
	v_add_f32_e32 v107, v107, v142
	v_fmamk_f32 v35, v165, 0xba800000, v35
	v_fmamk_f32 v33, v165, 0xba800000, v33
	v_add_f32_e32 v106, v106, v107
	v_fmamk_f32 v34, v165, 0xba800000, v34
	v_fmac_f32_e32 v32, 0xba800000, v165
	v_mul_f32_e32 v107, v33, v33
	v_mul_f32_e32 v142, v35, v35
	v_fmac_f32_e32 v107, v32, v32
	v_fmac_f32_e32 v142, v34, v34
	v_add_f32_e32 v107, v107, v142
	v_fmamk_f32 v3, v165, 0xba800000, v3
	v_fmamk_f32 v1, v165, 0xba800000, v1
	v_add_f32_e32 v106, v107, v106
	v_fmamk_f32 v2, v165, 0xba800000, v2
	v_fmac_f32_e32 v0, 0xba800000, v165
	v_mul_f32_e32 v107, v1, v1
	v_mul_f32_e32 v142, v3, v3
	v_fmac_f32_e32 v107, v0, v0
	v_fmac_f32_e32 v142, v2, v2
	v_add_f32_e32 v107, v107, v142
	v_fmamk_f32 v99, v164, 0xba800000, v99
	v_fmamk_f32 v97, v164, 0xba800000, v97
	v_add_f32_e32 v166, v107, v106
	v_fmamk_f32 v98, v164, 0xba800000, v98
	v_fmac_f32_e32 v96, 0xba800000, v164
	v_mul_f32_e32 v106, v97, v97
	v_mul_f32_e32 v107, v99, v99
	v_fmac_f32_e32 v106, v96, v96
	v_fmac_f32_e32 v107, v98, v98
	v_add_f32_e32 v142, v106, v107
	v_fmamk_f32 v107, v164, 0xba800000, v71
	v_fmamk_f32 v69, v164, 0xba800000, v69
	v_fmamk_f32 v106, v164, 0xba800000, v70
	v_fmac_f32_e32 v68, 0xba800000, v164
	v_mul_f32_e32 v70, v69, v69
	v_mul_f32_e32 v71, v107, v107
	v_fmac_f32_e32 v70, v68, v68
	v_fmac_f32_e32 v71, v106, v106
	v_add_f32_e32 v70, v70, v71
	v_fmamk_f32 v39, v164, 0xba800000, v39
	v_fmamk_f32 v37, v164, 0xba800000, v37
	v_add_f32_e32 v70, v142, v70
	v_fmamk_f32 v38, v164, 0xba800000, v38
	v_fmac_f32_e32 v36, 0xba800000, v164
	v_mul_f32_e32 v71, v37, v37
	v_mul_f32_e32 v142, v39, v39
	v_fmac_f32_e32 v71, v36, v36
	v_fmac_f32_e32 v142, v38, v38
	v_add_f32_e32 v71, v71, v142
	v_fmamk_f32 v7, v164, 0xba800000, v7
	v_fmamk_f32 v5, v164, 0xba800000, v5
	v_add_f32_e32 v70, v71, v70
	v_fmamk_f32 v6, v164, 0xba800000, v6
	v_fmac_f32_e32 v4, 0xba800000, v164
	v_mul_f32_e32 v71, v5, v5
	v_mul_f32_e32 v142, v7, v7
	v_fmac_f32_e32 v71, v4, v4
	v_fmac_f32_e32 v142, v6, v6
	v_add_f32_e32 v71, v71, v142
	v_fmamk_f32 v153, v133, 0xba800000, v111
	v_fmamk_f32 v109, v133, 0xba800000, v109
	v_add_f32_e32 v167, v71, v70
	v_fmamk_f32 v152, v133, 0xba800000, v110
	v_fmac_f32_e32 v108, 0xba800000, v133
	v_mul_f32_e32 v70, v109, v109
	v_mul_f32_e32 v71, v153, v153
	v_fmac_f32_e32 v70, v108, v108
	v_fmac_f32_e32 v71, v152, v152
	v_fmamk_f32 v111, v133, 0xba800000, v75
	v_fmamk_f32 v73, v133, 0xba800000, v73
	v_add_f32_e32 v70, v70, v71
	v_fmamk_f32 v110, v133, 0xba800000, v74
	v_fmac_f32_e32 v72, 0xba800000, v133
	v_mul_f32_e32 v71, v73, v73
	v_mul_f32_e32 v74, v111, v111
	v_fmac_f32_e32 v71, v72, v72
	v_fmac_f32_e32 v74, v110, v110
	v_add_f32_e32 v71, v71, v74
	v_fmamk_f32 v43, v133, 0xba800000, v43
	v_fmamk_f32 v41, v133, 0xba800000, v41
	v_add_f32_e32 v70, v70, v71
	v_fmamk_f32 v42, v133, 0xba800000, v42
	v_fmac_f32_e32 v40, 0xba800000, v133
	v_mul_f32_e32 v71, v41, v41
	v_mul_f32_e32 v74, v43, v43
	v_fmac_f32_e32 v71, v40, v40
	v_fmac_f32_e32 v74, v42, v42
	v_add_f32_e32 v71, v71, v74
	v_fmamk_f32 v11, v133, 0xba800000, v11
	v_fmamk_f32 v9, v133, 0xba800000, v9
	v_add_f32_e32 v70, v71, v70
	v_fmamk_f32 v10, v133, 0xba800000, v10
	v_fmac_f32_e32 v8, 0xba800000, v133
	v_mul_f32_e32 v71, v9, v9
	v_mul_f32_e32 v74, v11, v11
	v_fmac_f32_e32 v71, v8, v8
	v_fmac_f32_e32 v74, v10, v10
	v_mov_b32_e32 v143, v129
	v_add_f32_e32 v71, v71, v74
	v_fmamk_f32 v155, v132, 0xba800000, v103
	v_fmamk_f32 v101, v132, 0xba800000, v101
	v_permlane32_swap_b32_e32 v129, v143
	v_add_f32_e32 v74, v71, v70
	v_fmamk_f32 v154, v132, 0xba800000, v102
	v_fmac_f32_e32 v100, 0xba800000, v132
	v_mul_f32_e32 v70, v101, v101
	v_mul_f32_e32 v71, v155, v155
	v_add_f32_e32 v129, v129, v143
	v_fmac_f32_e32 v70, v100, v100
	v_fmac_f32_e32 v71, v154, v154
	v_fmamk_f32 v143, v132, 0xba800000, v79
	v_fmamk_f32 v77, v132, 0xba800000, v77
	v_add_f32_e32 v70, v70, v71
	v_fmamk_f32 v142, v132, 0xba800000, v78
	v_fmac_f32_e32 v76, 0xba800000, v132
	v_mul_f32_e32 v71, v77, v77
	v_mul_f32_e32 v75, v143, v143
	v_fmac_f32_e32 v71, v76, v76
	v_fmac_f32_e32 v75, v142, v142
	v_add_f32_e32 v71, v71, v75
	v_fmamk_f32 v47, v132, 0xba800000, v47
	v_fmamk_f32 v45, v132, 0xba800000, v45
	v_add_f32_e32 v70, v70, v71
	v_fmamk_f32 v46, v132, 0xba800000, v46
	v_fmac_f32_e32 v44, 0xba800000, v132
	v_mul_f32_e32 v71, v45, v45
	v_mul_f32_e32 v75, v47, v47
	v_fmac_f32_e32 v71, v44, v44
	v_fmac_f32_e32 v75, v46, v46
	v_add_f32_e32 v71, v71, v75
	v_fmamk_f32 v15, v132, 0xba800000, v15
	v_fmamk_f32 v13, v132, 0xba800000, v13
	v_add_f32_e32 v70, v71, v70
	v_fmamk_f32 v14, v132, 0xba800000, v14
	v_fmac_f32_e32 v12, 0xba800000, v132
	v_mul_f32_e32 v71, v13, v13
	v_mul_f32_e32 v75, v15, v15
	v_fmac_f32_e32 v71, v12, v12
	v_fmac_f32_e32 v75, v14, v14
	v_add_f32_e32 v71, v71, v75
	v_fmamk_f32 v157, v131, 0xba800000, v119
	v_fmamk_f32 v117, v131, 0xba800000, v117
	v_add_f32_e32 v75, v71, v70
	v_fmamk_f32 v156, v131, 0xba800000, v118
	v_fmac_f32_e32 v116, 0xba800000, v131
	v_mul_f32_e32 v70, v117, v117
	v_mul_f32_e32 v71, v157, v157
	v_fmac_f32_e32 v70, v116, v116
	v_fmac_f32_e32 v71, v156, v156
	v_fmamk_f32 v145, v131, 0xba800000, v83
	v_fmamk_f32 v81, v131, 0xba800000, v81
	v_add_f32_e32 v70, v70, v71
	v_fmamk_f32 v144, v131, 0xba800000, v82
	v_fmac_f32_e32 v80, 0xba800000, v131
	v_mul_f32_e32 v71, v81, v81
	v_mul_f32_e32 v78, v145, v145
	v_fmac_f32_e32 v71, v80, v80
	v_fmac_f32_e32 v78, v144, v144
	v_add_f32_e32 v71, v71, v78
	v_fmamk_f32 v51, v131, 0xba800000, v51
	v_fmamk_f32 v49, v131, 0xba800000, v49
	v_add_f32_e32 v70, v70, v71
	v_fmamk_f32 v50, v131, 0xba800000, v50
	v_fmac_f32_e32 v48, 0xba800000, v131
	v_mul_f32_e32 v71, v49, v49
	v_mul_f32_e32 v78, v51, v51
	v_fmac_f32_e32 v71, v48, v48
	v_fmac_f32_e32 v78, v50, v50
	v_add_f32_e32 v71, v71, v78
	v_fmamk_f32 v19, v131, 0xba800000, v19
	v_fmamk_f32 v17, v131, 0xba800000, v17
	v_add_f32_e32 v70, v71, v70
	v_fmamk_f32 v18, v131, 0xba800000, v18
	v_fmac_f32_e32 v16, 0xba800000, v131
	v_mul_f32_e32 v71, v17, v17
	v_mul_f32_e32 v78, v19, v19
	v_fmac_f32_e32 v71, v16, v16
	v_fmac_f32_e32 v78, v18, v18
	v_add_f32_e32 v71, v71, v78
	v_fmamk_f32 v159, v130, 0xba800000, v115
	v_fmamk_f32 v113, v130, 0xba800000, v113
	v_add_f32_e32 v79, v71, v70
	v_fmamk_f32 v158, v130, 0xba800000, v114
	v_fmac_f32_e32 v112, 0xba800000, v130
	v_mul_f32_e32 v70, v113, v113
	v_mul_f32_e32 v71, v159, v159
	v_fmac_f32_e32 v70, v112, v112
	v_fmac_f32_e32 v71, v158, v158
	v_fmamk_f32 v147, v130, 0xba800000, v87
	v_fmamk_f32 v85, v130, 0xba800000, v85
	v_add_f32_e32 v70, v70, v71
	v_fmamk_f32 v146, v130, 0xba800000, v86
	v_fmac_f32_e32 v84, 0xba800000, v130
	v_mul_f32_e32 v71, v85, v85
	v_mul_f32_e32 v78, v147, v147
	v_fmac_f32_e32 v71, v84, v84
	v_fmac_f32_e32 v78, v146, v146
	v_add_f32_e32 v71, v71, v78
	v_fmamk_f32 v55, v130, 0xba800000, v55
	v_fmamk_f32 v53, v130, 0xba800000, v53
	v_add_f32_e32 v70, v70, v71
	v_fmamk_f32 v54, v130, 0xba800000, v54
	v_fmac_f32_e32 v52, 0xba800000, v130
	v_mul_f32_e32 v71, v53, v53
	v_mul_f32_e32 v78, v55, v55
	v_fmac_f32_e32 v71, v52, v52
	v_fmac_f32_e32 v78, v54, v54
	v_add_f32_e32 v71, v71, v78
	v_fmamk_f32 v23, v130, 0xba800000, v23
	v_fmamk_f32 v21, v130, 0xba800000, v21
	v_add_f32_e32 v70, v71, v70
	v_fmamk_f32 v22, v130, 0xba800000, v22
	v_fmac_f32_e32 v20, 0xba800000, v130
	v_mul_f32_e32 v71, v21, v21
	v_mul_f32_e32 v78, v23, v23
	v_fmac_f32_e32 v71, v20, v20
	v_fmac_f32_e32 v78, v22, v22
	v_add_f32_e32 v71, v71, v78
	v_fmamk_f32 v161, v129, 0xba800000, v127
	v_fmamk_f32 v125, v129, 0xba800000, v125
	v_add_f32_e32 v83, v71, v70
	v_fmamk_f32 v160, v129, 0xba800000, v126
	v_fmac_f32_e32 v124, 0xba800000, v129
	v_mul_f32_e32 v70, v125, v125
	v_mul_f32_e32 v71, v161, v161
	v_fmac_f32_e32 v70, v124, v124
	v_fmac_f32_e32 v71, v160, v160
	v_fmamk_f32 v149, v129, 0xba800000, v91
	v_fmamk_f32 v89, v129, 0xba800000, v89
	v_add_f32_e32 v70, v70, v71
	v_fmamk_f32 v148, v129, 0xba800000, v90
	v_fmac_f32_e32 v88, 0xba800000, v129
	v_mul_f32_e32 v71, v89, v89
	v_mul_f32_e32 v78, v149, v149
	v_fmac_f32_e32 v71, v88, v88
	v_fmac_f32_e32 v78, v148, v148
	v_add_f32_e32 v71, v71, v78
	v_fmamk_f32 v59, v129, 0xba800000, v59
	v_fmamk_f32 v57, v129, 0xba800000, v57
	v_add_f32_e32 v70, v70, v71
	v_fmamk_f32 v58, v129, 0xba800000, v58
	v_fmac_f32_e32 v56, 0xba800000, v129
	v_mul_f32_e32 v71, v57, v57
	v_mul_f32_e32 v78, v59, v59
	v_fmac_f32_e32 v71, v56, v56
	v_fmac_f32_e32 v78, v58, v58
	v_add_f32_e32 v71, v71, v78
	v_fmamk_f32 v27, v129, 0xba800000, v27
	v_fmamk_f32 v25, v129, 0xba800000, v25
	v_add_f32_e32 v70, v71, v70
	v_fmamk_f32 v26, v129, 0xba800000, v26
	v_fmac_f32_e32 v24, 0xba800000, v129
	v_mul_f32_e32 v71, v25, v25
	v_mul_f32_e32 v78, v27, v27
	v_fmac_f32_e32 v71, v24, v24
	v_fmac_f32_e32 v78, v26, v26
	v_add_f32_e32 v71, v71, v78
	v_fmamk_f32 v163, v128, 0xba800000, v123
	v_fmamk_f32 v121, v128, 0xba800000, v121
	v_add_f32_e32 v87, v71, v70
	v_fmamk_f32 v162, v128, 0xba800000, v122
	v_fmac_f32_e32 v120, 0xba800000, v128
	v_mul_f32_e32 v70, v121, v121
	v_mul_f32_e32 v71, v163, v163
	v_fmac_f32_e32 v70, v120, v120
	v_fmac_f32_e32 v71, v162, v162
	v_fmamk_f32 v123, v128, 0xba800000, v95
	v_fmamk_f32 v93, v128, 0xba800000, v93
	v_add_f32_e32 v70, v70, v71
	v_fmamk_f32 v122, v128, 0xba800000, v94
	v_fmac_f32_e32 v92, 0xba800000, v128
	v_mul_f32_e32 v71, v93, v93
	v_mul_f32_e32 v78, v123, v123
	v_fmac_f32_e32 v71, v92, v92
	v_fmac_f32_e32 v78, v122, v122
	v_add_f32_e32 v71, v71, v78
	v_add_f32_e32 v78, v70, v71
	v_fmamk_f32 v70, v128, 0xba800000, v62
	ds_swizzle_b32 v62, v166 offset:swizzle(SWAP,1)
	v_fmamk_f32 v71, v128, 0xba800000, v63
	v_fmamk_f32 v61, v128, 0xba800000, v61
	v_fmac_f32_e32 v60, 0xba800000, v128
	v_mul_f32_e32 v63, v61, v61
	s_waitcnt lgkmcnt(0)
	v_add_f32_e32 v62, v166, v62
	ds_swizzle_b32 v86, v62 offset:swizzle(SWAP,2)
	v_mul_f32_e32 v82, v71, v71
	v_fmac_f32_e32 v63, v60, v60
	v_fmac_f32_e32 v82, v70, v70
	v_add_f32_e32 v63, v63, v82
	s_waitcnt lgkmcnt(0)
	v_add_f32_e32 v62, v62, v86
	v_add_f32_e32 v63, v63, v78
	ds_swizzle_b32 v78, v62 offset:swizzle(SWAP,4)
	ds_swizzle_b32 v82, v167 offset:swizzle(SWAP,1)
	v_fmamk_f32 v31, v128, 0xba800000, v31
	v_fmamk_f32 v29, v128, 0xba800000, v29
	v_fmamk_f32 v30, v128, 0xba800000, v30
	s_waitcnt lgkmcnt(1)
	v_add_f32_e32 v62, v62, v78
	s_waitcnt lgkmcnt(0)
	v_add_f32_e32 v82, v167, v82
	ds_swizzle_b32 v78, v62 offset:swizzle(SWAP,8)
	ds_swizzle_b32 v90, v82 offset:swizzle(SWAP,2)
	v_fmac_f32_e32 v28, 0xba800000, v128
	v_mul_f32_e32 v86, v29, v29
	v_mul_f32_e32 v91, v31, v31
	s_waitcnt lgkmcnt(1)
	v_add_f32_e32 v62, v62, v78
	s_waitcnt lgkmcnt(0)
	v_add_f32_e32 v82, v82, v90
	ds_swizzle_b32 v78, v62 offset:swizzle(SWAP,16)
	ds_swizzle_b32 v90, v82 offset:swizzle(SWAP,4)
	v_fmac_f32_e32 v86, v28, v28
	v_fmac_f32_e32 v91, v30, v30
	v_add_f32_e32 v86, v86, v91
	s_waitcnt lgkmcnt(1)
	v_add_f32_e32 v62, v62, v78
	s_waitcnt lgkmcnt(0)
	v_add_f32_e32 v78, v82, v90
	ds_swizzle_b32 v90, v74 offset:swizzle(SWAP,1)
	ds_swizzle_b32 v82, v78 offset:swizzle(SWAP,8)
	v_add_f32_e32 v63, v86, v63
	v_mov_b32_e32 v86, v62
	s_nop 1
	v_permlane32_swap_b32_e32 v62, v86
	s_waitcnt lgkmcnt(1)
	v_add_f32_e32 v74, v74, v90
	s_waitcnt lgkmcnt(0)
	v_add_f32_e32 v78, v78, v82
	ds_swizzle_b32 v90, v74 offset:swizzle(SWAP,2)
	v_add_f32_e32 v62, v62, v86
	ds_swizzle_b32 v86, v75 offset:swizzle(SWAP,1)
	ds_swizzle_b32 v82, v78 offset:swizzle(SWAP,16)
	ds_swizzle_b32 v91, v83 offset:swizzle(SWAP,1)
	s_waitcnt lgkmcnt(3)
	v_add_f32_e32 v74, v74, v90
	ds_swizzle_b32 v90, v79 offset:swizzle(SWAP,1)
	s_waitcnt lgkmcnt(3)
	v_add_f32_e32 v75, v75, v86
	s_waitcnt lgkmcnt(2)
	v_add_f32_e32 v78, v78, v82
	ds_swizzle_b32 v82, v74 offset:swizzle(SWAP,4)
	ds_swizzle_b32 v86, v75 offset:swizzle(SWAP,2)
	s_waitcnt lgkmcnt(2)
	v_add_f32_e32 v79, v79, v90
	ds_swizzle_b32 v90, v79 offset:swizzle(SWAP,2)
	ds_swizzle_b32 v103, v87 offset:swizzle(SWAP,1)
	s_waitcnt lgkmcnt(3)
	v_add_f32_e32 v74, v74, v82
	s_waitcnt lgkmcnt(2)
	v_add_f32_e32 v75, v75, v86
	ds_swizzle_b32 v82, v74 offset:swizzle(SWAP,8)
	ds_swizzle_b32 v86, v75 offset:swizzle(SWAP,4)
	s_waitcnt lgkmcnt(3)
	v_add_f32_e32 v79, v79, v90
	ds_swizzle_b32 v90, v79 offset:swizzle(SWAP,4)
	v_fmamk_f32 v62, v62, 0x3a800000, v243
	s_waitcnt lgkmcnt(2)
	v_add_f32_e32 v74, v74, v82
	s_waitcnt lgkmcnt(1)
	v_add_f32_e32 v75, v75, v86
	ds_swizzle_b32 v82, v74 offset:swizzle(SWAP,16)
	ds_swizzle_b32 v86, v75 offset:swizzle(SWAP,8)
	s_waitcnt lgkmcnt(2)
	v_add_f32_e32 v79, v79, v90
	ds_swizzle_b32 v90, v79 offset:swizzle(SWAP,8)
	v_cmp_gt_f32_e32 vcc, s84, v62
	s_waitcnt lgkmcnt(2)
	v_add_f32_e32 v82, v74, v82
	s_waitcnt lgkmcnt(1)
	v_add_f32_e32 v74, v75, v86
	ds_swizzle_b32 v75, v74 offset:swizzle(SWAP,16)
	v_mov_b32_e32 v102, v78
	v_mov_b32_e32 v95, v82
	s_nop 0
	v_permlane32_swap_b32_e32 v78, v102
	s_waitcnt lgkmcnt(0)
	v_add_f32_e32 v86, v74, v75
	v_add_f32_e32 v74, v79, v90
	v_add_f32_e32 v79, v83, v91
	ds_swizzle_b32 v75, v74 offset:swizzle(SWAP,16)
	ds_swizzle_b32 v83, v79 offset:swizzle(SWAP,2)
	v_mov_b32_e32 v94, v86
	v_permlane32_swap_b32_e32 v82, v95
	s_waitcnt lgkmcnt(1)
	v_add_f32_e32 v90, v74, v75
	s_waitcnt lgkmcnt(0)
	v_add_f32_e32 v74, v79, v83
	v_add_f32_e32 v79, v87, v103
	ds_swizzle_b32 v87, v63 offset:swizzle(SWAP,1)
	ds_swizzle_b32 v75, v74 offset:swizzle(SWAP,4)
	ds_swizzle_b32 v83, v79 offset:swizzle(SWAP,2)
	v_mov_b32_e32 v91, v90
	v_permlane32_swap_b32_e32 v86, v94
	s_waitcnt lgkmcnt(2)
	v_add_f32_e32 v63, v63, v87
	s_waitcnt lgkmcnt(1)
	v_add_f32_e32 v74, v74, v75
	s_waitcnt lgkmcnt(0)
	v_add_f32_e32 v79, v79, v83
	ds_swizzle_b32 v87, v63 offset:swizzle(SWAP,2)
	ds_swizzle_b32 v75, v74 offset:swizzle(SWAP,8)
	ds_swizzle_b32 v83, v79 offset:swizzle(SWAP,4)
	v_permlane32_swap_b32_e32 v90, v91
	s_waitcnt lgkmcnt(2)
	v_add_f32_e32 v63, v63, v87
	s_waitcnt lgkmcnt(1)
	v_add_f32_e32 v74, v74, v75
	s_waitcnt lgkmcnt(0)
	v_add_f32_e32 v79, v79, v83
	ds_swizzle_b32 v114, v63 offset:swizzle(SWAP,4)
	ds_swizzle_b32 v75, v74 offset:swizzle(SWAP,16)
	ds_swizzle_b32 v103, v79 offset:swizzle(SWAP,8)
	s_waitcnt lgkmcnt(2)
	v_add_f32_e32 v63, v63, v114
	s_waitcnt lgkmcnt(1)
	v_add_f32_e32 v83, v74, v75
	s_waitcnt lgkmcnt(0)
	v_add_f32_e32 v74, v79, v103
	ds_swizzle_b32 v103, v63 offset:swizzle(SWAP,8)
	ds_swizzle_b32 v75, v74 offset:swizzle(SWAP,16)
	v_mov_b32_e32 v87, v83
	s_nop 1
	v_permlane32_swap_b32_e32 v83, v87
	s_waitcnt lgkmcnt(1)
	v_add_f32_e32 v63, v63, v103
	v_mul_f32_e32 v103, 0x4f800000, v62
	s_waitcnt lgkmcnt(0)
	v_add_f32_e32 v75, v74, v75
	ds_swizzle_b32 v74, v63 offset:swizzle(SWAP,16)
	v_cndmask_b32_e32 v103, v62, v103, vcc
	v_sqrt_f32_e32 v114, v103
	v_mov_b32_e32 v79, v75
	s_nop 1
	v_permlane32_swap_b32_e32 v75, v79
	s_waitcnt lgkmcnt(0)
	v_add_f32_e32 v62, v63, v74
	v_add_u32_e32 v63, -1, v114
	v_fma_f32 v74, -v63, v114, v103
	v_cmp_ge_f32_e64 s[6:7], 0, v74
	v_add_u32_e32 v74, 1, v114
	s_nop 0
	v_cndmask_b32_e64 v63, v114, v63, s[6:7]
	v_fma_f32 v114, -v74, v114, v103
	v_cmp_lt_f32_e64 s[6:7], 0, v114
	s_nop 1
	v_cndmask_b32_e64 v63, v63, v74, s[6:7]
	v_mul_f32_e32 v74, 0x37800000, v63
	v_cndmask_b32_e32 v63, v63, v74, vcc
	v_cmp_class_f32_e32 vcc, v103, v248
	s_nop 1
	v_cndmask_b32_e32 v74, v63, v103, vcc
	v_div_scale_f32 v103, s[6:7], v74, v74, 1.0
	v_rcp_f32_e32 v114, v103
	v_mov_b32_e32 v63, v62
	s_nop 1
	v_permlane32_swap_b32_e32 v62, v63
	v_fma_f32 v115, -v103, v114, 1.0
	v_fmac_f32_e32 v114, v115, v114
	v_div_scale_f32 v115, vcc, 1.0, v74, 1.0
	v_mul_f32_e32 v118, v115, v114
	v_fma_f32 v119, -v103, v118, v115
	v_fmac_f32_e32 v118, v119, v114
	v_fma_f32 v103, -v103, v118, v115
	v_div_fmas_f32 v103, v103, v114, v118
	v_div_fixup_f32 v74, v103, v74, 1.0
	s_and_saveexec_b64 s[6:7], s[4:5]
	s_cbranch_execz .LBB0_1561
	v_mov_b32_e32 v103, s13
	v_add_co_u32_e32 v118, vcc, 0x1fa00000, v103
	v_mov_b32_e32 v103, s11
	v_mul_f32_e32 v114, 0x3a800000, v165
	v_addc_co_u32_e32 v119, vcc, 0, v103, vcc
	v_mov_b32_e32 v115, v74
	global_store_dwordx2 v[118:119], v[114:115], off
